# O9S + merged waits + s_setprio 1 hoisted above the wait (barrier directly follows the wait)
# baseline (speedup 1.0000x reference)
.LBB0_170:
	ds_read_b128 v[136:139], v191
	ds_read_b128 v[158:161], v191 offset:1024
	ds_read_b128 v[162:165], v191 offset:2048
	ds_read_b128 v[166:169], v191 offset:3072
	ds_read_b128 v[170:173], v192
	ds_read_b128 v[174:177], v192 offset:1024
	ds_read_b128 v[178:181], v192 offset:2048
	ds_read_b128 v[194:197], v192 offset:3072
	s_add_u32 s0, s42, 0xfff00080
	s_addc_u32 s50, s43, -1
	s_cmp_eq_u32 s70, 60
	s_cselect_b32 s53, s23, s50
	s_cselect_b32 s52, s41, s0
	s_cselect_b32 s51, s21, s68
	s_cselect_b32 s50, s66, s67
	s_add_i32 m0, s31, 0xc000
	ds_read_b128 v[198:201], v193
	ds_read_b128 v[202:205], v193 offset:1024
	ds_read_b128 v[206:209], v193 offset:2048
	ds_read_b128 v[210:213], v193 offset:3072
	ds_read_b128 v[214:217], v193 offset:4096
	ds_read_b128 v[218:221], v193 offset:5120
	ds_read_b128 v[222:225], v193 offset:6144
	ds_read_b128 v[226:229], v193 offset:7168
	global_load_lds_dwordx4 v152, s[42:43]
	s_add_i32 m0, s31, 0xe000
	s_nop 0
	global_load_lds_dwordx4 v154, s[42:43]
	s_setprio 1
	s_waitcnt vmcnt(8) lgkmcnt(0)
	s_barrier
	v_mfma_f32_16x16x32_bf16 v[132:135], v[136:139], v[198:201], v[132:135]
	v_mfma_f32_16x16x32_bf16 v[132:135], v[158:161], v[202:205], v[132:135]
	v_mfma_f32_16x16x32_bf16 v[128:131], v[162:165], v[198:201], v[128:131]
	v_mfma_f32_16x16x32_bf16 v[128:131], v[166:169], v[202:205], v[128:131]
	v_mfma_f32_16x16x32_bf16 v[124:127], v[170:173], v[198:201], v[124:127]
	v_mfma_f32_16x16x32_bf16 v[124:127], v[174:177], v[202:205], v[124:127]
	v_mfma_f32_16x16x32_bf16 v[120:123], v[178:181], v[198:201], v[120:123]
	v_mfma_f32_16x16x32_bf16 v[120:123], v[194:197], v[202:205], v[120:123]
	v_mfma_f32_16x16x32_bf16 v[104:107], v[178:181], v[206:209], v[104:107]
	v_mfma_f32_16x16x32_bf16 v[104:107], v[194:197], v[210:213], v[104:107]
	v_mfma_f32_16x16x32_bf16 v[108:111], v[170:173], v[206:209], v[108:111]
	v_mfma_f32_16x16x32_bf16 v[108:111], v[174:177], v[210:213], v[108:111]
	v_mfma_f32_16x16x32_bf16 v[112:115], v[162:165], v[206:209], v[112:115]
	v_mfma_f32_16x16x32_bf16 v[112:115], v[166:169], v[210:213], v[112:115]
	v_mfma_f32_16x16x32_bf16 v[116:119], v[136:139], v[206:209], v[116:119]
	v_mfma_f32_16x16x32_bf16 v[116:119], v[158:161], v[210:213], v[116:119]
	v_mfma_f32_16x16x32_bf16 v[100:103], v[136:139], v[214:217], v[100:103]
	v_mfma_f32_16x16x32_bf16 v[100:103], v[158:161], v[218:221], v[100:103]
	v_mfma_f32_16x16x32_bf16 v[96:99], v[162:165], v[214:217], v[96:99]
	v_mfma_f32_16x16x32_bf16 v[96:99], v[166:169], v[218:221], v[96:99]
	v_mfma_f32_16x16x32_bf16 v[92:95], v[170:173], v[214:217], v[92:95]
	v_mfma_f32_16x16x32_bf16 v[92:95], v[174:177], v[218:221], v[92:95]
	v_mfma_f32_16x16x32_bf16 v[88:91], v[178:181], v[214:217], v[88:91]
	v_mfma_f32_16x16x32_bf16 v[88:91], v[194:197], v[218:221], v[88:91]
	v_mfma_f32_16x16x32_bf16 v[72:75], v[178:181], v[222:225], v[72:75]
	v_mfma_f32_16x16x32_bf16 v[72:75], v[194:197], v[226:229], v[72:75]
	v_mfma_f32_16x16x32_bf16 v[76:79], v[170:173], v[222:225], v[76:79]
	v_mfma_f32_16x16x32_bf16 v[76:79], v[174:177], v[226:229], v[76:79]
	v_mfma_f32_16x16x32_bf16 v[80:83], v[162:165], v[222:225], v[80:83]
	v_mfma_f32_16x16x32_bf16 v[80:83], v[166:169], v[226:229], v[80:83]
	v_mfma_f32_16x16x32_bf16 v[84:87], v[136:139], v[222:225], v[84:87]
	v_mfma_f32_16x16x32_bf16 v[84:87], v[158:161], v[226:229], v[84:87]
	s_setprio 0
	s_barrier
	s_add_i32 s0, s61, s19
	s_mov_b32 m0, s0
	ds_read_b128 v[198:201], v193 offset:16384
	ds_read_b128 v[202:205], v193 offset:17408
	ds_read_b128 v[206:209], v193 offset:18432
	ds_read_b128 v[210:213], v193 offset:19456
	ds_read_b128 v[214:217], v193 offset:20480
	ds_read_b128 v[218:221], v193 offset:21504
	ds_read_b128 v[222:225], v193 offset:22528
	ds_read_b128 v[226:229], v193 offset:23552
	global_load_lds_dwordx4 v142, s[50:51]
	s_add_i32 m0, s0, 0x2000
	s_add_u32 s72, s50, 0x100000
	s_addc_u32 s73, s51, 0
	s_add_i32 s0, s62, s19
	global_load_lds_dwordx4 v146, s[50:51]
	s_mov_b32 m0, s0
	s_nop 0
	global_load_lds_dwordx4 v142, s[72:73]
	s_add_i32 m0, s0, 0x2000
	s_nop 0
	global_load_lds_dwordx4 v146, s[72:73]
	s_mov_b32 m0, s31
	s_nop 0
	global_load_lds_dwordx4 v140, s[52:53]
	s_mov_b32 m0, s35
	s_nop 0
	global_load_lds_dwordx4 v144, s[52:53]
	s_setprio 1
	s_waitcnt vmcnt(8) lgkmcnt(0)
	s_barrier
	v_mfma_f32_16x16x32_bf16 v[68:71], v[136:139], v[198:201], v[68:71]
	v_mfma_f32_16x16x32_bf16 v[68:71], v[158:161], v[202:205], v[68:71]
	v_mfma_f32_16x16x32_bf16 v[64:67], v[162:165], v[198:201], v[64:67]
	v_mfma_f32_16x16x32_bf16 v[64:67], v[166:169], v[202:205], v[64:67]
	v_mfma_f32_16x16x32_bf16 v[60:63], v[170:173], v[198:201], v[60:63]
	v_mfma_f32_16x16x32_bf16 v[60:63], v[174:177], v[202:205], v[60:63]
	v_mfma_f32_16x16x32_bf16 v[56:59], v[178:181], v[198:201], v[56:59]
	v_mfma_f32_16x16x32_bf16 v[56:59], v[194:197], v[202:205], v[56:59]
	v_mfma_f32_16x16x32_bf16 v[40:43], v[178:181], v[206:209], v[40:43]
	v_mfma_f32_16x16x32_bf16 v[40:43], v[194:197], v[210:213], v[40:43]
	v_mfma_f32_16x16x32_bf16 v[44:47], v[170:173], v[206:209], v[44:47]
	v_mfma_f32_16x16x32_bf16 v[44:47], v[174:177], v[210:213], v[44:47]
	v_mfma_f32_16x16x32_bf16 v[48:51], v[162:165], v[206:209], v[48:51]
	v_mfma_f32_16x16x32_bf16 v[48:51], v[166:169], v[210:213], v[48:51]
	v_mfma_f32_16x16x32_bf16 v[52:55], v[136:139], v[206:209], v[52:55]
	v_mfma_f32_16x16x32_bf16 v[52:55], v[158:161], v[210:213], v[52:55]
	v_mfma_f32_16x16x32_bf16 v[36:39], v[136:139], v[214:217], v[36:39]
	v_mfma_f32_16x16x32_bf16 v[36:39], v[158:161], v[218:221], v[36:39]
	v_mfma_f32_16x16x32_bf16 v[32:35], v[162:165], v[214:217], v[32:35]
	v_mfma_f32_16x16x32_bf16 v[32:35], v[166:169], v[218:221], v[32:35]
	v_mfma_f32_16x16x32_bf16 v[28:31], v[170:173], v[214:217], v[28:31]
	v_mfma_f32_16x16x32_bf16 v[28:31], v[174:177], v[218:221], v[28:31]
	v_mfma_f32_16x16x32_bf16 v[24:27], v[178:181], v[214:217], v[24:27]
	v_mfma_f32_16x16x32_bf16 v[24:27], v[194:197], v[218:221], v[24:27]
	v_mfma_f32_16x16x32_bf16 v[6:9], v[178:181], v[222:225], v[8:11]
	v_mfma_f32_16x16x32_bf16 v[6:9], v[194:197], v[226:229], v[6:9]
	v_mfma_f32_16x16x32_bf16 v[12:15], v[170:173], v[222:225], v[12:15]
	v_mfma_f32_16x16x32_bf16 v[12:15], v[174:177], v[226:229], v[12:15]
	v_mfma_f32_16x16x32_bf16 v[16:19], v[162:165], v[222:225], v[16:19]
	v_mfma_f32_16x16x32_bf16 v[16:19], v[166:169], v[226:229], v[16:19]
	v_mfma_f32_16x16x32_bf16 v[20:23], v[136:139], v[222:225], v[20:23]
	v_mfma_f32_16x16x32_bf16 v[20:23], v[158:161], v[226:229], v[20:23]
	s_setprio 0
	s_barrier
	s_add_i32 s0, 0, 0x18000
	v_add_u32_e32 v5, s0, v1
	s_add_i32 s71, 0, 0x1c000
	ds_read_b128 v[136:139], v5
	ds_read_b128 v[158:161], v5 offset:1024
	ds_read_b128 v[162:165], v5 offset:2048
	ds_read_b128 v[166:169], v5 offset:3072
	v_add_u32_e32 v5, s71, v1
	ds_read_b128 v[170:173], v5
	ds_read_b128 v[174:177], v5 offset:1024
	ds_read_b128 v[178:181], v5 offset:2048
	ds_read_b128 v[194:197], v5 offset:3072
	s_add_u32 s98, s52, 0x100000
	s_addc_u32 s99, s53, 0
	s_mov_b32 m0, s45
	ds_read_b128 v[198:201], v193 offset:32768
	ds_read_b128 v[202:205], v193 offset:33792
	ds_read_b128 v[206:209], v193 offset:34816
	ds_read_b128 v[210:213], v193 offset:35840
	ds_read_b128 v[214:217], v193 offset:36864
	ds_read_b128 v[218:221], v193 offset:37888
	ds_read_b128 v[222:225], v193 offset:38912
	ds_read_b128 v[226:229], v193 offset:39936
	global_load_lds_dwordx4 v140, s[98:99]
	s_mov_b32 m0, s46
	s_nop 0
	global_load_lds_dwordx4 v144, s[98:99]
	s_setprio 1
	s_waitcnt vmcnt(8) lgkmcnt(0)
	s_barrier
	v_mfma_f32_16x16x32_bf16 v[132:135], v[136:139], v[198:201], v[132:135]
	v_mfma_f32_16x16x32_bf16 v[132:135], v[158:161], v[202:205], v[132:135]
	v_mfma_f32_16x16x32_bf16 v[128:131], v[162:165], v[198:201], v[128:131]
	v_mfma_f32_16x16x32_bf16 v[128:131], v[166:169], v[202:205], v[128:131]
	v_mfma_f32_16x16x32_bf16 v[124:127], v[170:173], v[198:201], v[124:127]
	v_mfma_f32_16x16x32_bf16 v[124:127], v[174:177], v[202:205], v[124:127]
	v_mfma_f32_16x16x32_bf16 v[120:123], v[178:181], v[198:201], v[120:123]
	v_mfma_f32_16x16x32_bf16 v[120:123], v[194:197], v[202:205], v[120:123]
	v_mfma_f32_16x16x32_bf16 v[104:107], v[178:181], v[206:209], v[104:107]
	v_mfma_f32_16x16x32_bf16 v[104:107], v[194:197], v[210:213], v[104:107]
	v_mfma_f32_16x16x32_bf16 v[108:111], v[170:173], v[206:209], v[108:111]
	v_mfma_f32_16x16x32_bf16 v[108:111], v[174:177], v[210:213], v[108:111]
	v_mfma_f32_16x16x32_bf16 v[112:115], v[162:165], v[206:209], v[112:115]
	v_mfma_f32_16x16x32_bf16 v[112:115], v[166:169], v[210:213], v[112:115]
	v_mfma_f32_16x16x32_bf16 v[116:119], v[136:139], v[206:209], v[116:119]
	v_mfma_f32_16x16x32_bf16 v[116:119], v[158:161], v[210:213], v[116:119]
	v_mfma_f32_16x16x32_bf16 v[100:103], v[136:139], v[214:217], v[100:103]
	v_mfma_f32_16x16x32_bf16 v[100:103], v[158:161], v[218:221], v[100:103]
	v_mfma_f32_16x16x32_bf16 v[96:99], v[162:165], v[214:217], v[96:99]
	v_mfma_f32_16x16x32_bf16 v[96:99], v[166:169], v[218:221], v[96:99]
	v_mfma_f32_16x16x32_bf16 v[92:95], v[170:173], v[214:217], v[92:95]
	v_mfma_f32_16x16x32_bf16 v[92:95], v[174:177], v[218:221], v[92:95]
	v_mfma_f32_16x16x32_bf16 v[88:91], v[178:181], v[214:217], v[88:91]
	v_mfma_f32_16x16x32_bf16 v[88:91], v[194:197], v[218:221], v[88:91]
	v_mfma_f32_16x16x32_bf16 v[72:75], v[178:181], v[222:225], v[72:75]
	v_mfma_f32_16x16x32_bf16 v[72:75], v[194:197], v[226:229], v[72:75]
	v_mfma_f32_16x16x32_bf16 v[76:79], v[170:173], v[222:225], v[76:79]
	v_mfma_f32_16x16x32_bf16 v[76:79], v[174:177], v[226:229], v[76:79]
	v_mfma_f32_16x16x32_bf16 v[80:83], v[162:165], v[222:225], v[80:83]
	v_mfma_f32_16x16x32_bf16 v[80:83], v[166:169], v[226:229], v[80:83]
	v_mfma_f32_16x16x32_bf16 v[84:87], v[136:139], v[222:225], v[84:87]
	v_mfma_f32_16x16x32_bf16 v[84:87], v[158:161], v[226:229], v[84:87]
	s_setprio 0
	s_barrier
	s_add_i32 s0, s0, s19
	s_add_i32 m0, s0, 0xffffff80
	ds_read_b128 v[198:201], v193 offset:49152
	ds_read_b128 v[202:205], v193 offset:50176
	ds_read_b128 v[206:209], v193 offset:51200
	ds_read_b128 v[210:213], v193 offset:52224
	ds_read_b128 v[214:217], v193 offset:53248
	ds_read_b128 v[218:221], v193 offset:54272
	ds_read_b128 v[222:225], v193 offset:55296
	ds_read_b128 v[226:229], v193 offset:56320
	global_load_lds_dwordx4 v142, s[50:51] offset:128
	s_add_i32 m0, s0, 0x1f80
	s_add_i32 s0, s71, s19
	global_load_lds_dwordx4 v146, s[50:51] offset:128
	s_add_u32 s50, s50, 0x100080
	s_addc_u32 s51, s51, 0
	s_mov_b32 m0, s0
	s_nop 0
	global_load_lds_dwordx4 v142, s[50:51]
	s_add_i32 m0, s0, 0x2000
	s_nop 0
	global_load_lds_dwordx4 v146, s[50:51]
	s_add_i32 m0, s56, 0xffffff80
	s_nop 0
	global_load_lds_dwordx4 v140, s[52:53] offset:128
	s_add_i32 m0, s57, 0xffffff80
	s_nop 0
	global_load_lds_dwordx4 v144, s[52:53] offset:128
	s_setprio 1
	s_waitcnt vmcnt(8) lgkmcnt(0)
	s_barrier
	v_mfma_f32_16x16x32_bf16 v[68:71], v[136:139], v[198:201], v[68:71]
	v_mfma_f32_16x16x32_bf16 v[68:71], v[158:161], v[202:205], v[68:71]
	v_mfma_f32_16x16x32_bf16 v[64:67], v[162:165], v[198:201], v[64:67]
	v_mfma_f32_16x16x32_bf16 v[64:67], v[166:169], v[202:205], v[64:67]
	v_mfma_f32_16x16x32_bf16 v[60:63], v[170:173], v[198:201], v[60:63]
	v_mfma_f32_16x16x32_bf16 v[60:63], v[174:177], v[202:205], v[60:63]
	v_mfma_f32_16x16x32_bf16 v[56:59], v[178:181], v[198:201], v[56:59]
	v_mfma_f32_16x16x32_bf16 v[56:59], v[194:197], v[202:205], v[56:59]
	v_mfma_f32_16x16x32_bf16 v[52:55], v[136:139], v[206:209], v[52:55]
	v_mfma_f32_16x16x32_bf16 v[52:55], v[158:161], v[210:213], v[52:55]
	v_mfma_f32_16x16x32_bf16 v[48:51], v[162:165], v[206:209], v[48:51]
	v_mfma_f32_16x16x32_bf16 v[48:51], v[166:169], v[210:213], v[48:51]
	v_mfma_f32_16x16x32_bf16 v[44:47], v[170:173], v[206:209], v[44:47]
	v_mfma_f32_16x16x32_bf16 v[44:47], v[174:177], v[210:213], v[44:47]
	v_mfma_f32_16x16x32_bf16 v[40:43], v[178:181], v[206:209], v[40:43]
	v_mfma_f32_16x16x32_bf16 v[40:43], v[194:197], v[210:213], v[40:43]
	v_mfma_f32_16x16x32_bf16 v[36:39], v[136:139], v[214:217], v[36:39]
	v_mfma_f32_16x16x32_bf16 v[36:39], v[158:161], v[218:221], v[36:39]
	v_mfma_f32_16x16x32_bf16 v[32:35], v[162:165], v[214:217], v[32:35]
	v_mfma_f32_16x16x32_bf16 v[32:35], v[166:169], v[218:221], v[32:35]
	v_mfma_f32_16x16x32_bf16 v[28:31], v[170:173], v[214:217], v[28:31]
	v_mfma_f32_16x16x32_bf16 v[28:31], v[174:177], v[218:221], v[28:31]
	v_mfma_f32_16x16x32_bf16 v[24:27], v[178:181], v[214:217], v[24:27]
	v_mfma_f32_16x16x32_bf16 v[24:27], v[194:197], v[218:221], v[24:27]
	v_mfma_f32_16x16x32_bf16 v[20:23], v[136:139], v[222:225], v[20:23]
	v_mfma_f32_16x16x32_bf16 v[20:23], v[158:161], v[226:229], v[20:23]
	v_mfma_f32_16x16x32_bf16 v[16:19], v[162:165], v[222:225], v[16:19]
	v_mfma_f32_16x16x32_bf16 v[16:19], v[166:169], v[226:229], v[16:19]
	v_mfma_f32_16x16x32_bf16 v[10:13], v[170:173], v[222:225], v[12:15]
	v_mfma_f32_16x16x32_bf16 v[12:15], v[174:177], v[226:229], v[10:13]
	v_mfma_f32_16x16x32_bf16 v[6:9], v[178:181], v[222:225], v[6:9]
	v_mfma_f32_16x16x32_bf16 v[8:11], v[194:197], v[226:229], v[6:9]
	s_setprio 0
	s_barrier
	s_add_i32 s70, s70, 2
	s_add_u32 s42, s42, 0x100
	s_addc_u32 s43, s43, 0
	s_add_u32 s67, s67, 0x100
	s_addc_u32 s68, s68, 0
	s_cmp_gt_u32 s70, 61
	s_cbranch_scc0 .LBB0_170
	s_and_b64 vcc, exec, s[16:17]
	s_cbranch_vccz .LBB0_173
	s_barrier

.LBB0_342:
	ds_read_b128 v[132:135], v209
	ds_read_b128 v[136:139], v209 offset:1024
	ds_read_b128 v[140:143], v209 offset:2048
	ds_read_b128 v[144:147], v209 offset:3072
	ds_read_b128 v[148:151], v210
	ds_read_b128 v[152:155], v210 offset:1024
	ds_read_b128 v[156:159], v210 offset:2048
	ds_read_b128 v[160:163], v210 offset:3072
	s_add_u32 s0, s26, 0xffd50080
	s_addc_u32 s28, s27, -1
	s_cmpk_eq_i32 s62, 0xa8
	s_cselect_b32 s31, s7, s28
	s_cselect_b32 s30, s6, s0
	s_cselect_b32 s29, s25, s61
	s_cselect_b32 s28, s24, s60
	s_add_i32 m0, s43, 0xc000
	ds_read_b128 v[164:167], v211
	ds_read_b128 v[168:171], v211 offset:1024
	ds_read_b128 v[172:175], v211 offset:2048
	ds_read_b128 v[176:179], v211 offset:3072
	ds_read_b128 v[196:199], v211 offset:4096
	ds_read_b128 v[200:203], v211 offset:5120
	ds_read_b128 v[204:207], v211 offset:6144
	ds_read_b128 v[214:217], v211 offset:7168
	global_load_lds_dwordx4 v188, s[26:27]
	s_add_i32 m0, s43, 0xe000
	s_nop 0
	global_load_lds_dwordx4 v190, s[26:27]
	s_setprio 1
	s_waitcnt vmcnt(8) lgkmcnt(0)
	s_barrier
	v_mfma_f32_16x16x32_bf16 v[128:131], v[132:135], v[164:167], v[128:131]
	v_mfma_f32_16x16x32_bf16 v[128:131], v[136:139], v[168:171], v[128:131]
	v_mfma_f32_16x16x32_bf16 v[124:127], v[140:143], v[164:167], v[124:127]
	v_mfma_f32_16x16x32_bf16 v[124:127], v[144:147], v[168:171], v[124:127]
	v_mfma_f32_16x16x32_bf16 v[120:123], v[148:151], v[164:167], v[120:123]
	v_mfma_f32_16x16x32_bf16 v[120:123], v[152:155], v[168:171], v[120:123]
	v_mfma_f32_16x16x32_bf16 v[116:119], v[156:159], v[164:167], v[116:119]
	v_mfma_f32_16x16x32_bf16 v[116:119], v[160:163], v[168:171], v[116:119]
	v_mfma_f32_16x16x32_bf16 v[100:103], v[156:159], v[172:175], v[100:103]
	v_mfma_f32_16x16x32_bf16 v[100:103], v[160:163], v[176:179], v[100:103]
	v_mfma_f32_16x16x32_bf16 v[104:107], v[148:151], v[172:175], v[104:107]
	v_mfma_f32_16x16x32_bf16 v[104:107], v[152:155], v[176:179], v[104:107]
	v_mfma_f32_16x16x32_bf16 v[108:111], v[140:143], v[172:175], v[108:111]
	v_mfma_f32_16x16x32_bf16 v[108:111], v[144:147], v[176:179], v[108:111]
	v_mfma_f32_16x16x32_bf16 v[112:115], v[132:135], v[172:175], v[112:115]
	v_mfma_f32_16x16x32_bf16 v[112:115], v[136:139], v[176:179], v[112:115]
	v_mfma_f32_16x16x32_bf16 v[96:99], v[132:135], v[196:199], v[96:99]
	v_mfma_f32_16x16x32_bf16 v[96:99], v[136:139], v[200:203], v[96:99]
	v_mfma_f32_16x16x32_bf16 v[92:95], v[140:143], v[196:199], v[92:95]
	v_mfma_f32_16x16x32_bf16 v[92:95], v[144:147], v[200:203], v[92:95]
	v_mfma_f32_16x16x32_bf16 v[88:91], v[148:151], v[196:199], v[88:91]
	v_mfma_f32_16x16x32_bf16 v[88:91], v[152:155], v[200:203], v[88:91]
	v_mfma_f32_16x16x32_bf16 v[84:87], v[156:159], v[196:199], v[84:87]
	v_mfma_f32_16x16x32_bf16 v[84:87], v[160:163], v[200:203], v[84:87]
	v_mfma_f32_16x16x32_bf16 v[68:71], v[156:159], v[204:207], v[68:71]
	v_mfma_f32_16x16x32_bf16 v[68:71], v[160:163], v[214:217], v[68:71]
	v_mfma_f32_16x16x32_bf16 v[72:75], v[148:151], v[204:207], v[72:75]
	v_mfma_f32_16x16x32_bf16 v[72:75], v[152:155], v[214:217], v[72:75]
	v_mfma_f32_16x16x32_bf16 v[76:79], v[140:143], v[204:207], v[76:79]
	v_mfma_f32_16x16x32_bf16 v[76:79], v[144:147], v[214:217], v[76:79]
	v_mfma_f32_16x16x32_bf16 v[80:83], v[132:135], v[204:207], v[80:83]
	v_mfma_f32_16x16x32_bf16 v[80:83], v[136:139], v[214:217], v[80:83]
	s_setprio 0
	s_barrier
	s_add_i32 s0, s53, s42
	s_mov_b32 m0, s0
	ds_read_b128 v[164:167], v211 offset:16384
	ds_read_b128 v[168:171], v211 offset:17408
	ds_read_b128 v[172:175], v211 offset:18432
	ds_read_b128 v[176:179], v211 offset:19456
	ds_read_b128 v[196:199], v211 offset:20480
	ds_read_b128 v[200:203], v211 offset:21504
	ds_read_b128 v[204:207], v211 offset:22528
	ds_read_b128 v[214:217], v211 offset:23552
	global_load_lds_dwordx4 v182, s[28:29]
	s_add_i32 m0, s0, 0x2000
	s_add_u32 s64, s28, 0x2b0000
	s_addc_u32 s65, s29, 0
	s_add_i32 s0, s54, s42
	global_load_lds_dwordx4 v186, s[28:29]
	s_mov_b32 m0, s0
	s_nop 0
	global_load_lds_dwordx4 v182, s[64:65]
	s_add_i32 m0, s0, 0x2000
	s_nop 0
	global_load_lds_dwordx4 v186, s[64:65]
	s_mov_b32 m0, s43
	s_nop 0
	global_load_lds_dwordx4 v180, s[30:31]
	s_mov_b32 m0, s45
	s_nop 0
	global_load_lds_dwordx4 v184, s[30:31]
	s_setprio 1
	s_waitcnt vmcnt(8) lgkmcnt(0)
	s_barrier
	v_mfma_f32_16x16x32_bf16 v[64:67], v[132:135], v[164:167], v[64:67]
	v_mfma_f32_16x16x32_bf16 v[64:67], v[136:139], v[168:171], v[64:67]
	v_mfma_f32_16x16x32_bf16 v[60:63], v[140:143], v[164:167], v[60:63]
	v_mfma_f32_16x16x32_bf16 v[60:63], v[144:147], v[168:171], v[60:63]
	v_mfma_f32_16x16x32_bf16 v[56:59], v[148:151], v[164:167], v[56:59]
	v_mfma_f32_16x16x32_bf16 v[56:59], v[152:155], v[168:171], v[56:59]
	v_mfma_f32_16x16x32_bf16 v[52:55], v[156:159], v[164:167], v[52:55]
	v_mfma_f32_16x16x32_bf16 v[52:55], v[160:163], v[168:171], v[52:55]
	v_mfma_f32_16x16x32_bf16 v[36:39], v[156:159], v[172:175], v[36:39]
	v_mfma_f32_16x16x32_bf16 v[36:39], v[160:163], v[176:179], v[36:39]
	v_mfma_f32_16x16x32_bf16 v[40:43], v[148:151], v[172:175], v[40:43]
	v_mfma_f32_16x16x32_bf16 v[40:43], v[152:155], v[176:179], v[40:43]
	v_mfma_f32_16x16x32_bf16 v[44:47], v[140:143], v[172:175], v[44:47]
	v_mfma_f32_16x16x32_bf16 v[44:47], v[144:147], v[176:179], v[44:47]
	v_mfma_f32_16x16x32_bf16 v[48:51], v[132:135], v[172:175], v[48:51]
	v_mfma_f32_16x16x32_bf16 v[48:51], v[136:139], v[176:179], v[48:51]
	v_mfma_f32_16x16x32_bf16 v[32:35], v[132:135], v[196:199], v[32:35]
	v_mfma_f32_16x16x32_bf16 v[32:35], v[136:139], v[200:203], v[32:35]
	v_mfma_f32_16x16x32_bf16 v[28:31], v[140:143], v[196:199], v[28:31]
	v_mfma_f32_16x16x32_bf16 v[28:31], v[144:147], v[200:203], v[28:31]
	v_mfma_f32_16x16x32_bf16 v[24:27], v[148:151], v[196:199], v[24:27]
	v_mfma_f32_16x16x32_bf16 v[24:27], v[152:155], v[200:203], v[24:27]
	v_mfma_f32_16x16x32_bf16 v[20:23], v[156:159], v[196:199], v[20:23]
	v_mfma_f32_16x16x32_bf16 v[20:23], v[160:163], v[200:203], v[20:23]
	v_mfma_f32_16x16x32_bf16 v[4:7], v[156:159], v[204:207], v[4:7]
	v_mfma_f32_16x16x32_bf16 v[4:7], v[160:163], v[214:217], v[4:7]
	v_mfma_f32_16x16x32_bf16 v[8:11], v[148:151], v[204:207], v[8:11]
	v_mfma_f32_16x16x32_bf16 v[8:11], v[152:155], v[214:217], v[8:11]
	v_mfma_f32_16x16x32_bf16 v[12:15], v[140:143], v[204:207], v[12:15]
	v_mfma_f32_16x16x32_bf16 v[12:15], v[144:147], v[214:217], v[12:15]
	v_mfma_f32_16x16x32_bf16 v[16:19], v[132:135], v[204:207], v[16:19]
	v_mfma_f32_16x16x32_bf16 v[16:19], v[136:139], v[214:217], v[16:19]
	s_setprio 0
	s_barrier
	s_add_i32 s0, 0, 0x18000
	s_add_i32 s63, 0, 0x1c000
	v_add_u32_e32 v144, s0, v3
	v_add_u32_e32 v160, s63, v3
	ds_read_b128 v[132:135], v144
	ds_read_b128 v[136:139], v144 offset:1024
	ds_read_b128 v[140:143], v144 offset:2048
	ds_read_b128 v[144:147], v144 offset:3072
	ds_read_b128 v[148:151], v160
	ds_read_b128 v[152:155], v160 offset:1024
	ds_read_b128 v[156:159], v160 offset:2048
	ds_read_b128 v[160:163], v160 offset:3072
	s_add_u32 s98, s30, 0x2b0000
	s_addc_u32 s99, s31, 0
	s_mov_b32 m0, s46
	ds_read_b128 v[164:167], v211 offset:32768
	ds_read_b128 v[168:171], v211 offset:33792
	ds_read_b128 v[172:175], v211 offset:34816
	ds_read_b128 v[176:179], v211 offset:35840
	ds_read_b128 v[196:199], v211 offset:36864
	ds_read_b128 v[200:203], v211 offset:37888
	ds_read_b128 v[204:207], v211 offset:38912
	ds_read_b128 v[214:217], v211 offset:39936
	global_load_lds_dwordx4 v180, s[98:99]
	s_mov_b32 m0, s47
	s_nop 0
	global_load_lds_dwordx4 v184, s[98:99]
	s_setprio 1
	s_waitcnt vmcnt(8) lgkmcnt(0)
	s_barrier
	v_mfma_f32_16x16x32_bf16 v[128:131], v[132:135], v[164:167], v[128:131]
	v_mfma_f32_16x16x32_bf16 v[128:131], v[136:139], v[168:171], v[128:131]
	v_mfma_f32_16x16x32_bf16 v[124:127], v[140:143], v[164:167], v[124:127]
	v_mfma_f32_16x16x32_bf16 v[124:127], v[144:147], v[168:171], v[124:127]
	v_mfma_f32_16x16x32_bf16 v[120:123], v[148:151], v[164:167], v[120:123]
	v_mfma_f32_16x16x32_bf16 v[120:123], v[152:155], v[168:171], v[120:123]
	v_mfma_f32_16x16x32_bf16 v[116:119], v[156:159], v[164:167], v[116:119]
	v_mfma_f32_16x16x32_bf16 v[116:119], v[160:163], v[168:171], v[116:119]
	v_mfma_f32_16x16x32_bf16 v[100:103], v[156:159], v[172:175], v[100:103]
	v_mfma_f32_16x16x32_bf16 v[100:103], v[160:163], v[176:179], v[100:103]
	v_mfma_f32_16x16x32_bf16 v[104:107], v[148:151], v[172:175], v[104:107]
	v_mfma_f32_16x16x32_bf16 v[104:107], v[152:155], v[176:179], v[104:107]
	v_mfma_f32_16x16x32_bf16 v[108:111], v[140:143], v[172:175], v[108:111]
	v_mfma_f32_16x16x32_bf16 v[108:111], v[144:147], v[176:179], v[108:111]
	v_mfma_f32_16x16x32_bf16 v[112:115], v[132:135], v[172:175], v[112:115]
	v_mfma_f32_16x16x32_bf16 v[112:115], v[136:139], v[176:179], v[112:115]
	v_mfma_f32_16x16x32_bf16 v[96:99], v[132:135], v[196:199], v[96:99]
	v_mfma_f32_16x16x32_bf16 v[96:99], v[136:139], v[200:203], v[96:99]
	v_mfma_f32_16x16x32_bf16 v[92:95], v[140:143], v[196:199], v[92:95]
	v_mfma_f32_16x16x32_bf16 v[92:95], v[144:147], v[200:203], v[92:95]
	v_mfma_f32_16x16x32_bf16 v[88:91], v[148:151], v[196:199], v[88:91]
	v_mfma_f32_16x16x32_bf16 v[88:91], v[152:155], v[200:203], v[88:91]
	v_mfma_f32_16x16x32_bf16 v[84:87], v[156:159], v[196:199], v[84:87]
	v_mfma_f32_16x16x32_bf16 v[84:87], v[160:163], v[200:203], v[84:87]
	v_mfma_f32_16x16x32_bf16 v[68:71], v[156:159], v[204:207], v[68:71]
	v_mfma_f32_16x16x32_bf16 v[68:71], v[160:163], v[214:217], v[68:71]
	v_mfma_f32_16x16x32_bf16 v[72:75], v[148:151], v[204:207], v[72:75]
	v_mfma_f32_16x16x32_bf16 v[72:75], v[152:155], v[214:217], v[72:75]
	v_mfma_f32_16x16x32_bf16 v[76:79], v[140:143], v[204:207], v[76:79]
	v_mfma_f32_16x16x32_bf16 v[76:79], v[144:147], v[214:217], v[76:79]
	v_mfma_f32_16x16x32_bf16 v[80:83], v[132:135], v[204:207], v[80:83]
	v_mfma_f32_16x16x32_bf16 v[80:83], v[136:139], v[214:217], v[80:83]
	s_setprio 0
	s_barrier
	s_add_i32 s0, s0, s42
	s_add_i32 m0, s0, 0xffffff80
	ds_read_b128 v[164:167], v211 offset:49152
	ds_read_b128 v[168:171], v211 offset:50176
	ds_read_b128 v[172:175], v211 offset:51200
	ds_read_b128 v[176:179], v211 offset:52224
	ds_read_b128 v[196:199], v211 offset:53248
	ds_read_b128 v[200:203], v211 offset:54272
	ds_read_b128 v[204:207], v211 offset:55296
	ds_read_b128 v[214:217], v211 offset:56320
	global_load_lds_dwordx4 v182, s[28:29] offset:128
	s_add_i32 m0, s0, 0x1f80
	s_add_i32 s0, s63, s42
	global_load_lds_dwordx4 v186, s[28:29] offset:128
	s_add_u32 s28, s28, 0x2b0080
	s_addc_u32 s29, s29, 0
	s_mov_b32 m0, s0
	s_nop 0
	global_load_lds_dwordx4 v182, s[28:29]
	s_add_i32 m0, s0, 0x2000
	s_nop 0
	global_load_lds_dwordx4 v186, s[28:29]
	s_add_i32 m0, s51, 0xffffff80
	s_nop 0
	global_load_lds_dwordx4 v180, s[30:31] offset:128
	s_add_i32 m0, s52, 0xffffff80
	s_nop 0
	global_load_lds_dwordx4 v184, s[30:31] offset:128
	s_setprio 1
	s_waitcnt vmcnt(8) lgkmcnt(0)
	s_barrier
	v_mfma_f32_16x16x32_bf16 v[64:67], v[132:135], v[164:167], v[64:67]
	v_mfma_f32_16x16x32_bf16 v[64:67], v[136:139], v[168:171], v[64:67]
	v_mfma_f32_16x16x32_bf16 v[60:63], v[140:143], v[164:167], v[60:63]
	v_mfma_f32_16x16x32_bf16 v[60:63], v[144:147], v[168:171], v[60:63]
	v_mfma_f32_16x16x32_bf16 v[56:59], v[148:151], v[164:167], v[56:59]
	v_mfma_f32_16x16x32_bf16 v[56:59], v[152:155], v[168:171], v[56:59]
	v_mfma_f32_16x16x32_bf16 v[52:55], v[156:159], v[164:167], v[52:55]
	v_mfma_f32_16x16x32_bf16 v[52:55], v[160:163], v[168:171], v[52:55]
	v_mfma_f32_16x16x32_bf16 v[36:39], v[156:159], v[172:175], v[36:39]
	v_mfma_f32_16x16x32_bf16 v[36:39], v[160:163], v[176:179], v[36:39]
	v_mfma_f32_16x16x32_bf16 v[40:43], v[148:151], v[172:175], v[40:43]
	v_mfma_f32_16x16x32_bf16 v[40:43], v[152:155], v[176:179], v[40:43]
	v_mfma_f32_16x16x32_bf16 v[44:47], v[140:143], v[172:175], v[44:47]
	v_mfma_f32_16x16x32_bf16 v[44:47], v[144:147], v[176:179], v[44:47]
	v_mfma_f32_16x16x32_bf16 v[48:51], v[132:135], v[172:175], v[48:51]
	v_mfma_f32_16x16x32_bf16 v[48:51], v[136:139], v[176:179], v[48:51]
	v_mfma_f32_16x16x32_bf16 v[32:35], v[132:135], v[196:199], v[32:35]
	v_mfma_f32_16x16x32_bf16 v[32:35], v[136:139], v[200:203], v[32:35]
	v_mfma_f32_16x16x32_bf16 v[28:31], v[140:143], v[196:199], v[28:31]
	v_mfma_f32_16x16x32_bf16 v[28:31], v[144:147], v[200:203], v[28:31]
	v_mfma_f32_16x16x32_bf16 v[24:27], v[148:151], v[196:199], v[24:27]
	v_mfma_f32_16x16x32_bf16 v[24:27], v[152:155], v[200:203], v[24:27]
	v_mfma_f32_16x16x32_bf16 v[20:23], v[156:159], v[196:199], v[20:23]
	v_mfma_f32_16x16x32_bf16 v[20:23], v[160:163], v[200:203], v[20:23]
	v_mfma_f32_16x16x32_bf16 v[4:7], v[156:159], v[204:207], v[4:7]
	v_mfma_f32_16x16x32_bf16 v[4:7], v[160:163], v[214:217], v[4:7]
	v_mfma_f32_16x16x32_bf16 v[8:11], v[148:151], v[204:207], v[8:11]
	v_mfma_f32_16x16x32_bf16 v[8:11], v[152:155], v[214:217], v[8:11]
	v_mfma_f32_16x16x32_bf16 v[12:15], v[140:143], v[204:207], v[12:15]
	v_mfma_f32_16x16x32_bf16 v[12:15], v[144:147], v[214:217], v[12:15]
	v_mfma_f32_16x16x32_bf16 v[16:19], v[132:135], v[204:207], v[16:19]
	v_mfma_f32_16x16x32_bf16 v[16:19], v[136:139], v[214:217], v[16:19]
	s_setprio 0
	s_barrier
	s_add_i32 s62, s62, 2
	s_add_u32 s26, s26, 0x100
	s_addc_u32 s27, s27, 0
	s_add_u32 s60, s60, 0x100
	s_addc_u32 s61, s61, 0
	s_cmpk_gt_u32 s62, 0xa9
	s_cbranch_scc0 .LBB0_342
	s_and_b64 vcc, exec, s[22:23]
	s_cbranch_vccz .LBB0_345
	s_barrier

.LBB0_429:
	ds_read_b128 v[150:153], v156
	ds_read_b128 v[162:165], v156 offset:1024
	ds_read_b128 v[166:169], v156 offset:2048
	ds_read_b128 v[170:173], v156 offset:3072
	ds_read_b128 v[174:177], v157
	ds_read_b128 v[178:181], v157 offset:1024
	ds_read_b128 v[182:185], v157 offset:2048
	ds_read_b128 v[186:189], v157 offset:3072
	s_add_u32 s0, s50, 0xfff00080
	s_addc_u32 s52, s51, -1
	s_cmp_eq_u32 s72, 60
	s_cselect_b32 s55, s27, s52
	s_cselect_b32 s54, s67, s0
	s_cselect_b32 s53, s25, s71
	s_cselect_b32 s52, s68, s70
	s_add_i32 m0, s43, 0xc000
	ds_read_b128 v[190:193], v158
	ds_read_b128 v[194:197], v158 offset:1024
	ds_read_b128 v[198:201], v158 offset:2048
	ds_read_b128 v[202:205], v158 offset:3072
	ds_read_b128 v[206:209], v158 offset:4096
	ds_read_b128 v[210:213], v158 offset:5120
	ds_read_b128 v[214:217], v158 offset:6144
	ds_read_b128 v[218:221], v158 offset:7168
	global_load_lds_dwordx4 v142, s[50:51]
	s_add_i32 m0, s43, 0xe000
	s_nop 0
	global_load_lds_dwordx4 v144, s[50:51]
	s_setprio 1
	s_waitcnt vmcnt(8) lgkmcnt(0)
	s_barrier
	v_mfma_f32_16x16x32_bf16 v[128:131], v[150:153], v[190:193], v[128:131]
	v_mfma_f32_16x16x32_bf16 v[128:131], v[162:165], v[194:197], v[128:131]
	v_mfma_f32_16x16x32_bf16 v[124:127], v[166:169], v[190:193], v[124:127]
	v_mfma_f32_16x16x32_bf16 v[124:127], v[170:173], v[194:197], v[124:127]
	v_mfma_f32_16x16x32_bf16 v[120:123], v[174:177], v[190:193], v[120:123]
	v_mfma_f32_16x16x32_bf16 v[120:123], v[178:181], v[194:197], v[120:123]
	v_mfma_f32_16x16x32_bf16 v[116:119], v[182:185], v[190:193], v[116:119]
	v_mfma_f32_16x16x32_bf16 v[116:119], v[186:189], v[194:197], v[116:119]
	v_mfma_f32_16x16x32_bf16 v[100:103], v[182:185], v[198:201], v[100:103]
	v_mfma_f32_16x16x32_bf16 v[100:103], v[186:189], v[202:205], v[100:103]
	v_mfma_f32_16x16x32_bf16 v[104:107], v[174:177], v[198:201], v[104:107]
	v_mfma_f32_16x16x32_bf16 v[104:107], v[178:181], v[202:205], v[104:107]
	v_mfma_f32_16x16x32_bf16 v[108:111], v[166:169], v[198:201], v[108:111]
	v_mfma_f32_16x16x32_bf16 v[108:111], v[170:173], v[202:205], v[108:111]
	v_mfma_f32_16x16x32_bf16 v[112:115], v[150:153], v[198:201], v[112:115]
	v_mfma_f32_16x16x32_bf16 v[112:115], v[162:165], v[202:205], v[112:115]
	v_mfma_f32_16x16x32_bf16 v[96:99], v[150:153], v[206:209], v[96:99]
	v_mfma_f32_16x16x32_bf16 v[96:99], v[162:165], v[210:213], v[96:99]
	v_mfma_f32_16x16x32_bf16 v[92:95], v[166:169], v[206:209], v[92:95]
	v_mfma_f32_16x16x32_bf16 v[92:95], v[170:173], v[210:213], v[92:95]
	v_mfma_f32_16x16x32_bf16 v[88:91], v[174:177], v[206:209], v[88:91]
	v_mfma_f32_16x16x32_bf16 v[88:91], v[178:181], v[210:213], v[88:91]
	v_mfma_f32_16x16x32_bf16 v[84:87], v[182:185], v[206:209], v[84:87]
	v_mfma_f32_16x16x32_bf16 v[84:87], v[186:189], v[210:213], v[84:87]
	v_mfma_f32_16x16x32_bf16 v[68:71], v[182:185], v[214:217], v[68:71]
	v_mfma_f32_16x16x32_bf16 v[68:71], v[186:189], v[218:221], v[68:71]
	v_mfma_f32_16x16x32_bf16 v[72:75], v[174:177], v[214:217], v[72:75]
	v_mfma_f32_16x16x32_bf16 v[72:75], v[178:181], v[218:221], v[72:75]
	v_mfma_f32_16x16x32_bf16 v[76:79], v[166:169], v[214:217], v[76:79]
	v_mfma_f32_16x16x32_bf16 v[76:79], v[170:173], v[218:221], v[76:79]
	v_mfma_f32_16x16x32_bf16 v[80:83], v[150:153], v[214:217], v[80:83]
	v_mfma_f32_16x16x32_bf16 v[80:83], v[162:165], v[218:221], v[80:83]
	s_setprio 0
	s_barrier
	s_add_i32 s0, s62, s41
	s_mov_b32 m0, s0
	ds_read_b128 v[190:193], v158 offset:16384
	ds_read_b128 v[194:197], v158 offset:17408
	ds_read_b128 v[198:201], v158 offset:18432
	ds_read_b128 v[202:205], v158 offset:19456
	ds_read_b128 v[206:209], v158 offset:20480
	ds_read_b128 v[210:213], v158 offset:21504
	ds_read_b128 v[214:217], v158 offset:22528
	ds_read_b128 v[218:221], v158 offset:23552
	global_load_lds_dwordx4 v136, s[52:53]
	s_add_i32 m0, s0, 0x2000
	s_add_u32 s74, s52, 0x100000
	s_addc_u32 s75, s53, 0
	s_add_i32 s0, s63, s41
	global_load_lds_dwordx4 v140, s[52:53]
	s_mov_b32 m0, s0
	s_nop 0
	global_load_lds_dwordx4 v136, s[74:75]
	s_add_i32 m0, s0, 0x2000
	s_nop 0
	global_load_lds_dwordx4 v140, s[74:75]
	s_mov_b32 m0, s43
	s_nop 0
	global_load_lds_dwordx4 v134, s[54:55]
	s_mov_b32 m0, s48
	s_nop 0
	global_load_lds_dwordx4 v138, s[54:55]
	s_setprio 1
	s_waitcnt vmcnt(8) lgkmcnt(0)
	s_barrier
	v_mfma_f32_16x16x32_bf16 v[64:67], v[150:153], v[190:193], v[64:67]
	v_mfma_f32_16x16x32_bf16 v[64:67], v[162:165], v[194:197], v[64:67]
	v_mfma_f32_16x16x32_bf16 v[60:63], v[166:169], v[190:193], v[60:63]
	v_mfma_f32_16x16x32_bf16 v[60:63], v[170:173], v[194:197], v[60:63]
	v_mfma_f32_16x16x32_bf16 v[56:59], v[174:177], v[190:193], v[56:59]
	v_mfma_f32_16x16x32_bf16 v[56:59], v[178:181], v[194:197], v[56:59]
	v_mfma_f32_16x16x32_bf16 v[52:55], v[182:185], v[190:193], v[52:55]
	v_mfma_f32_16x16x32_bf16 v[52:55], v[186:189], v[194:197], v[52:55]
	v_mfma_f32_16x16x32_bf16 v[36:39], v[182:185], v[198:201], v[36:39]
	v_mfma_f32_16x16x32_bf16 v[36:39], v[186:189], v[202:205], v[36:39]
	v_mfma_f32_16x16x32_bf16 v[40:43], v[174:177], v[198:201], v[40:43]
	v_mfma_f32_16x16x32_bf16 v[40:43], v[178:181], v[202:205], v[40:43]
	v_mfma_f32_16x16x32_bf16 v[44:47], v[166:169], v[198:201], v[44:47]
	v_mfma_f32_16x16x32_bf16 v[44:47], v[170:173], v[202:205], v[44:47]
	v_mfma_f32_16x16x32_bf16 v[48:51], v[150:153], v[198:201], v[48:51]
	v_mfma_f32_16x16x32_bf16 v[48:51], v[162:165], v[202:205], v[48:51]
	v_mfma_f32_16x16x32_bf16 v[32:35], v[150:153], v[206:209], v[32:35]
	v_mfma_f32_16x16x32_bf16 v[32:35], v[162:165], v[210:213], v[32:35]
	v_mfma_f32_16x16x32_bf16 v[28:31], v[166:169], v[206:209], v[28:31]
	v_mfma_f32_16x16x32_bf16 v[28:31], v[170:173], v[210:213], v[28:31]
	v_mfma_f32_16x16x32_bf16 v[24:27], v[174:177], v[206:209], v[24:27]
	v_mfma_f32_16x16x32_bf16 v[24:27], v[178:181], v[210:213], v[24:27]
	v_mfma_f32_16x16x32_bf16 v[20:23], v[182:185], v[206:209], v[20:23]
	v_mfma_f32_16x16x32_bf16 v[20:23], v[186:189], v[210:213], v[20:23]
	v_mfma_f32_16x16x32_bf16 v[4:7], v[182:185], v[214:217], v[4:7]
	v_mfma_f32_16x16x32_bf16 v[4:7], v[186:189], v[218:221], v[4:7]
	v_mfma_f32_16x16x32_bf16 v[8:11], v[174:177], v[214:217], v[8:11]
	v_mfma_f32_16x16x32_bf16 v[8:11], v[178:181], v[218:221], v[8:11]
	v_mfma_f32_16x16x32_bf16 v[12:15], v[166:169], v[214:217], v[12:15]
	v_mfma_f32_16x16x32_bf16 v[12:15], v[170:173], v[218:221], v[12:15]
	v_mfma_f32_16x16x32_bf16 v[16:19], v[150:153], v[214:217], v[16:19]
	v_mfma_f32_16x16x32_bf16 v[16:19], v[162:165], v[218:221], v[16:19]
	s_setprio 0
	s_barrier
	s_add_i32 s0, 0, 0x18000
	v_add_u32_e32 v161, s0, v133
	s_add_i32 s73, 0, 0x1c000
	ds_read_b128 v[150:153], v161
	ds_read_b128 v[162:165], v161 offset:1024
	ds_read_b128 v[166:169], v161 offset:2048
	ds_read_b128 v[170:173], v161 offset:3072
	v_add_u32_e32 v161, s73, v133
	ds_read_b128 v[174:177], v161
	ds_read_b128 v[178:181], v161 offset:1024
	ds_read_b128 v[182:185], v161 offset:2048
	ds_read_b128 v[186:189], v161 offset:3072
	s_add_u32 s98, s54, 0x100000
	s_addc_u32 s99, s55, 0
	s_mov_b32 m0, s49
	ds_read_b128 v[190:193], v158 offset:32768
	ds_read_b128 v[194:197], v158 offset:33792
	ds_read_b128 v[198:201], v158 offset:34816
	ds_read_b128 v[202:205], v158 offset:35840
	ds_read_b128 v[206:209], v158 offset:36864
	ds_read_b128 v[210:213], v158 offset:37888
	ds_read_b128 v[214:217], v158 offset:38912
	ds_read_b128 v[218:221], v158 offset:39936
	global_load_lds_dwordx4 v134, s[98:99]
	s_mov_b32 m0, s56
	s_nop 0
	global_load_lds_dwordx4 v138, s[98:99]
	s_setprio 1
	s_waitcnt vmcnt(8) lgkmcnt(0)
	s_barrier
	v_mfma_f32_16x16x32_bf16 v[128:131], v[150:153], v[190:193], v[128:131]
	v_mfma_f32_16x16x32_bf16 v[128:131], v[162:165], v[194:197], v[128:131]
	v_mfma_f32_16x16x32_bf16 v[124:127], v[166:169], v[190:193], v[124:127]
	v_mfma_f32_16x16x32_bf16 v[124:127], v[170:173], v[194:197], v[124:127]
	v_mfma_f32_16x16x32_bf16 v[120:123], v[174:177], v[190:193], v[120:123]
	v_mfma_f32_16x16x32_bf16 v[120:123], v[178:181], v[194:197], v[120:123]
	v_mfma_f32_16x16x32_bf16 v[116:119], v[182:185], v[190:193], v[116:119]
	v_mfma_f32_16x16x32_bf16 v[116:119], v[186:189], v[194:197], v[116:119]
	v_mfma_f32_16x16x32_bf16 v[100:103], v[182:185], v[198:201], v[100:103]
	v_mfma_f32_16x16x32_bf16 v[100:103], v[186:189], v[202:205], v[100:103]
	v_mfma_f32_16x16x32_bf16 v[104:107], v[174:177], v[198:201], v[104:107]
	v_mfma_f32_16x16x32_bf16 v[104:107], v[178:181], v[202:205], v[104:107]
	v_mfma_f32_16x16x32_bf16 v[108:111], v[166:169], v[198:201], v[108:111]
	v_mfma_f32_16x16x32_bf16 v[108:111], v[170:173], v[202:205], v[108:111]
	v_mfma_f32_16x16x32_bf16 v[112:115], v[150:153], v[198:201], v[112:115]
	v_mfma_f32_16x16x32_bf16 v[112:115], v[162:165], v[202:205], v[112:115]
	v_mfma_f32_16x16x32_bf16 v[96:99], v[150:153], v[206:209], v[96:99]
	v_mfma_f32_16x16x32_bf16 v[96:99], v[162:165], v[210:213], v[96:99]
	v_mfma_f32_16x16x32_bf16 v[92:95], v[166:169], v[206:209], v[92:95]
	v_mfma_f32_16x16x32_bf16 v[92:95], v[170:173], v[210:213], v[92:95]
	v_mfma_f32_16x16x32_bf16 v[88:91], v[174:177], v[206:209], v[88:91]
	v_mfma_f32_16x16x32_bf16 v[88:91], v[178:181], v[210:213], v[88:91]
	v_mfma_f32_16x16x32_bf16 v[84:87], v[182:185], v[206:209], v[84:87]
	v_mfma_f32_16x16x32_bf16 v[84:87], v[186:189], v[210:213], v[84:87]
	v_mfma_f32_16x16x32_bf16 v[68:71], v[182:185], v[214:217], v[68:71]
	v_mfma_f32_16x16x32_bf16 v[68:71], v[186:189], v[218:221], v[68:71]
	v_mfma_f32_16x16x32_bf16 v[72:75], v[174:177], v[214:217], v[72:75]
	v_mfma_f32_16x16x32_bf16 v[72:75], v[178:181], v[218:221], v[72:75]
	v_mfma_f32_16x16x32_bf16 v[76:79], v[166:169], v[214:217], v[76:79]
	v_mfma_f32_16x16x32_bf16 v[76:79], v[170:173], v[218:221], v[76:79]
	v_mfma_f32_16x16x32_bf16 v[80:83], v[150:153], v[214:217], v[80:83]
	v_mfma_f32_16x16x32_bf16 v[80:83], v[162:165], v[218:221], v[80:83]
	s_setprio 0
	s_barrier
	s_add_i32 s0, s0, s41
	s_add_i32 m0, s0, 0xffffff80
	ds_read_b128 v[190:193], v158 offset:49152
	ds_read_b128 v[194:197], v158 offset:50176
	ds_read_b128 v[198:201], v158 offset:51200
	ds_read_b128 v[202:205], v158 offset:52224
	ds_read_b128 v[206:209], v158 offset:53248
	ds_read_b128 v[210:213], v158 offset:54272
	ds_read_b128 v[214:217], v158 offset:55296
	ds_read_b128 v[218:221], v158 offset:56320
	global_load_lds_dwordx4 v136, s[52:53] offset:128
	s_add_i32 m0, s0, 0x1f80
	s_add_i32 s0, s73, s41
	global_load_lds_dwordx4 v140, s[52:53] offset:128
	s_add_u32 s52, s52, 0x100080
	s_addc_u32 s53, s53, 0
	s_mov_b32 m0, s0
	s_nop 0
	global_load_lds_dwordx4 v136, s[52:53]
	s_add_i32 m0, s0, 0x2000
	s_nop 0
	global_load_lds_dwordx4 v140, s[52:53]
	s_add_i32 m0, s59, 0xffffff80
	s_nop 0
	global_load_lds_dwordx4 v134, s[54:55] offset:128
	s_add_i32 m0, s60, 0xffffff80
	s_nop 0
	global_load_lds_dwordx4 v138, s[54:55] offset:128
	s_setprio 1
	s_waitcnt vmcnt(8) lgkmcnt(0)
	s_barrier
	v_mfma_f32_16x16x32_bf16 v[64:67], v[150:153], v[190:193], v[64:67]
	v_mfma_f32_16x16x32_bf16 v[64:67], v[162:165], v[194:197], v[64:67]
	v_mfma_f32_16x16x32_bf16 v[60:63], v[166:169], v[190:193], v[60:63]
	v_mfma_f32_16x16x32_bf16 v[60:63], v[170:173], v[194:197], v[60:63]
	v_mfma_f32_16x16x32_bf16 v[56:59], v[174:177], v[190:193], v[56:59]
	v_mfma_f32_16x16x32_bf16 v[56:59], v[178:181], v[194:197], v[56:59]
	v_mfma_f32_16x16x32_bf16 v[52:55], v[182:185], v[190:193], v[52:55]
	v_mfma_f32_16x16x32_bf16 v[52:55], v[186:189], v[194:197], v[52:55]
	v_mfma_f32_16x16x32_bf16 v[36:39], v[182:185], v[198:201], v[36:39]
	v_mfma_f32_16x16x32_bf16 v[36:39], v[186:189], v[202:205], v[36:39]
	v_mfma_f32_16x16x32_bf16 v[40:43], v[174:177], v[198:201], v[40:43]
	v_mfma_f32_16x16x32_bf16 v[40:43], v[178:181], v[202:205], v[40:43]
	v_mfma_f32_16x16x32_bf16 v[44:47], v[166:169], v[198:201], v[44:47]
	v_mfma_f32_16x16x32_bf16 v[44:47], v[170:173], v[202:205], v[44:47]
	v_mfma_f32_16x16x32_bf16 v[48:51], v[150:153], v[198:201], v[48:51]
	v_mfma_f32_16x16x32_bf16 v[48:51], v[162:165], v[202:205], v[48:51]
	v_mfma_f32_16x16x32_bf16 v[32:35], v[150:153], v[206:209], v[32:35]
	v_mfma_f32_16x16x32_bf16 v[32:35], v[162:165], v[210:213], v[32:35]
	v_mfma_f32_16x16x32_bf16 v[28:31], v[166:169], v[206:209], v[28:31]
	v_mfma_f32_16x16x32_bf16 v[28:31], v[170:173], v[210:213], v[28:31]
	v_mfma_f32_16x16x32_bf16 v[24:27], v[174:177], v[206:209], v[24:27]
	v_mfma_f32_16x16x32_bf16 v[24:27], v[178:181], v[210:213], v[24:27]
	v_mfma_f32_16x16x32_bf16 v[20:23], v[182:185], v[206:209], v[20:23]
	v_mfma_f32_16x16x32_bf16 v[20:23], v[186:189], v[210:213], v[20:23]
	v_mfma_f32_16x16x32_bf16 v[4:7], v[182:185], v[214:217], v[4:7]
	v_mfma_f32_16x16x32_bf16 v[4:7], v[186:189], v[218:221], v[4:7]
	v_mfma_f32_16x16x32_bf16 v[8:11], v[174:177], v[214:217], v[8:11]
	v_mfma_f32_16x16x32_bf16 v[8:11], v[178:181], v[218:221], v[8:11]
	v_mfma_f32_16x16x32_bf16 v[12:15], v[166:169], v[214:217], v[12:15]
	v_mfma_f32_16x16x32_bf16 v[12:15], v[170:173], v[218:221], v[12:15]
	v_mfma_f32_16x16x32_bf16 v[16:19], v[150:153], v[214:217], v[16:19]
	v_mfma_f32_16x16x32_bf16 v[16:19], v[162:165], v[218:221], v[16:19]
	s_setprio 0
	s_barrier
	s_add_i32 s72, s72, 2
	s_add_u32 s50, s50, 0x100
	s_addc_u32 s51, s51, 0
	s_add_u32 s70, s70, 0x100
	s_addc_u32 s71, s71, 0
	s_cmp_gt_u32 s72, 61
	s_cbranch_scc0 .LBB0_429
	s_and_b64 vcc, exec, s[22:23]
	s_cbranch_vccz .LBB0_432
	s_barrier

.LBB0_1032:
	v_add_u32_e32 v5, s60, v3
	ds_read_b128 v[140:143], v5
	ds_read_b128 v[144:147], v5 offset:1024
	ds_read_b128 v[148:151], v5 offset:2048
	ds_read_b128 v[152:155], v5 offset:3072
	v_add_u32_e32 v5, s61, v3
	ds_read_b128 v[156:159], v5
	ds_read_b128 v[160:163], v5 offset:1024
	ds_read_b128 v[164:167], v5 offset:2048
	ds_read_b128 v[168:171], v5 offset:3072
	s_add_u32 s42, s40, 0xfff80080
	s_addc_u32 s43, s41, -1
	s_cmp_eq_u32 s67, 28
	s_cselect_b32 s51, s5, s43
	s_cselect_b32 s50, s7, s42
	s_cselect_b32 s43, s25, s66
	s_cselect_b32 s42, s27, s65
	s_add_i32 m0, s47, 0xc000
	ds_read_b128 v[172:175], v246
	ds_read_b128 v[176:179], v246 offset:1024
	ds_read_b128 v[180:183], v246 offset:2048
	ds_read_b128 v[184:187], v246 offset:3072
	ds_read_b128 v[188:191], v246 offset:4096
	ds_read_b128 v[192:195], v246 offset:5120
	ds_read_b128 v[196:199], v246 offset:6144
	ds_read_b128 v[200:203], v246 offset:7168
	global_load_lds_dwordx4 v216, s[40:41]
	s_add_i32 m0, s47, 0xe000
	s_nop 0
	global_load_lds_dwordx4 v218, s[40:41]
	s_setprio 1
	s_waitcnt vmcnt(8) lgkmcnt(0)
	s_barrier
	v_mfma_f32_16x16x32_bf16 v[136:139], v[140:143], v[172:175], v[136:139]
	v_mfma_f32_16x16x32_bf16 v[136:139], v[144:147], v[176:179], v[136:139]
	v_mfma_f32_16x16x32_bf16 v[132:135], v[148:151], v[172:175], v[132:135]
	v_mfma_f32_16x16x32_bf16 v[132:135], v[152:155], v[176:179], v[132:135]
	v_mfma_f32_16x16x32_bf16 v[104:107], v[156:159], v[172:175], v[104:107]
	v_mfma_f32_16x16x32_bf16 v[104:107], v[160:163], v[176:179], v[104:107]
	v_mfma_f32_16x16x32_bf16 v[100:103], v[164:167], v[172:175], v[100:103]
	v_mfma_f32_16x16x32_bf16 v[100:103], v[168:171], v[176:179], v[100:103]
	v_mfma_f32_16x16x32_bf16 v[92:95], v[164:167], v[180:183], v[92:95]
	v_mfma_f32_16x16x32_bf16 v[92:95], v[168:171], v[184:187], v[92:95]
	v_mfma_f32_16x16x32_bf16 v[96:99], v[156:159], v[180:183], v[96:99]
	v_mfma_f32_16x16x32_bf16 v[96:99], v[160:163], v[184:187], v[96:99]
	v_mfma_f32_16x16x32_bf16 v[124:127], v[148:151], v[180:183], v[124:127]
	v_mfma_f32_16x16x32_bf16 v[124:127], v[152:155], v[184:187], v[124:127]
	v_mfma_f32_16x16x32_bf16 v[128:131], v[140:143], v[180:183], v[128:131]
	v_mfma_f32_16x16x32_bf16 v[128:131], v[144:147], v[184:187], v[128:131]
	v_mfma_f32_16x16x32_bf16 v[120:123], v[140:143], v[188:191], v[120:123]
	v_mfma_f32_16x16x32_bf16 v[120:123], v[144:147], v[192:195], v[120:123]
	v_mfma_f32_16x16x32_bf16 v[116:119], v[148:151], v[188:191], v[116:119]
	v_mfma_f32_16x16x32_bf16 v[116:119], v[152:155], v[192:195], v[116:119]
	v_mfma_f32_16x16x32_bf16 v[88:91], v[156:159], v[188:191], v[88:91]
	v_mfma_f32_16x16x32_bf16 v[88:91], v[160:163], v[192:195], v[88:91]
	v_mfma_f32_16x16x32_bf16 v[84:87], v[164:167], v[188:191], v[84:87]
	v_mfma_f32_16x16x32_bf16 v[84:87], v[168:171], v[192:195], v[84:87]
	v_mfma_f32_16x16x32_bf16 v[76:79], v[164:167], v[196:199], v[76:79]
	v_mfma_f32_16x16x32_bf16 v[76:79], v[168:171], v[200:203], v[76:79]
	v_mfma_f32_16x16x32_bf16 v[80:83], v[156:159], v[196:199], v[80:83]
	v_mfma_f32_16x16x32_bf16 v[80:83], v[160:163], v[200:203], v[80:83]
	v_mfma_f32_16x16x32_bf16 v[108:111], v[148:151], v[196:199], v[108:111]
	v_mfma_f32_16x16x32_bf16 v[108:111], v[152:155], v[200:203], v[108:111]
	v_mfma_f32_16x16x32_bf16 v[112:115], v[140:143], v[196:199], v[112:115]
	v_mfma_f32_16x16x32_bf16 v[112:115], v[144:147], v[200:203], v[112:115]
	s_setprio 0
	s_barrier
	s_add_i32 s68, s60, s46
	s_mov_b32 m0, s68
	ds_read_b128 v[172:175], v246 offset:16384
	ds_read_b128 v[176:179], v246 offset:17408
	ds_read_b128 v[180:183], v246 offset:18432
	ds_read_b128 v[184:187], v246 offset:19456
	ds_read_b128 v[188:191], v246 offset:20480
	ds_read_b128 v[192:195], v246 offset:21504
	ds_read_b128 v[196:199], v246 offset:22528
	ds_read_b128 v[200:203], v246 offset:23552
	global_load_lds_dwordx4 v210, s[42:43]
	s_add_i32 m0, s68, 0x2000
	s_add_u32 s70, s42, 0x80000
	s_addc_u32 s71, s43, 0
	s_add_i32 s68, s61, s46
	global_load_lds_dwordx4 v214, s[42:43]
	s_mov_b32 m0, s68
	s_nop 0
	global_load_lds_dwordx4 v210, s[70:71]
	s_add_i32 m0, s68, 0x2000
	s_nop 0
	global_load_lds_dwordx4 v214, s[70:71]
	s_mov_b32 m0, s47
	s_nop 0
	global_load_lds_dwordx4 v208, s[50:51]
	s_mov_b32 m0, s48
	s_nop 0
	global_load_lds_dwordx4 v212, s[50:51]
	s_setprio 1
	s_waitcnt vmcnt(8) lgkmcnt(0)
	s_barrier
	v_mfma_f32_16x16x32_bf16 v[72:75], v[140:143], v[172:175], v[72:75]
	v_mfma_f32_16x16x32_bf16 v[72:75], v[144:147], v[176:179], v[72:75]
	v_mfma_f32_16x16x32_bf16 v[68:71], v[148:151], v[172:175], v[68:71]
	v_mfma_f32_16x16x32_bf16 v[68:71], v[152:155], v[176:179], v[68:71]
	v_mfma_f32_16x16x32_bf16 v[40:43], v[156:159], v[172:175], v[40:43]
	v_mfma_f32_16x16x32_bf16 v[40:43], v[160:163], v[176:179], v[40:43]
	v_mfma_f32_16x16x32_bf16 v[36:39], v[164:167], v[172:175], v[36:39]
	v_mfma_f32_16x16x32_bf16 v[36:39], v[168:171], v[176:179], v[36:39]
	v_mfma_f32_16x16x32_bf16 v[28:31], v[164:167], v[180:183], v[28:31]
	v_mfma_f32_16x16x32_bf16 v[28:31], v[168:171], v[184:187], v[28:31]
	v_mfma_f32_16x16x32_bf16 v[32:35], v[156:159], v[180:183], v[32:35]
	v_mfma_f32_16x16x32_bf16 v[32:35], v[160:163], v[184:187], v[32:35]
	v_mfma_f32_16x16x32_bf16 v[60:63], v[148:151], v[180:183], v[60:63]
	v_mfma_f32_16x16x32_bf16 v[60:63], v[152:155], v[184:187], v[60:63]
	v_mfma_f32_16x16x32_bf16 v[64:67], v[140:143], v[180:183], v[64:67]
	v_mfma_f32_16x16x32_bf16 v[64:67], v[144:147], v[184:187], v[64:67]
	v_mfma_f32_16x16x32_bf16 v[56:59], v[140:143], v[188:191], v[56:59]
	v_mfma_f32_16x16x32_bf16 v[56:59], v[144:147], v[192:195], v[56:59]
	v_mfma_f32_16x16x32_bf16 v[52:55], v[148:151], v[188:191], v[52:55]
	v_mfma_f32_16x16x32_bf16 v[52:55], v[152:155], v[192:195], v[52:55]
	v_mfma_f32_16x16x32_bf16 v[24:27], v[156:159], v[188:191], v[24:27]
	v_mfma_f32_16x16x32_bf16 v[24:27], v[160:163], v[192:195], v[24:27]
	v_mfma_f32_16x16x32_bf16 v[20:23], v[164:167], v[188:191], v[20:23]
	v_mfma_f32_16x16x32_bf16 v[20:23], v[168:171], v[192:195], v[20:23]
	v_mfma_f32_16x16x32_bf16 v[12:15], v[164:167], v[196:199], v[12:15]
	v_mfma_f32_16x16x32_bf16 v[12:15], v[168:171], v[200:203], v[12:15]
	v_mfma_f32_16x16x32_bf16 v[16:19], v[156:159], v[196:199], v[16:19]
	v_mfma_f32_16x16x32_bf16 v[16:19], v[160:163], v[200:203], v[16:19]
	v_mfma_f32_16x16x32_bf16 v[44:47], v[148:151], v[196:199], v[44:47]
	v_mfma_f32_16x16x32_bf16 v[44:47], v[152:155], v[200:203], v[44:47]
	v_mfma_f32_16x16x32_bf16 v[48:51], v[140:143], v[196:199], v[48:51]
	v_mfma_f32_16x16x32_bf16 v[48:51], v[144:147], v[200:203], v[48:51]
	s_setprio 0
	s_barrier
	s_add_i32 s68, 0, 0x18000
	v_add_u32_e32 v5, s68, v3
	s_add_i32 s70, 0, 0x1c000
	ds_read_b128 v[140:143], v5
	ds_read_b128 v[144:147], v5 offset:1024
	ds_read_b128 v[148:151], v5 offset:2048
	ds_read_b128 v[152:155], v5 offset:3072
	v_add_u32_e32 v5, s70, v3
	ds_read_b128 v[156:159], v5
	ds_read_b128 v[160:163], v5 offset:1024
	ds_read_b128 v[164:167], v5 offset:2048
	ds_read_b128 v[168:171], v5 offset:3072
	s_add_u32 s98, s50, 0x80000
	s_addc_u32 s99, s51, 0
	s_mov_b64 s[100:101], s[50:51]
	s_mov_b32 m0, s49
	ds_read_b128 v[172:175], v246 offset:32768
	ds_read_b128 v[176:179], v246 offset:33792
	ds_read_b128 v[180:183], v246 offset:34816
	ds_read_b128 v[184:187], v246 offset:35840
	ds_read_b128 v[188:191], v246 offset:36864
	ds_read_b128 v[192:195], v246 offset:37888
	ds_read_b128 v[196:199], v246 offset:38912
	ds_read_b128 v[200:203], v246 offset:39936
	global_load_lds_dwordx4 v208, s[98:99]
	s_mov_b32 m0, s52
	s_nop 0
	global_load_lds_dwordx4 v212, s[98:99]
	s_setprio 1
	s_waitcnt vmcnt(8) lgkmcnt(0)
	s_barrier
	v_mfma_f32_16x16x32_bf16 v[136:139], v[140:143], v[172:175], v[136:139]
	v_mfma_f32_16x16x32_bf16 v[136:139], v[144:147], v[176:179], v[136:139]
	v_mfma_f32_16x16x32_bf16 v[132:135], v[148:151], v[172:175], v[132:135]
	v_mfma_f32_16x16x32_bf16 v[132:135], v[152:155], v[176:179], v[132:135]
	v_mfma_f32_16x16x32_bf16 v[104:107], v[156:159], v[172:175], v[104:107]
	v_mfma_f32_16x16x32_bf16 v[104:107], v[160:163], v[176:179], v[104:107]
	v_mfma_f32_16x16x32_bf16 v[100:103], v[164:167], v[172:175], v[100:103]
	v_mfma_f32_16x16x32_bf16 v[100:103], v[168:171], v[176:179], v[100:103]
	v_mfma_f32_16x16x32_bf16 v[92:95], v[164:167], v[180:183], v[92:95]
	v_mfma_f32_16x16x32_bf16 v[92:95], v[168:171], v[184:187], v[92:95]
	v_mfma_f32_16x16x32_bf16 v[96:99], v[156:159], v[180:183], v[96:99]
	v_mfma_f32_16x16x32_bf16 v[96:99], v[160:163], v[184:187], v[96:99]
	v_mfma_f32_16x16x32_bf16 v[124:127], v[148:151], v[180:183], v[124:127]
	v_mfma_f32_16x16x32_bf16 v[124:127], v[152:155], v[184:187], v[124:127]
	v_mfma_f32_16x16x32_bf16 v[128:131], v[140:143], v[180:183], v[128:131]
	v_mfma_f32_16x16x32_bf16 v[128:131], v[144:147], v[184:187], v[128:131]
	v_mfma_f32_16x16x32_bf16 v[120:123], v[140:143], v[188:191], v[120:123]
	v_mfma_f32_16x16x32_bf16 v[120:123], v[144:147], v[192:195], v[120:123]
	v_mfma_f32_16x16x32_bf16 v[116:119], v[148:151], v[188:191], v[116:119]
	v_mfma_f32_16x16x32_bf16 v[116:119], v[152:155], v[192:195], v[116:119]
	v_mfma_f32_16x16x32_bf16 v[88:91], v[156:159], v[188:191], v[88:91]
	v_mfma_f32_16x16x32_bf16 v[88:91], v[160:163], v[192:195], v[88:91]
	v_mfma_f32_16x16x32_bf16 v[84:87], v[164:167], v[188:191], v[84:87]
	v_mfma_f32_16x16x32_bf16 v[84:87], v[168:171], v[192:195], v[84:87]
	v_mfma_f32_16x16x32_bf16 v[76:79], v[164:167], v[196:199], v[76:79]
	v_mfma_f32_16x16x32_bf16 v[76:79], v[168:171], v[200:203], v[76:79]
	v_mfma_f32_16x16x32_bf16 v[80:83], v[156:159], v[196:199], v[80:83]
	v_mfma_f32_16x16x32_bf16 v[80:83], v[160:163], v[200:203], v[80:83]
	v_mfma_f32_16x16x32_bf16 v[108:111], v[148:151], v[196:199], v[108:111]
	v_mfma_f32_16x16x32_bf16 v[108:111], v[152:155], v[200:203], v[108:111]
	v_mfma_f32_16x16x32_bf16 v[112:115], v[140:143], v[196:199], v[112:115]
	v_mfma_f32_16x16x32_bf16 v[112:115], v[144:147], v[200:203], v[112:115]
	s_setprio 0
	s_barrier
	s_add_i32 s50, s68, s46
	s_add_i32 m0, s50, 0xffffff80
	ds_read_b128 v[172:175], v246 offset:49152
	ds_read_b128 v[176:179], v246 offset:50176
	ds_read_b128 v[180:183], v246 offset:51200
	ds_read_b128 v[184:187], v246 offset:52224
	ds_read_b128 v[188:191], v246 offset:53248
	ds_read_b128 v[192:195], v246 offset:54272
	ds_read_b128 v[196:199], v246 offset:55296
	ds_read_b128 v[200:203], v246 offset:56320
	global_load_lds_dwordx4 v210, s[42:43] offset:128
	s_add_i32 m0, s50, 0x1f80
	s_add_i32 s50, s70, s46
	global_load_lds_dwordx4 v214, s[42:43] offset:128
	s_add_u32 s42, s42, 0x80080
	s_addc_u32 s43, s43, 0
	s_mov_b32 m0, s50
	s_nop 0
	global_load_lds_dwordx4 v210, s[42:43]
	s_add_i32 m0, s50, 0x2000
	s_nop 0
	global_load_lds_dwordx4 v214, s[42:43]
	s_add_i32 m0, s58, 0xffffff80
	s_nop 0
	global_load_lds_dwordx4 v208, s[100:101] offset:128
	s_add_i32 m0, s59, 0xffffff80
	s_nop 0
	global_load_lds_dwordx4 v212, s[100:101] offset:128
	s_setprio 1
	s_waitcnt vmcnt(8) lgkmcnt(0)
	s_barrier
	v_mfma_f32_16x16x32_bf16 v[72:75], v[140:143], v[172:175], v[72:75]
	v_mfma_f32_16x16x32_bf16 v[72:75], v[144:147], v[176:179], v[72:75]
	v_mfma_f32_16x16x32_bf16 v[68:71], v[148:151], v[172:175], v[68:71]
	v_mfma_f32_16x16x32_bf16 v[68:71], v[152:155], v[176:179], v[68:71]
	v_mfma_f32_16x16x32_bf16 v[40:43], v[156:159], v[172:175], v[40:43]
	v_mfma_f32_16x16x32_bf16 v[40:43], v[160:163], v[176:179], v[40:43]
	v_mfma_f32_16x16x32_bf16 v[36:39], v[164:167], v[172:175], v[36:39]
	v_mfma_f32_16x16x32_bf16 v[36:39], v[168:171], v[176:179], v[36:39]
	v_mfma_f32_16x16x32_bf16 v[28:31], v[164:167], v[180:183], v[28:31]
	v_mfma_f32_16x16x32_bf16 v[28:31], v[168:171], v[184:187], v[28:31]
	v_mfma_f32_16x16x32_bf16 v[32:35], v[156:159], v[180:183], v[32:35]
	v_mfma_f32_16x16x32_bf16 v[32:35], v[160:163], v[184:187], v[32:35]
	v_mfma_f32_16x16x32_bf16 v[60:63], v[148:151], v[180:183], v[60:63]
	v_mfma_f32_16x16x32_bf16 v[60:63], v[152:155], v[184:187], v[60:63]
	v_mfma_f32_16x16x32_bf16 v[64:67], v[140:143], v[180:183], v[64:67]
	v_mfma_f32_16x16x32_bf16 v[64:67], v[144:147], v[184:187], v[64:67]
	v_mfma_f32_16x16x32_bf16 v[56:59], v[140:143], v[188:191], v[56:59]
	v_mfma_f32_16x16x32_bf16 v[56:59], v[144:147], v[192:195], v[56:59]
	v_mfma_f32_16x16x32_bf16 v[52:55], v[148:151], v[188:191], v[52:55]
	v_mfma_f32_16x16x32_bf16 v[52:55], v[152:155], v[192:195], v[52:55]
	v_mfma_f32_16x16x32_bf16 v[24:27], v[156:159], v[188:191], v[24:27]
	v_mfma_f32_16x16x32_bf16 v[24:27], v[160:163], v[192:195], v[24:27]
	v_mfma_f32_16x16x32_bf16 v[20:23], v[164:167], v[188:191], v[20:23]
	v_mfma_f32_16x16x32_bf16 v[20:23], v[168:171], v[192:195], v[20:23]
	v_mfma_f32_16x16x32_bf16 v[12:15], v[164:167], v[196:199], v[12:15]
	v_mfma_f32_16x16x32_bf16 v[12:15], v[168:171], v[200:203], v[12:15]
	v_mfma_f32_16x16x32_bf16 v[16:19], v[156:159], v[196:199], v[16:19]
	v_mfma_f32_16x16x32_bf16 v[16:19], v[160:163], v[200:203], v[16:19]
	v_mfma_f32_16x16x32_bf16 v[44:47], v[148:151], v[196:199], v[44:47]
	v_mfma_f32_16x16x32_bf16 v[44:47], v[152:155], v[200:203], v[44:47]
	v_mfma_f32_16x16x32_bf16 v[48:51], v[140:143], v[196:199], v[48:51]
	v_mfma_f32_16x16x32_bf16 v[48:51], v[144:147], v[200:203], v[48:51]
	s_setprio 0
	s_barrier
	s_add_i32 s67, s67, 2
	s_add_u32 s40, s40, 0x100
	s_addc_u32 s41, s41, 0
	s_add_u32 s65, s65, 0x100
	s_addc_u32 s66, s66, 0
	s_cmp_gt_u32 s67, 29
	s_cbranch_scc0 .LBB0_1032
	s_and_b64 vcc, exec, s[22:23]
	s_cbranch_vccz .LBB0_1035
	s_barrier

.LBB0_1203:
	ds_read_b128 v[132:135], v187
	ds_read_b128 v[136:139], v187 offset:1024
	ds_read_b128 v[140:143], v187 offset:2048
	ds_read_b128 v[144:147], v187 offset:3072
	ds_read_b128 v[148:151], v188
	ds_read_b128 v[152:155], v188 offset:1024
	ds_read_b128 v[172:175], v188 offset:2048
	ds_read_b128 v[176:179], v188 offset:3072
	s_add_u32 s0, s42, 0xfff00080
	s_addc_u32 s50, s43, -1
	s_cmp_eq_u32 s65, 60
	s_cselect_b32 s53, s25, s50
	s_cselect_b32 s52, s31, s0
	s_cselect_b32 s51, s23, s64
	s_cselect_b32 s50, s62, s63
	s_add_i32 m0, s41, 0xc000
	ds_read_b128 v[180:183], v189
	ds_read_b128 v[192:195], v189 offset:1024
	ds_read_b128 v[196:199], v189 offset:2048
	ds_read_b128 v[200:203], v189 offset:3072
	ds_read_b128 v[204:207], v189 offset:4096
	ds_read_b128 v[208:211], v189 offset:5120
	ds_read_b128 v[212:215], v189 offset:6144
	ds_read_b128 v[216:219], v189 offset:7168
	global_load_lds_dwordx4 v164, s[42:43]
	s_add_i32 m0, s41, 0xe000
	s_nop 0
	global_load_lds_dwordx4 v166, s[42:43]
	s_setprio 1
	s_waitcnt vmcnt(8) lgkmcnt(0)
	s_barrier
	v_mfma_f32_16x16x32_bf16 v[128:131], v[132:135], v[180:183], v[128:131]
	v_mfma_f32_16x16x32_bf16 v[128:131], v[136:139], v[192:195], v[128:131]
	v_mfma_f32_16x16x32_bf16 v[124:127], v[140:143], v[180:183], v[124:127]
	v_mfma_f32_16x16x32_bf16 v[124:127], v[144:147], v[192:195], v[124:127]
	v_mfma_f32_16x16x32_bf16 v[120:123], v[148:151], v[180:183], v[120:123]
	v_mfma_f32_16x16x32_bf16 v[120:123], v[152:155], v[192:195], v[120:123]
	v_mfma_f32_16x16x32_bf16 v[116:119], v[172:175], v[180:183], v[116:119]
	v_mfma_f32_16x16x32_bf16 v[116:119], v[176:179], v[192:195], v[116:119]
	v_mfma_f32_16x16x32_bf16 v[100:103], v[172:175], v[196:199], v[100:103]
	v_mfma_f32_16x16x32_bf16 v[100:103], v[176:179], v[200:203], v[100:103]
	v_mfma_f32_16x16x32_bf16 v[104:107], v[148:151], v[196:199], v[104:107]
	v_mfma_f32_16x16x32_bf16 v[104:107], v[152:155], v[200:203], v[104:107]
	v_mfma_f32_16x16x32_bf16 v[108:111], v[140:143], v[196:199], v[108:111]
	v_mfma_f32_16x16x32_bf16 v[108:111], v[144:147], v[200:203], v[108:111]
	v_mfma_f32_16x16x32_bf16 v[112:115], v[132:135], v[196:199], v[112:115]
	v_mfma_f32_16x16x32_bf16 v[112:115], v[136:139], v[200:203], v[112:115]
	v_mfma_f32_16x16x32_bf16 v[96:99], v[132:135], v[204:207], v[96:99]
	v_mfma_f32_16x16x32_bf16 v[96:99], v[136:139], v[208:211], v[96:99]
	v_mfma_f32_16x16x32_bf16 v[92:95], v[140:143], v[204:207], v[92:95]
	v_mfma_f32_16x16x32_bf16 v[92:95], v[144:147], v[208:211], v[92:95]
	v_mfma_f32_16x16x32_bf16 v[88:91], v[148:151], v[204:207], v[88:91]
	v_mfma_f32_16x16x32_bf16 v[88:91], v[152:155], v[208:211], v[88:91]
	v_mfma_f32_16x16x32_bf16 v[84:87], v[172:175], v[204:207], v[84:87]
	v_mfma_f32_16x16x32_bf16 v[84:87], v[176:179], v[208:211], v[84:87]
	v_mfma_f32_16x16x32_bf16 v[68:71], v[172:175], v[212:215], v[68:71]
	v_mfma_f32_16x16x32_bf16 v[68:71], v[176:179], v[216:219], v[68:71]
	v_mfma_f32_16x16x32_bf16 v[72:75], v[148:151], v[212:215], v[72:75]
	v_mfma_f32_16x16x32_bf16 v[72:75], v[152:155], v[216:219], v[72:75]
	v_mfma_f32_16x16x32_bf16 v[76:79], v[140:143], v[212:215], v[76:79]
	v_mfma_f32_16x16x32_bf16 v[76:79], v[144:147], v[216:219], v[76:79]
	v_mfma_f32_16x16x32_bf16 v[80:83], v[132:135], v[212:215], v[80:83]
	v_mfma_f32_16x16x32_bf16 v[80:83], v[136:139], v[216:219], v[80:83]
	s_setprio 0
	s_barrier
	s_add_i32 s0, s59, s46
	s_mov_b32 m0, s0
	ds_read_b128 v[180:183], v189 offset:16384
	ds_read_b128 v[192:195], v189 offset:17408
	ds_read_b128 v[196:199], v189 offset:18432
	ds_read_b128 v[200:203], v189 offset:19456
	ds_read_b128 v[204:207], v189 offset:20480
	ds_read_b128 v[208:211], v189 offset:21504
	ds_read_b128 v[212:215], v189 offset:22528
	ds_read_b128 v[216:219], v189 offset:23552
	global_load_lds_dwordx4 v158, s[50:51]
	s_add_i32 m0, s0, 0x2000
	s_add_u32 s66, s50, 0x100000
	s_addc_u32 s67, s51, 0
	s_add_i32 s0, s60, s46
	global_load_lds_dwordx4 v162, s[50:51]
	s_mov_b32 m0, s0
	s_nop 0
	global_load_lds_dwordx4 v158, s[66:67]
	s_add_i32 m0, s0, 0x2000
	s_nop 0
	global_load_lds_dwordx4 v162, s[66:67]
	s_mov_b32 m0, s41
	s_nop 0
	global_load_lds_dwordx4 v156, s[52:53]
	s_mov_b32 m0, s47
	s_nop 0
	global_load_lds_dwordx4 v160, s[52:53]
	s_setprio 1
	s_waitcnt vmcnt(8) lgkmcnt(0)
	s_barrier
	v_mfma_f32_16x16x32_bf16 v[64:67], v[132:135], v[180:183], v[64:67]
	v_mfma_f32_16x16x32_bf16 v[64:67], v[136:139], v[192:195], v[64:67]
	v_mfma_f32_16x16x32_bf16 v[60:63], v[140:143], v[180:183], v[60:63]
	v_mfma_f32_16x16x32_bf16 v[60:63], v[144:147], v[192:195], v[60:63]
	v_mfma_f32_16x16x32_bf16 v[56:59], v[148:151], v[180:183], v[56:59]
	v_mfma_f32_16x16x32_bf16 v[56:59], v[152:155], v[192:195], v[56:59]
	v_mfma_f32_16x16x32_bf16 v[52:55], v[172:175], v[180:183], v[52:55]
	v_mfma_f32_16x16x32_bf16 v[52:55], v[176:179], v[192:195], v[52:55]
	v_mfma_f32_16x16x32_bf16 v[36:39], v[172:175], v[196:199], v[36:39]
	v_mfma_f32_16x16x32_bf16 v[36:39], v[176:179], v[200:203], v[36:39]
	v_mfma_f32_16x16x32_bf16 v[40:43], v[148:151], v[196:199], v[40:43]
	v_mfma_f32_16x16x32_bf16 v[40:43], v[152:155], v[200:203], v[40:43]
	v_mfma_f32_16x16x32_bf16 v[44:47], v[140:143], v[196:199], v[44:47]
	v_mfma_f32_16x16x32_bf16 v[44:47], v[144:147], v[200:203], v[44:47]
	v_mfma_f32_16x16x32_bf16 v[48:51], v[132:135], v[196:199], v[48:51]
	v_mfma_f32_16x16x32_bf16 v[48:51], v[136:139], v[200:203], v[48:51]
	v_mfma_f32_16x16x32_bf16 v[32:35], v[132:135], v[204:207], v[32:35]
	v_mfma_f32_16x16x32_bf16 v[32:35], v[136:139], v[208:211], v[32:35]
	v_mfma_f32_16x16x32_bf16 v[28:31], v[140:143], v[204:207], v[28:31]
	v_mfma_f32_16x16x32_bf16 v[28:31], v[144:147], v[208:211], v[28:31]
	v_mfma_f32_16x16x32_bf16 v[24:27], v[148:151], v[204:207], v[24:27]
	v_mfma_f32_16x16x32_bf16 v[24:27], v[152:155], v[208:211], v[24:27]
	v_mfma_f32_16x16x32_bf16 v[20:23], v[172:175], v[204:207], v[20:23]
	v_mfma_f32_16x16x32_bf16 v[20:23], v[176:179], v[208:211], v[20:23]
	v_mfma_f32_16x16x32_bf16 v[4:7], v[172:175], v[212:215], v[4:7]
	v_mfma_f32_16x16x32_bf16 v[4:7], v[176:179], v[216:219], v[4:7]
	v_mfma_f32_16x16x32_bf16 v[8:11], v[148:151], v[212:215], v[8:11]
	v_mfma_f32_16x16x32_bf16 v[8:11], v[152:155], v[216:219], v[8:11]
	v_mfma_f32_16x16x32_bf16 v[12:15], v[140:143], v[212:215], v[12:15]
	v_mfma_f32_16x16x32_bf16 v[12:15], v[144:147], v[216:219], v[12:15]
	v_mfma_f32_16x16x32_bf16 v[16:19], v[132:135], v[212:215], v[16:19]
	v_mfma_f32_16x16x32_bf16 v[16:19], v[136:139], v[216:219], v[16:19]
	s_setprio 0
	s_barrier
	s_add_i32 s0, 0, 0x18000
	s_add_i32 s66, 0, 0x1c000
	v_add_u32_e32 v144, s0, v3
	v_add_u32_e32 v176, s66, v3
	ds_read_b128 v[132:135], v144
	ds_read_b128 v[136:139], v144 offset:1024
	ds_read_b128 v[140:143], v144 offset:2048
	ds_read_b128 v[144:147], v144 offset:3072
	ds_read_b128 v[148:151], v176
	ds_read_b128 v[152:155], v176 offset:1024
	ds_read_b128 v[172:175], v176 offset:2048
	ds_read_b128 v[176:179], v176 offset:3072
	s_add_u32 s98, s52, 0x100000
	s_addc_u32 s99, s53, 0
	s_mov_b32 m0, s48
	ds_read_b128 v[180:183], v189 offset:32768
	ds_read_b128 v[192:195], v189 offset:33792
	ds_read_b128 v[196:199], v189 offset:34816
	ds_read_b128 v[200:203], v189 offset:35840
	ds_read_b128 v[204:207], v189 offset:36864
	ds_read_b128 v[208:211], v189 offset:37888
	ds_read_b128 v[212:215], v189 offset:38912
	ds_read_b128 v[216:219], v189 offset:39936
	global_load_lds_dwordx4 v156, s[98:99]
	s_mov_b32 m0, s49
	s_nop 0
	global_load_lds_dwordx4 v160, s[98:99]
	s_setprio 1
	s_waitcnt vmcnt(8) lgkmcnt(0)
	s_barrier
	v_mfma_f32_16x16x32_bf16 v[128:131], v[132:135], v[180:183], v[128:131]
	v_mfma_f32_16x16x32_bf16 v[128:131], v[136:139], v[192:195], v[128:131]
	v_mfma_f32_16x16x32_bf16 v[124:127], v[140:143], v[180:183], v[124:127]
	v_mfma_f32_16x16x32_bf16 v[124:127], v[144:147], v[192:195], v[124:127]
	v_mfma_f32_16x16x32_bf16 v[120:123], v[148:151], v[180:183], v[120:123]
	v_mfma_f32_16x16x32_bf16 v[120:123], v[152:155], v[192:195], v[120:123]
	v_mfma_f32_16x16x32_bf16 v[116:119], v[172:175], v[180:183], v[116:119]
	v_mfma_f32_16x16x32_bf16 v[116:119], v[176:179], v[192:195], v[116:119]
	v_mfma_f32_16x16x32_bf16 v[100:103], v[172:175], v[196:199], v[100:103]
	v_mfma_f32_16x16x32_bf16 v[100:103], v[176:179], v[200:203], v[100:103]
	v_mfma_f32_16x16x32_bf16 v[104:107], v[148:151], v[196:199], v[104:107]
	v_mfma_f32_16x16x32_bf16 v[104:107], v[152:155], v[200:203], v[104:107]
	v_mfma_f32_16x16x32_bf16 v[108:111], v[140:143], v[196:199], v[108:111]
	v_mfma_f32_16x16x32_bf16 v[108:111], v[144:147], v[200:203], v[108:111]
	v_mfma_f32_16x16x32_bf16 v[112:115], v[132:135], v[196:199], v[112:115]
	v_mfma_f32_16x16x32_bf16 v[112:115], v[136:139], v[200:203], v[112:115]
	v_mfma_f32_16x16x32_bf16 v[96:99], v[132:135], v[204:207], v[96:99]
	v_mfma_f32_16x16x32_bf16 v[96:99], v[136:139], v[208:211], v[96:99]
	v_mfma_f32_16x16x32_bf16 v[92:95], v[140:143], v[204:207], v[92:95]
	v_mfma_f32_16x16x32_bf16 v[92:95], v[144:147], v[208:211], v[92:95]
	v_mfma_f32_16x16x32_bf16 v[88:91], v[148:151], v[204:207], v[88:91]
	v_mfma_f32_16x16x32_bf16 v[88:91], v[152:155], v[208:211], v[88:91]
	v_mfma_f32_16x16x32_bf16 v[84:87], v[172:175], v[204:207], v[84:87]
	v_mfma_f32_16x16x32_bf16 v[84:87], v[176:179], v[208:211], v[84:87]
	v_mfma_f32_16x16x32_bf16 v[68:71], v[172:175], v[212:215], v[68:71]
	v_mfma_f32_16x16x32_bf16 v[68:71], v[176:179], v[216:219], v[68:71]
	v_mfma_f32_16x16x32_bf16 v[72:75], v[148:151], v[212:215], v[72:75]
	v_mfma_f32_16x16x32_bf16 v[72:75], v[152:155], v[216:219], v[72:75]
	v_mfma_f32_16x16x32_bf16 v[76:79], v[140:143], v[212:215], v[76:79]
	v_mfma_f32_16x16x32_bf16 v[76:79], v[144:147], v[216:219], v[76:79]
	v_mfma_f32_16x16x32_bf16 v[80:83], v[132:135], v[212:215], v[80:83]
	v_mfma_f32_16x16x32_bf16 v[80:83], v[136:139], v[216:219], v[80:83]
	s_setprio 0
	s_barrier
	s_add_i32 s0, s0, s46
	s_add_i32 m0, s0, 0xffffff80
	ds_read_b128 v[180:183], v189 offset:49152
	ds_read_b128 v[192:195], v189 offset:50176
	ds_read_b128 v[196:199], v189 offset:51200
	ds_read_b128 v[200:203], v189 offset:52224
	ds_read_b128 v[204:207], v189 offset:53248
	ds_read_b128 v[208:211], v189 offset:54272
	ds_read_b128 v[212:215], v189 offset:55296
	ds_read_b128 v[216:219], v189 offset:56320
	global_load_lds_dwordx4 v158, s[50:51] offset:128
	s_add_i32 m0, s0, 0x1f80
	s_add_i32 s0, s66, s46
	global_load_lds_dwordx4 v162, s[50:51] offset:128
	s_add_u32 s50, s50, 0x100080
	s_addc_u32 s51, s51, 0
	s_mov_b32 m0, s0
	s_nop 0
	global_load_lds_dwordx4 v158, s[50:51]
	s_add_i32 m0, s0, 0x2000
	s_nop 0
	global_load_lds_dwordx4 v162, s[50:51]
	s_add_i32 m0, s57, 0xffffff80
	s_nop 0
	global_load_lds_dwordx4 v156, s[52:53] offset:128
	s_add_i32 m0, s58, 0xffffff80
	s_nop 0
	global_load_lds_dwordx4 v160, s[52:53] offset:128
	s_setprio 1
	s_waitcnt vmcnt(8) lgkmcnt(0)
	s_barrier
	v_mfma_f32_16x16x32_bf16 v[64:67], v[132:135], v[180:183], v[64:67]
	v_mfma_f32_16x16x32_bf16 v[64:67], v[136:139], v[192:195], v[64:67]
	v_mfma_f32_16x16x32_bf16 v[60:63], v[140:143], v[180:183], v[60:63]
	v_mfma_f32_16x16x32_bf16 v[60:63], v[144:147], v[192:195], v[60:63]
	v_mfma_f32_16x16x32_bf16 v[56:59], v[148:151], v[180:183], v[56:59]
	v_mfma_f32_16x16x32_bf16 v[56:59], v[152:155], v[192:195], v[56:59]
	v_mfma_f32_16x16x32_bf16 v[52:55], v[172:175], v[180:183], v[52:55]
	v_mfma_f32_16x16x32_bf16 v[52:55], v[176:179], v[192:195], v[52:55]
	v_mfma_f32_16x16x32_bf16 v[36:39], v[172:175], v[196:199], v[36:39]
	v_mfma_f32_16x16x32_bf16 v[36:39], v[176:179], v[200:203], v[36:39]
	v_mfma_f32_16x16x32_bf16 v[40:43], v[148:151], v[196:199], v[40:43]
	v_mfma_f32_16x16x32_bf16 v[40:43], v[152:155], v[200:203], v[40:43]
	v_mfma_f32_16x16x32_bf16 v[44:47], v[140:143], v[196:199], v[44:47]
	v_mfma_f32_16x16x32_bf16 v[44:47], v[144:147], v[200:203], v[44:47]
	v_mfma_f32_16x16x32_bf16 v[48:51], v[132:135], v[196:199], v[48:51]
	v_mfma_f32_16x16x32_bf16 v[48:51], v[136:139], v[200:203], v[48:51]
	v_mfma_f32_16x16x32_bf16 v[32:35], v[132:135], v[204:207], v[32:35]
	v_mfma_f32_16x16x32_bf16 v[32:35], v[136:139], v[208:211], v[32:35]
	v_mfma_f32_16x16x32_bf16 v[28:31], v[140:143], v[204:207], v[28:31]
	v_mfma_f32_16x16x32_bf16 v[28:31], v[144:147], v[208:211], v[28:31]
	v_mfma_f32_16x16x32_bf16 v[24:27], v[148:151], v[204:207], v[24:27]
	v_mfma_f32_16x16x32_bf16 v[24:27], v[152:155], v[208:211], v[24:27]
	v_mfma_f32_16x16x32_bf16 v[20:23], v[172:175], v[204:207], v[20:23]
	v_mfma_f32_16x16x32_bf16 v[20:23], v[176:179], v[208:211], v[20:23]
	v_mfma_f32_16x16x32_bf16 v[4:7], v[172:175], v[212:215], v[4:7]
	v_mfma_f32_16x16x32_bf16 v[4:7], v[176:179], v[216:219], v[4:7]
	v_mfma_f32_16x16x32_bf16 v[8:11], v[148:151], v[212:215], v[8:11]
	v_mfma_f32_16x16x32_bf16 v[8:11], v[152:155], v[216:219], v[8:11]
	v_mfma_f32_16x16x32_bf16 v[12:15], v[140:143], v[212:215], v[12:15]
	v_mfma_f32_16x16x32_bf16 v[12:15], v[144:147], v[216:219], v[12:15]
	v_mfma_f32_16x16x32_bf16 v[16:19], v[132:135], v[212:215], v[16:19]
	v_mfma_f32_16x16x32_bf16 v[16:19], v[136:139], v[216:219], v[16:19]
	s_setprio 0
	s_barrier
	s_add_i32 s65, s65, 2
	s_add_u32 s42, s42, 0x100
	s_addc_u32 s43, s43, 0
	s_add_u32 s63, s63, 0x100
	s_addc_u32 s64, s64, 0
	s_cmp_gt_u32 s65, 61
	s_cbranch_scc0 .LBB0_1203
	s_and_b64 vcc, exec, s[20:21]
	s_cbranch_vccz .LBB0_1206
	s_barrier

.LBB0_1288:
	ds_read_b128 v[154:157], v150
	ds_read_b128 v[158:161], v150 offset:1024
	ds_read_b128 v[162:165], v150 offset:2048
	ds_read_b128 v[166:169], v150 offset:3072
	ds_read_b128 v[170:173], v151
	ds_read_b128 v[174:177], v151 offset:1024
	ds_read_b128 v[178:181], v151 offset:2048
	ds_read_b128 v[182:185], v151 offset:3072
	s_add_u32 s0, s42, 0xfff00080
	s_addc_u32 s50, s43, -1
	s_cmp_eq_u32 s70, 12
	s_cselect_b32 s53, s29, s50
	s_cselect_b32 s52, s28, s0
	s_cselect_b32 s51, s5, s41
	s_cselect_b32 s50, s4, s31
	s_add_i32 m0, s17, 0xc000
	ds_read_b128 v[186:189], v152
	ds_read_b128 v[190:193], v152 offset:1024
	ds_read_b128 v[194:197], v152 offset:2048
	ds_read_b128 v[198:201], v152 offset:3072
	ds_read_b128 v[202:205], v152 offset:4096
	ds_read_b128 v[206:209], v152 offset:5120
	ds_read_b128 v[210:213], v152 offset:6144
	ds_read_b128 v[214:217], v152 offset:7168
	global_load_lds_dwordx4 v142, s[42:43]
	s_add_i32 m0, s17, 0xe000
	s_nop 0
	global_load_lds_dwordx4 v144, s[42:43]
	s_setprio 1
	s_waitcnt vmcnt(8) lgkmcnt(0)
	s_barrier
	v_mfma_f32_16x16x32_bf16 v[128:131], v[154:157], v[186:189], v[128:131]
	v_mfma_f32_16x16x32_bf16 v[128:131], v[158:161], v[190:193], v[128:131]
	v_mfma_f32_16x16x32_bf16 v[124:127], v[162:165], v[186:189], v[124:127]
	v_mfma_f32_16x16x32_bf16 v[124:127], v[166:169], v[190:193], v[124:127]
	v_mfma_f32_16x16x32_bf16 v[112:115], v[170:173], v[186:189], v[112:115]
	v_mfma_f32_16x16x32_bf16 v[112:115], v[174:177], v[190:193], v[112:115]
	v_mfma_f32_16x16x32_bf16 v[108:111], v[178:181], v[186:189], v[108:111]
	v_mfma_f32_16x16x32_bf16 v[108:111], v[182:185], v[190:193], v[108:111]
	v_mfma_f32_16x16x32_bf16 v[92:95], v[178:181], v[194:197], v[92:95]
	v_mfma_f32_16x16x32_bf16 v[92:95], v[182:185], v[198:201], v[92:95]
	v_mfma_f32_16x16x32_bf16 v[96:99], v[170:173], v[194:197], v[96:99]
	v_mfma_f32_16x16x32_bf16 v[96:99], v[174:177], v[198:201], v[96:99]
	v_mfma_f32_16x16x32_bf16 v[116:119], v[162:165], v[194:197], v[116:119]
	v_mfma_f32_16x16x32_bf16 v[116:119], v[166:169], v[198:201], v[116:119]
	v_mfma_f32_16x16x32_bf16 v[120:123], v[154:157], v[194:197], v[120:123]
	v_mfma_f32_16x16x32_bf16 v[120:123], v[158:161], v[198:201], v[120:123]
	v_mfma_f32_16x16x32_bf16 v[104:107], v[154:157], v[202:205], v[104:107]
	v_mfma_f32_16x16x32_bf16 v[104:107], v[158:161], v[206:209], v[104:107]
	v_mfma_f32_16x16x32_bf16 v[100:103], v[162:165], v[202:205], v[100:103]
	v_mfma_f32_16x16x32_bf16 v[100:103], v[166:169], v[206:209], v[100:103]
	v_mfma_f32_16x16x32_bf16 v[80:83], v[170:173], v[202:205], v[80:83]
	v_mfma_f32_16x16x32_bf16 v[80:83], v[174:177], v[206:209], v[80:83]
	v_mfma_f32_16x16x32_bf16 v[76:79], v[178:181], v[202:205], v[76:79]
	v_mfma_f32_16x16x32_bf16 v[76:79], v[182:185], v[206:209], v[76:79]
	v_mfma_f32_16x16x32_bf16 v[68:71], v[178:181], v[210:213], v[68:71]
	v_mfma_f32_16x16x32_bf16 v[68:71], v[182:185], v[214:217], v[68:71]
	v_mfma_f32_16x16x32_bf16 v[72:75], v[170:173], v[210:213], v[72:75]
	v_mfma_f32_16x16x32_bf16 v[72:75], v[174:177], v[214:217], v[72:75]
	v_mfma_f32_16x16x32_bf16 v[84:87], v[162:165], v[210:213], v[84:87]
	v_mfma_f32_16x16x32_bf16 v[84:87], v[166:169], v[214:217], v[84:87]
	v_mfma_f32_16x16x32_bf16 v[88:91], v[154:157], v[210:213], v[88:91]
	v_mfma_f32_16x16x32_bf16 v[88:91], v[158:161], v[214:217], v[88:91]
	s_setprio 0
	s_barrier
	s_add_i32 s0, s60, s46
	s_mov_b32 m0, s0
	ds_read_b128 v[186:189], v152 offset:16384
	ds_read_b128 v[190:193], v152 offset:17408
	ds_read_b128 v[194:197], v152 offset:18432
	ds_read_b128 v[198:201], v152 offset:19456
	ds_read_b128 v[202:205], v152 offset:20480
	ds_read_b128 v[206:209], v152 offset:21504
	ds_read_b128 v[210:213], v152 offset:22528
	ds_read_b128 v[214:217], v152 offset:23552
	global_load_lds_dwordx4 v136, s[50:51]
	s_add_i32 m0, s0, 0x2000
	s_add_u32 s72, s50, 0x100000
	s_addc_u32 s73, s51, 0
	s_add_i32 s0, s61, s46
	global_load_lds_dwordx4 v132, s[50:51]
	s_mov_b32 m0, s0
	s_nop 0
	global_load_lds_dwordx4 v136, s[72:73]
	s_add_i32 m0, s0, 0x2000
	s_nop 0
	global_load_lds_dwordx4 v132, s[72:73]
	s_mov_b32 m0, s17
	s_nop 0
	global_load_lds_dwordx4 v138, s[52:53]
	s_mov_b32 m0, s47
	s_nop 0
	global_load_lds_dwordx4 v134, s[52:53]
	s_setprio 1
	s_waitcnt vmcnt(8) lgkmcnt(0)
	s_barrier
	v_mfma_f32_16x16x32_bf16 v[64:67], v[154:157], v[186:189], v[64:67]
	v_mfma_f32_16x16x32_bf16 v[64:67], v[158:161], v[190:193], v[64:67]
	v_mfma_f32_16x16x32_bf16 v[60:63], v[162:165], v[186:189], v[60:63]
	v_mfma_f32_16x16x32_bf16 v[60:63], v[166:169], v[190:193], v[60:63]
	v_mfma_f32_16x16x32_bf16 v[48:51], v[170:173], v[186:189], v[48:51]
	v_mfma_f32_16x16x32_bf16 v[48:51], v[174:177], v[190:193], v[48:51]
	v_mfma_f32_16x16x32_bf16 v[44:47], v[178:181], v[186:189], v[44:47]
	v_mfma_f32_16x16x32_bf16 v[44:47], v[182:185], v[190:193], v[44:47]
	v_mfma_f32_16x16x32_bf16 v[28:31], v[178:181], v[194:197], v[28:31]
	v_mfma_f32_16x16x32_bf16 v[28:31], v[182:185], v[198:201], v[28:31]
	v_mfma_f32_16x16x32_bf16 v[32:35], v[170:173], v[194:197], v[32:35]
	v_mfma_f32_16x16x32_bf16 v[32:35], v[174:177], v[198:201], v[32:35]
	v_mfma_f32_16x16x32_bf16 v[52:55], v[162:165], v[194:197], v[52:55]
	v_mfma_f32_16x16x32_bf16 v[52:55], v[166:169], v[198:201], v[52:55]
	v_mfma_f32_16x16x32_bf16 v[56:59], v[154:157], v[194:197], v[56:59]
	v_mfma_f32_16x16x32_bf16 v[56:59], v[158:161], v[198:201], v[56:59]
	v_mfma_f32_16x16x32_bf16 v[40:43], v[154:157], v[202:205], v[40:43]
	v_mfma_f32_16x16x32_bf16 v[40:43], v[158:161], v[206:209], v[40:43]
	v_mfma_f32_16x16x32_bf16 v[36:39], v[162:165], v[202:205], v[36:39]
	v_mfma_f32_16x16x32_bf16 v[36:39], v[166:169], v[206:209], v[36:39]
	v_mfma_f32_16x16x32_bf16 v[16:19], v[170:173], v[202:205], v[16:19]
	v_mfma_f32_16x16x32_bf16 v[16:19], v[174:177], v[206:209], v[16:19]
	v_mfma_f32_16x16x32_bf16 v[12:15], v[178:181], v[202:205], v[12:15]
	v_mfma_f32_16x16x32_bf16 v[12:15], v[182:185], v[206:209], v[12:15]
	v_mfma_f32_16x16x32_bf16 v[4:7], v[178:181], v[210:213], v[4:7]
	v_mfma_f32_16x16x32_bf16 v[4:7], v[182:185], v[214:217], v[4:7]
	v_mfma_f32_16x16x32_bf16 v[8:11], v[170:173], v[210:213], v[8:11]
	v_mfma_f32_16x16x32_bf16 v[8:11], v[174:177], v[214:217], v[8:11]
	v_mfma_f32_16x16x32_bf16 v[20:23], v[162:165], v[210:213], v[20:23]
	v_mfma_f32_16x16x32_bf16 v[20:23], v[166:169], v[214:217], v[20:23]
	v_mfma_f32_16x16x32_bf16 v[24:27], v[154:157], v[210:213], v[24:27]
	v_mfma_f32_16x16x32_bf16 v[24:27], v[158:161], v[214:217], v[24:27]
	s_setprio 0
	s_barrier
	s_add_i32 s0, 0, 0x18000
	v_add_u32_e32 v140, s0, v3
	s_add_i32 s71, 0, 0x1c000
	ds_read_b128 v[154:157], v140
	ds_read_b128 v[158:161], v140 offset:1024
	ds_read_b128 v[162:165], v140 offset:2048
	ds_read_b128 v[166:169], v140 offset:3072
	v_add_u32_e32 v140, s71, v3
	ds_read_b128 v[170:173], v140
	ds_read_b128 v[174:177], v140 offset:1024
	ds_read_b128 v[178:181], v140 offset:2048
	ds_read_b128 v[182:185], v140 offset:3072
	s_add_u32 s98, s52, 0x100000
	s_addc_u32 s99, s53, 0
	s_mov_b32 m0, s48
	ds_read_b128 v[186:189], v152 offset:32768
	ds_read_b128 v[190:193], v152 offset:33792
	ds_read_b128 v[194:197], v152 offset:34816
	ds_read_b128 v[198:201], v152 offset:35840
	ds_read_b128 v[202:205], v152 offset:36864
	ds_read_b128 v[206:209], v152 offset:37888
	ds_read_b128 v[210:213], v152 offset:38912
	ds_read_b128 v[214:217], v152 offset:39936
	global_load_lds_dwordx4 v138, s[98:99]
	s_mov_b32 m0, s49
	s_nop 0
	global_load_lds_dwordx4 v134, s[98:99]
	s_setprio 1
	s_waitcnt vmcnt(8) lgkmcnt(0)
	s_barrier
	v_mfma_f32_16x16x32_bf16 v[128:131], v[154:157], v[186:189], v[128:131]
	v_mfma_f32_16x16x32_bf16 v[128:131], v[158:161], v[190:193], v[128:131]
	v_mfma_f32_16x16x32_bf16 v[124:127], v[162:165], v[186:189], v[124:127]
	v_mfma_f32_16x16x32_bf16 v[124:127], v[166:169], v[190:193], v[124:127]
	v_mfma_f32_16x16x32_bf16 v[112:115], v[170:173], v[186:189], v[112:115]
	v_mfma_f32_16x16x32_bf16 v[112:115], v[174:177], v[190:193], v[112:115]
	v_mfma_f32_16x16x32_bf16 v[108:111], v[178:181], v[186:189], v[108:111]
	v_mfma_f32_16x16x32_bf16 v[108:111], v[182:185], v[190:193], v[108:111]
	v_mfma_f32_16x16x32_bf16 v[92:95], v[178:181], v[194:197], v[92:95]
	v_mfma_f32_16x16x32_bf16 v[92:95], v[182:185], v[198:201], v[92:95]
	v_mfma_f32_16x16x32_bf16 v[96:99], v[170:173], v[194:197], v[96:99]
	v_mfma_f32_16x16x32_bf16 v[96:99], v[174:177], v[198:201], v[96:99]
	v_mfma_f32_16x16x32_bf16 v[116:119], v[162:165], v[194:197], v[116:119]
	v_mfma_f32_16x16x32_bf16 v[116:119], v[166:169], v[198:201], v[116:119]
	v_mfma_f32_16x16x32_bf16 v[120:123], v[154:157], v[194:197], v[120:123]
	v_mfma_f32_16x16x32_bf16 v[120:123], v[158:161], v[198:201], v[120:123]
	v_mfma_f32_16x16x32_bf16 v[104:107], v[154:157], v[202:205], v[104:107]
	v_mfma_f32_16x16x32_bf16 v[104:107], v[158:161], v[206:209], v[104:107]
	v_mfma_f32_16x16x32_bf16 v[100:103], v[162:165], v[202:205], v[100:103]
	v_mfma_f32_16x16x32_bf16 v[100:103], v[166:169], v[206:209], v[100:103]
	v_mfma_f32_16x16x32_bf16 v[80:83], v[170:173], v[202:205], v[80:83]
	v_mfma_f32_16x16x32_bf16 v[80:83], v[174:177], v[206:209], v[80:83]
	v_mfma_f32_16x16x32_bf16 v[76:79], v[178:181], v[202:205], v[76:79]
	v_mfma_f32_16x16x32_bf16 v[76:79], v[182:185], v[206:209], v[76:79]
	v_mfma_f32_16x16x32_bf16 v[68:71], v[178:181], v[210:213], v[68:71]
	v_mfma_f32_16x16x32_bf16 v[68:71], v[182:185], v[214:217], v[68:71]
	v_mfma_f32_16x16x32_bf16 v[72:75], v[170:173], v[210:213], v[72:75]
	v_mfma_f32_16x16x32_bf16 v[72:75], v[174:177], v[214:217], v[72:75]
	v_mfma_f32_16x16x32_bf16 v[84:87], v[162:165], v[210:213], v[84:87]
	v_mfma_f32_16x16x32_bf16 v[84:87], v[166:169], v[214:217], v[84:87]
	v_mfma_f32_16x16x32_bf16 v[88:91], v[154:157], v[210:213], v[88:91]
	v_mfma_f32_16x16x32_bf16 v[88:91], v[158:161], v[214:217], v[88:91]
	s_setprio 0
	s_barrier
	s_add_i32 s0, s0, s46
	s_add_i32 m0, s0, 0xffffff80
	ds_read_b128 v[186:189], v152 offset:49152
	ds_read_b128 v[190:193], v152 offset:50176
	ds_read_b128 v[194:197], v152 offset:51200
	ds_read_b128 v[198:201], v152 offset:52224
	ds_read_b128 v[202:205], v152 offset:53248
	ds_read_b128 v[206:209], v152 offset:54272
	ds_read_b128 v[210:213], v152 offset:55296
	ds_read_b128 v[214:217], v152 offset:56320
	global_load_lds_dwordx4 v136, s[50:51] offset:128
	s_add_i32 m0, s0, 0x1f80
	s_add_i32 s0, s71, s46
	global_load_lds_dwordx4 v132, s[50:51] offset:128
	s_add_u32 s50, s50, 0x100080
	s_addc_u32 s51, s51, 0
	s_mov_b32 m0, s0
	s_nop 0
	global_load_lds_dwordx4 v136, s[50:51]
	s_add_i32 m0, s0, 0x2000
	s_nop 0
	global_load_lds_dwordx4 v132, s[50:51]
	s_add_i32 m0, s58, 0xffffff80
	s_nop 0
	global_load_lds_dwordx4 v138, s[52:53] offset:128
	s_add_i32 m0, s59, 0xffffff80
	s_nop 0
	global_load_lds_dwordx4 v134, s[52:53] offset:128
	s_setprio 1
	s_waitcnt vmcnt(8) lgkmcnt(0)
	s_barrier
	v_mfma_f32_16x16x32_bf16 v[64:67], v[154:157], v[186:189], v[64:67]
	v_mfma_f32_16x16x32_bf16 v[64:67], v[158:161], v[190:193], v[64:67]
	v_mfma_f32_16x16x32_bf16 v[60:63], v[162:165], v[186:189], v[60:63]
	v_mfma_f32_16x16x32_bf16 v[60:63], v[166:169], v[190:193], v[60:63]
	v_mfma_f32_16x16x32_bf16 v[48:51], v[170:173], v[186:189], v[48:51]
	v_mfma_f32_16x16x32_bf16 v[48:51], v[174:177], v[190:193], v[48:51]
	v_mfma_f32_16x16x32_bf16 v[44:47], v[178:181], v[186:189], v[44:47]
	v_mfma_f32_16x16x32_bf16 v[44:47], v[182:185], v[190:193], v[44:47]
	v_mfma_f32_16x16x32_bf16 v[28:31], v[178:181], v[194:197], v[28:31]
	v_mfma_f32_16x16x32_bf16 v[28:31], v[182:185], v[198:201], v[28:31]
	v_mfma_f32_16x16x32_bf16 v[32:35], v[170:173], v[194:197], v[32:35]
	v_mfma_f32_16x16x32_bf16 v[32:35], v[174:177], v[198:201], v[32:35]
	v_mfma_f32_16x16x32_bf16 v[52:55], v[162:165], v[194:197], v[52:55]
	v_mfma_f32_16x16x32_bf16 v[52:55], v[166:169], v[198:201], v[52:55]
	v_mfma_f32_16x16x32_bf16 v[56:59], v[154:157], v[194:197], v[56:59]
	v_mfma_f32_16x16x32_bf16 v[56:59], v[158:161], v[198:201], v[56:59]
	v_mfma_f32_16x16x32_bf16 v[40:43], v[154:157], v[202:205], v[40:43]
	v_mfma_f32_16x16x32_bf16 v[40:43], v[158:161], v[206:209], v[40:43]
	v_mfma_f32_16x16x32_bf16 v[36:39], v[162:165], v[202:205], v[36:39]
	v_mfma_f32_16x16x32_bf16 v[36:39], v[166:169], v[206:209], v[36:39]
	v_mfma_f32_16x16x32_bf16 v[16:19], v[170:173], v[202:205], v[16:19]
	v_mfma_f32_16x16x32_bf16 v[16:19], v[174:177], v[206:209], v[16:19]
	v_mfma_f32_16x16x32_bf16 v[12:15], v[178:181], v[202:205], v[12:15]
	v_mfma_f32_16x16x32_bf16 v[12:15], v[182:185], v[206:209], v[12:15]
	v_mfma_f32_16x16x32_bf16 v[4:7], v[178:181], v[210:213], v[4:7]
	v_mfma_f32_16x16x32_bf16 v[4:7], v[182:185], v[214:217], v[4:7]
	v_mfma_f32_16x16x32_bf16 v[8:11], v[170:173], v[210:213], v[8:11]
	v_mfma_f32_16x16x32_bf16 v[8:11], v[174:177], v[214:217], v[8:11]
	v_mfma_f32_16x16x32_bf16 v[20:23], v[162:165], v[210:213], v[20:23]
	v_mfma_f32_16x16x32_bf16 v[20:23], v[166:169], v[214:217], v[20:23]
	v_mfma_f32_16x16x32_bf16 v[24:27], v[154:157], v[210:213], v[24:27]
	v_mfma_f32_16x16x32_bf16 v[24:27], v[158:161], v[214:217], v[24:27]
	s_setprio 0
	s_barrier
	s_add_i32 s70, s70, 2
	s_add_u32 s42, s42, 0x100
	s_addc_u32 s43, s43, 0
	s_add_u32 s31, s31, 0x100
	s_addc_u32 s41, s41, 0
	s_cmp_gt_u32 s70, 13
	s_cbranch_scc0 .LBB0_1288
	s_and_b64 vcc, exec, s[14:15]
	s_cbranch_vccz .LBB0_1291
	s_barrier

.LBB0_1415:
	ds_read_b128 v[132:135], v187
	ds_read_b128 v[136:139], v187 offset:1024
	ds_read_b128 v[140:143], v187 offset:2048
	ds_read_b128 v[144:147], v187 offset:3072
	ds_read_b128 v[148:151], v188
	ds_read_b128 v[152:155], v188 offset:1024
	ds_read_b128 v[172:175], v188 offset:2048
	ds_read_b128 v[176:179], v188 offset:3072
	s_add_u32 s0, s42, 0xfffe0080
	s_addc_u32 s50, s43, -1
	s_cmp_eq_u32 s64, 4
	s_cselect_b32 s53, s25, s50
	s_cselect_b32 s52, s31, s0
	s_cselect_b32 s51, s23, s63
	s_cselect_b32 s50, s61, s62
	s_add_i32 m0, s41, 0xc000
	ds_read_b128 v[180:183], v189
	ds_read_b128 v[192:195], v189 offset:1024
	ds_read_b128 v[196:199], v189 offset:2048
	ds_read_b128 v[200:203], v189 offset:3072
	ds_read_b128 v[204:207], v189 offset:4096
	ds_read_b128 v[208:211], v189 offset:5120
	ds_read_b128 v[212:215], v189 offset:6144
	ds_read_b128 v[216:219], v189 offset:7168
	global_load_lds_dwordx4 v164, s[42:43]
	s_add_i32 m0, s41, 0xe000
	s_nop 0
	global_load_lds_dwordx4 v166, s[42:43]
	s_setprio 1
	s_waitcnt vmcnt(8) lgkmcnt(0)
	s_barrier
	v_mfma_f32_16x16x32_bf16 v[128:131], v[132:135], v[180:183], v[128:131]
	v_mfma_f32_16x16x32_bf16 v[128:131], v[136:139], v[192:195], v[128:131]
	v_mfma_f32_16x16x32_bf16 v[124:127], v[140:143], v[180:183], v[124:127]
	v_mfma_f32_16x16x32_bf16 v[124:127], v[144:147], v[192:195], v[124:127]
	v_mfma_f32_16x16x32_bf16 v[120:123], v[148:151], v[180:183], v[120:123]
	v_mfma_f32_16x16x32_bf16 v[120:123], v[152:155], v[192:195], v[120:123]
	v_mfma_f32_16x16x32_bf16 v[116:119], v[172:175], v[180:183], v[116:119]
	v_mfma_f32_16x16x32_bf16 v[116:119], v[176:179], v[192:195], v[116:119]
	v_mfma_f32_16x16x32_bf16 v[100:103], v[172:175], v[196:199], v[100:103]
	v_mfma_f32_16x16x32_bf16 v[100:103], v[176:179], v[200:203], v[100:103]
	v_mfma_f32_16x16x32_bf16 v[104:107], v[148:151], v[196:199], v[104:107]
	v_mfma_f32_16x16x32_bf16 v[104:107], v[152:155], v[200:203], v[104:107]
	v_mfma_f32_16x16x32_bf16 v[108:111], v[140:143], v[196:199], v[108:111]
	v_mfma_f32_16x16x32_bf16 v[108:111], v[144:147], v[200:203], v[108:111]
	v_mfma_f32_16x16x32_bf16 v[112:115], v[132:135], v[196:199], v[112:115]
	v_mfma_f32_16x16x32_bf16 v[112:115], v[136:139], v[200:203], v[112:115]
	v_mfma_f32_16x16x32_bf16 v[96:99], v[132:135], v[204:207], v[96:99]
	v_mfma_f32_16x16x32_bf16 v[96:99], v[136:139], v[208:211], v[96:99]
	v_mfma_f32_16x16x32_bf16 v[92:95], v[140:143], v[204:207], v[92:95]
	v_mfma_f32_16x16x32_bf16 v[92:95], v[144:147], v[208:211], v[92:95]
	v_mfma_f32_16x16x32_bf16 v[88:91], v[148:151], v[204:207], v[88:91]
	v_mfma_f32_16x16x32_bf16 v[88:91], v[152:155], v[208:211], v[88:91]
	v_mfma_f32_16x16x32_bf16 v[84:87], v[172:175], v[204:207], v[84:87]
	v_mfma_f32_16x16x32_bf16 v[84:87], v[176:179], v[208:211], v[84:87]
	v_mfma_f32_16x16x32_bf16 v[68:71], v[172:175], v[212:215], v[68:71]
	v_mfma_f32_16x16x32_bf16 v[68:71], v[176:179], v[216:219], v[68:71]
	v_mfma_f32_16x16x32_bf16 v[72:75], v[148:151], v[212:215], v[72:75]
	v_mfma_f32_16x16x32_bf16 v[72:75], v[152:155], v[216:219], v[72:75]
	v_mfma_f32_16x16x32_bf16 v[76:79], v[140:143], v[212:215], v[76:79]
	v_mfma_f32_16x16x32_bf16 v[76:79], v[144:147], v[216:219], v[76:79]
	v_mfma_f32_16x16x32_bf16 v[80:83], v[132:135], v[212:215], v[80:83]
	v_mfma_f32_16x16x32_bf16 v[80:83], v[136:139], v[216:219], v[80:83]
	s_setprio 0
	s_barrier
	s_add_i32 s0, s58, s45
	s_mov_b32 m0, s0
	ds_read_b128 v[180:183], v189 offset:16384
	ds_read_b128 v[192:195], v189 offset:17408
	ds_read_b128 v[196:199], v189 offset:18432
	ds_read_b128 v[200:203], v189 offset:19456
	ds_read_b128 v[204:207], v189 offset:20480
	ds_read_b128 v[208:211], v189 offset:21504
	ds_read_b128 v[212:215], v189 offset:22528
	ds_read_b128 v[216:219], v189 offset:23552
	global_load_lds_dwordx4 v158, s[50:51]
	s_add_i32 m0, s0, 0x2000
	s_add_u32 s66, s50, 0x20000
	s_addc_u32 s67, s51, 0
	s_add_i32 s0, s59, s45
	global_load_lds_dwordx4 v162, s[50:51]
	s_mov_b32 m0, s0
	s_nop 0
	global_load_lds_dwordx4 v158, s[66:67]
	s_add_i32 m0, s0, 0x2000
	s_nop 0
	global_load_lds_dwordx4 v162, s[66:67]
	s_mov_b32 m0, s41
	s_nop 0
	global_load_lds_dwordx4 v156, s[52:53]
	s_mov_b32 m0, s46
	s_nop 0
	global_load_lds_dwordx4 v160, s[52:53]
	s_setprio 1
	s_waitcnt vmcnt(8) lgkmcnt(0)
	s_barrier
	v_mfma_f32_16x16x32_bf16 v[64:67], v[132:135], v[180:183], v[64:67]
	v_mfma_f32_16x16x32_bf16 v[64:67], v[136:139], v[192:195], v[64:67]
	v_mfma_f32_16x16x32_bf16 v[60:63], v[140:143], v[180:183], v[60:63]
	v_mfma_f32_16x16x32_bf16 v[60:63], v[144:147], v[192:195], v[60:63]
	v_mfma_f32_16x16x32_bf16 v[56:59], v[148:151], v[180:183], v[56:59]
	v_mfma_f32_16x16x32_bf16 v[56:59], v[152:155], v[192:195], v[56:59]
	v_mfma_f32_16x16x32_bf16 v[52:55], v[172:175], v[180:183], v[52:55]
	v_mfma_f32_16x16x32_bf16 v[52:55], v[176:179], v[192:195], v[52:55]
	v_mfma_f32_16x16x32_bf16 v[36:39], v[172:175], v[196:199], v[36:39]
	v_mfma_f32_16x16x32_bf16 v[36:39], v[176:179], v[200:203], v[36:39]
	v_mfma_f32_16x16x32_bf16 v[40:43], v[148:151], v[196:199], v[40:43]
	v_mfma_f32_16x16x32_bf16 v[40:43], v[152:155], v[200:203], v[40:43]
	v_mfma_f32_16x16x32_bf16 v[44:47], v[140:143], v[196:199], v[44:47]
	v_mfma_f32_16x16x32_bf16 v[44:47], v[144:147], v[200:203], v[44:47]
	v_mfma_f32_16x16x32_bf16 v[48:51], v[132:135], v[196:199], v[48:51]
	v_mfma_f32_16x16x32_bf16 v[48:51], v[136:139], v[200:203], v[48:51]
	v_mfma_f32_16x16x32_bf16 v[32:35], v[132:135], v[204:207], v[32:35]
	v_mfma_f32_16x16x32_bf16 v[32:35], v[136:139], v[208:211], v[32:35]
	v_mfma_f32_16x16x32_bf16 v[28:31], v[140:143], v[204:207], v[28:31]
	v_mfma_f32_16x16x32_bf16 v[28:31], v[144:147], v[208:211], v[28:31]
	v_mfma_f32_16x16x32_bf16 v[24:27], v[148:151], v[204:207], v[24:27]
	v_mfma_f32_16x16x32_bf16 v[24:27], v[152:155], v[208:211], v[24:27]
	v_mfma_f32_16x16x32_bf16 v[20:23], v[172:175], v[204:207], v[20:23]
	v_mfma_f32_16x16x32_bf16 v[20:23], v[176:179], v[208:211], v[20:23]
	v_mfma_f32_16x16x32_bf16 v[4:7], v[172:175], v[212:215], v[4:7]
	v_mfma_f32_16x16x32_bf16 v[4:7], v[176:179], v[216:219], v[4:7]
	v_mfma_f32_16x16x32_bf16 v[8:11], v[148:151], v[212:215], v[8:11]
	v_mfma_f32_16x16x32_bf16 v[8:11], v[152:155], v[216:219], v[8:11]
	v_mfma_f32_16x16x32_bf16 v[12:15], v[140:143], v[212:215], v[12:15]
	v_mfma_f32_16x16x32_bf16 v[12:15], v[144:147], v[216:219], v[12:15]
	v_mfma_f32_16x16x32_bf16 v[16:19], v[132:135], v[212:215], v[16:19]
	v_mfma_f32_16x16x32_bf16 v[16:19], v[136:139], v[216:219], v[16:19]
	s_setprio 0
	s_barrier
	s_add_i32 s0, 0, 0x18000
	s_add_i32 s65, 0, 0x1c000
	v_add_u32_e32 v144, s0, v3
	v_add_u32_e32 v176, s65, v3
	ds_read_b128 v[132:135], v144
	ds_read_b128 v[136:139], v144 offset:1024
	ds_read_b128 v[140:143], v144 offset:2048
	ds_read_b128 v[144:147], v144 offset:3072
	ds_read_b128 v[148:151], v176
	ds_read_b128 v[152:155], v176 offset:1024
	ds_read_b128 v[172:175], v176 offset:2048
	ds_read_b128 v[176:179], v176 offset:3072
	s_add_u32 s98, s52, 0x20000
	s_addc_u32 s99, s53, 0
	s_mov_b32 m0, s47
	ds_read_b128 v[180:183], v189 offset:32768
	ds_read_b128 v[192:195], v189 offset:33792
	ds_read_b128 v[196:199], v189 offset:34816
	ds_read_b128 v[200:203], v189 offset:35840
	ds_read_b128 v[204:207], v189 offset:36864
	ds_read_b128 v[208:211], v189 offset:37888
	ds_read_b128 v[212:215], v189 offset:38912
	ds_read_b128 v[216:219], v189 offset:39936
	global_load_lds_dwordx4 v156, s[98:99]
	s_mov_b32 m0, s48
	s_nop 0
	global_load_lds_dwordx4 v160, s[98:99]
	s_setprio 1
	s_waitcnt vmcnt(8) lgkmcnt(0)
	s_barrier
	v_mfma_f32_16x16x32_bf16 v[128:131], v[132:135], v[180:183], v[128:131]
	v_mfma_f32_16x16x32_bf16 v[128:131], v[136:139], v[192:195], v[128:131]
	v_mfma_f32_16x16x32_bf16 v[124:127], v[140:143], v[180:183], v[124:127]
	v_mfma_f32_16x16x32_bf16 v[124:127], v[144:147], v[192:195], v[124:127]
	v_mfma_f32_16x16x32_bf16 v[120:123], v[148:151], v[180:183], v[120:123]
	v_mfma_f32_16x16x32_bf16 v[120:123], v[152:155], v[192:195], v[120:123]
	v_mfma_f32_16x16x32_bf16 v[116:119], v[172:175], v[180:183], v[116:119]
	v_mfma_f32_16x16x32_bf16 v[116:119], v[176:179], v[192:195], v[116:119]
	v_mfma_f32_16x16x32_bf16 v[100:103], v[172:175], v[196:199], v[100:103]
	v_mfma_f32_16x16x32_bf16 v[100:103], v[176:179], v[200:203], v[100:103]
	v_mfma_f32_16x16x32_bf16 v[104:107], v[148:151], v[196:199], v[104:107]
	v_mfma_f32_16x16x32_bf16 v[104:107], v[152:155], v[200:203], v[104:107]
	v_mfma_f32_16x16x32_bf16 v[108:111], v[140:143], v[196:199], v[108:111]
	v_mfma_f32_16x16x32_bf16 v[108:111], v[144:147], v[200:203], v[108:111]
	v_mfma_f32_16x16x32_bf16 v[112:115], v[132:135], v[196:199], v[112:115]
	v_mfma_f32_16x16x32_bf16 v[112:115], v[136:139], v[200:203], v[112:115]
	v_mfma_f32_16x16x32_bf16 v[96:99], v[132:135], v[204:207], v[96:99]
	v_mfma_f32_16x16x32_bf16 v[96:99], v[136:139], v[208:211], v[96:99]
	v_mfma_f32_16x16x32_bf16 v[92:95], v[140:143], v[204:207], v[92:95]
	v_mfma_f32_16x16x32_bf16 v[92:95], v[144:147], v[208:211], v[92:95]
	v_mfma_f32_16x16x32_bf16 v[88:91], v[148:151], v[204:207], v[88:91]
	v_mfma_f32_16x16x32_bf16 v[88:91], v[152:155], v[208:211], v[88:91]
	v_mfma_f32_16x16x32_bf16 v[84:87], v[172:175], v[204:207], v[84:87]
	v_mfma_f32_16x16x32_bf16 v[84:87], v[176:179], v[208:211], v[84:87]
	v_mfma_f32_16x16x32_bf16 v[68:71], v[172:175], v[212:215], v[68:71]
	v_mfma_f32_16x16x32_bf16 v[68:71], v[176:179], v[216:219], v[68:71]
	v_mfma_f32_16x16x32_bf16 v[72:75], v[148:151], v[212:215], v[72:75]
	v_mfma_f32_16x16x32_bf16 v[72:75], v[152:155], v[216:219], v[72:75]
	v_mfma_f32_16x16x32_bf16 v[76:79], v[140:143], v[212:215], v[76:79]
	v_mfma_f32_16x16x32_bf16 v[76:79], v[144:147], v[216:219], v[76:79]
	v_mfma_f32_16x16x32_bf16 v[80:83], v[132:135], v[212:215], v[80:83]
	v_mfma_f32_16x16x32_bf16 v[80:83], v[136:139], v[216:219], v[80:83]
	s_setprio 0
	s_barrier
	s_add_i32 s0, s0, s45
	s_add_i32 m0, s0, 0xffffff80
	ds_read_b128 v[180:183], v189 offset:49152
	ds_read_b128 v[192:195], v189 offset:50176
	ds_read_b128 v[196:199], v189 offset:51200
	ds_read_b128 v[200:203], v189 offset:52224
	ds_read_b128 v[204:207], v189 offset:53248
	ds_read_b128 v[208:211], v189 offset:54272
	ds_read_b128 v[212:215], v189 offset:55296
	ds_read_b128 v[216:219], v189 offset:56320
	global_load_lds_dwordx4 v158, s[50:51] offset:128
	s_add_i32 m0, s0, 0x1f80
	s_add_i32 s0, s65, s45
	global_load_lds_dwordx4 v162, s[50:51] offset:128
	s_add_u32 s50, s50, 0x20080
	s_addc_u32 s51, s51, 0
	s_mov_b32 m0, s0
	s_nop 0
	global_load_lds_dwordx4 v158, s[50:51]
	s_add_i32 m0, s0, 0x2000
	s_nop 0
	global_load_lds_dwordx4 v162, s[50:51]
	s_add_i32 m0, s56, 0xffffff80
	s_nop 0
	global_load_lds_dwordx4 v156, s[52:53] offset:128
	s_add_i32 m0, s57, 0xffffff80
	s_nop 0
	global_load_lds_dwordx4 v160, s[52:53] offset:128
	s_setprio 1
	s_waitcnt vmcnt(8) lgkmcnt(0)
	s_barrier
	v_mfma_f32_16x16x32_bf16 v[64:67], v[132:135], v[180:183], v[64:67]
	v_mfma_f32_16x16x32_bf16 v[64:67], v[136:139], v[192:195], v[64:67]
	v_mfma_f32_16x16x32_bf16 v[60:63], v[140:143], v[180:183], v[60:63]
	v_mfma_f32_16x16x32_bf16 v[60:63], v[144:147], v[192:195], v[60:63]
	v_mfma_f32_16x16x32_bf16 v[56:59], v[148:151], v[180:183], v[56:59]
	v_mfma_f32_16x16x32_bf16 v[56:59], v[152:155], v[192:195], v[56:59]
	v_mfma_f32_16x16x32_bf16 v[52:55], v[172:175], v[180:183], v[52:55]
	v_mfma_f32_16x16x32_bf16 v[52:55], v[176:179], v[192:195], v[52:55]
	v_mfma_f32_16x16x32_bf16 v[36:39], v[172:175], v[196:199], v[36:39]
	v_mfma_f32_16x16x32_bf16 v[36:39], v[176:179], v[200:203], v[36:39]
	v_mfma_f32_16x16x32_bf16 v[40:43], v[148:151], v[196:199], v[40:43]
	v_mfma_f32_16x16x32_bf16 v[40:43], v[152:155], v[200:203], v[40:43]
	v_mfma_f32_16x16x32_bf16 v[44:47], v[140:143], v[196:199], v[44:47]
	v_mfma_f32_16x16x32_bf16 v[44:47], v[144:147], v[200:203], v[44:47]
	v_mfma_f32_16x16x32_bf16 v[48:51], v[132:135], v[196:199], v[48:51]
	v_mfma_f32_16x16x32_bf16 v[48:51], v[136:139], v[200:203], v[48:51]
	v_mfma_f32_16x16x32_bf16 v[32:35], v[132:135], v[204:207], v[32:35]
	v_mfma_f32_16x16x32_bf16 v[32:35], v[136:139], v[208:211], v[32:35]
	v_mfma_f32_16x16x32_bf16 v[28:31], v[140:143], v[204:207], v[28:31]
	v_mfma_f32_16x16x32_bf16 v[28:31], v[144:147], v[208:211], v[28:31]
	v_mfma_f32_16x16x32_bf16 v[24:27], v[148:151], v[204:207], v[24:27]
	v_mfma_f32_16x16x32_bf16 v[24:27], v[152:155], v[208:211], v[24:27]
	v_mfma_f32_16x16x32_bf16 v[20:23], v[172:175], v[204:207], v[20:23]
	v_mfma_f32_16x16x32_bf16 v[20:23], v[176:179], v[208:211], v[20:23]
	v_mfma_f32_16x16x32_bf16 v[4:7], v[172:175], v[212:215], v[4:7]
	v_mfma_f32_16x16x32_bf16 v[4:7], v[176:179], v[216:219], v[4:7]
	v_mfma_f32_16x16x32_bf16 v[8:11], v[148:151], v[212:215], v[8:11]
	v_mfma_f32_16x16x32_bf16 v[8:11], v[152:155], v[216:219], v[8:11]
	v_mfma_f32_16x16x32_bf16 v[12:15], v[140:143], v[212:215], v[12:15]
	v_mfma_f32_16x16x32_bf16 v[12:15], v[144:147], v[216:219], v[12:15]
	v_mfma_f32_16x16x32_bf16 v[16:19], v[132:135], v[212:215], v[16:19]
	v_mfma_f32_16x16x32_bf16 v[16:19], v[136:139], v[216:219], v[16:19]
	s_setprio 0
	s_barrier
	s_add_i32 s64, s64, 2
	s_add_u32 s42, s42, 0x100
	s_addc_u32 s43, s43, 0
	s_add_u32 s62, s62, 0x100
	s_addc_u32 s63, s63, 0
	s_cmp_gt_u32 s64, 5
	s_cbranch_scc0 .LBB0_1415
	s_and_b64 vcc, exec, s[16:17]
	s_cbranch_vccz .LBB0_1418
	s_barrier

.LBB0_1503:
	ds_read_b128 v[132:135], v159
	ds_read_b128 v[164:167], v159 offset:1024
	ds_read_b128 v[168:171], v159 offset:2048
	ds_read_b128 v[172:175], v159 offset:3072
	ds_read_b128 v[176:179], v160
	ds_read_b128 v[180:183], v160 offset:1024
	ds_read_b128 v[184:187], v160 offset:2048
	ds_read_b128 v[188:191], v160 offset:3072
	s_add_u32 s0, s54, 0xfff00080
	s_addc_u32 s56, s55, -1
	s_cmp_eq_u32 s75, 60
	s_cselect_b32 s59, s31, s56
	s_cselect_b32 s58, s71, s0
	s_cselect_b32 s57, s29, s74
	s_cselect_b32 s56, s72, s73
	s_add_i32 m0, s48, 0xc000
	ds_read_b128 v[192:195], v161
	ds_read_b128 v[196:199], v161 offset:1024
	ds_read_b128 v[200:203], v161 offset:2048
	ds_read_b128 v[204:207], v161 offset:3072
	ds_read_b128 v[208:211], v161 offset:4096
	ds_read_b128 v[212:215], v161 offset:5120
	ds_read_b128 v[216:219], v161 offset:6144
	ds_read_b128 v[220:223], v161 offset:7168
	global_load_lds_dwordx4 v148, s[54:55]
	s_add_i32 m0, s48, 0xe000
	s_nop 0
	global_load_lds_dwordx4 v150, s[54:55]
	s_setprio 1
	s_waitcnt vmcnt(8) lgkmcnt(0)
	s_barrier
	v_mfma_f32_16x16x32_bf16 v[136:139], v[132:135], v[192:195], v[136:139]
	v_mfma_f32_16x16x32_bf16 v[136:139], v[164:167], v[196:199], v[136:139]
	v_mfma_f32_16x16x32_bf16 v[128:131], v[168:171], v[192:195], v[128:131]
	v_mfma_f32_16x16x32_bf16 v[128:131], v[172:175], v[196:199], v[128:131]
	v_mfma_f32_16x16x32_bf16 v[124:127], v[176:179], v[192:195], v[124:127]
	v_mfma_f32_16x16x32_bf16 v[124:127], v[180:183], v[196:199], v[124:127]
	v_mfma_f32_16x16x32_bf16 v[120:123], v[184:187], v[192:195], v[120:123]
	v_mfma_f32_16x16x32_bf16 v[120:123], v[188:191], v[196:199], v[120:123]
	v_mfma_f32_16x16x32_bf16 v[104:107], v[184:187], v[200:203], v[104:107]
	v_mfma_f32_16x16x32_bf16 v[104:107], v[188:191], v[204:207], v[104:107]
	v_mfma_f32_16x16x32_bf16 v[108:111], v[176:179], v[200:203], v[108:111]
	v_mfma_f32_16x16x32_bf16 v[108:111], v[180:183], v[204:207], v[108:111]
	v_mfma_f32_16x16x32_bf16 v[112:115], v[168:171], v[200:203], v[112:115]
	v_mfma_f32_16x16x32_bf16 v[112:115], v[172:175], v[204:207], v[112:115]
	v_mfma_f32_16x16x32_bf16 v[116:119], v[132:135], v[200:203], v[116:119]
	v_mfma_f32_16x16x32_bf16 v[116:119], v[164:167], v[204:207], v[116:119]
	v_mfma_f32_16x16x32_bf16 v[100:103], v[132:135], v[208:211], v[100:103]
	v_mfma_f32_16x16x32_bf16 v[100:103], v[164:167], v[212:215], v[100:103]
	v_mfma_f32_16x16x32_bf16 v[96:99], v[168:171], v[208:211], v[96:99]
	v_mfma_f32_16x16x32_bf16 v[96:99], v[172:175], v[212:215], v[96:99]
	v_mfma_f32_16x16x32_bf16 v[92:95], v[176:179], v[208:211], v[92:95]
	v_mfma_f32_16x16x32_bf16 v[92:95], v[180:183], v[212:215], v[92:95]
	v_mfma_f32_16x16x32_bf16 v[88:91], v[184:187], v[208:211], v[88:91]
	v_mfma_f32_16x16x32_bf16 v[88:91], v[188:191], v[212:215], v[88:91]
	v_mfma_f32_16x16x32_bf16 v[72:75], v[184:187], v[216:219], v[72:75]
	v_mfma_f32_16x16x32_bf16 v[72:75], v[188:191], v[220:223], v[72:75]
	v_mfma_f32_16x16x32_bf16 v[76:79], v[176:179], v[216:219], v[76:79]
	v_mfma_f32_16x16x32_bf16 v[76:79], v[180:183], v[220:223], v[76:79]
	v_mfma_f32_16x16x32_bf16 v[80:83], v[168:171], v[216:219], v[80:83]
	v_mfma_f32_16x16x32_bf16 v[80:83], v[172:175], v[220:223], v[80:83]
	v_mfma_f32_16x16x32_bf16 v[84:87], v[132:135], v[216:219], v[84:87]
	v_mfma_f32_16x16x32_bf16 v[84:87], v[164:167], v[220:223], v[84:87]
	s_setprio 0
	s_barrier
	s_add_i32 s0, s65, s47
	s_mov_b32 m0, s0
	ds_read_b128 v[192:195], v161 offset:16384
	ds_read_b128 v[196:199], v161 offset:17408
	ds_read_b128 v[200:203], v161 offset:18432
	ds_read_b128 v[204:207], v161 offset:19456
	ds_read_b128 v[208:211], v161 offset:20480
	ds_read_b128 v[212:215], v161 offset:21504
	ds_read_b128 v[216:219], v161 offset:22528
	ds_read_b128 v[220:223], v161 offset:23552
	global_load_lds_dwordx4 v142, s[56:57]
	s_add_i32 m0, s0, 0x2000
	s_add_u32 s76, s56, 0x100000
	s_addc_u32 s77, s57, 0
	s_add_i32 s0, s66, s47
	global_load_lds_dwordx4 v146, s[56:57]
	s_mov_b32 m0, s0
	s_nop 0
	global_load_lds_dwordx4 v142, s[76:77]
	s_add_i32 m0, s0, 0x2000
	s_nop 0
	global_load_lds_dwordx4 v146, s[76:77]
	s_mov_b32 m0, s48
	s_nop 0
	global_load_lds_dwordx4 v140, s[58:59]
	s_mov_b32 m0, s49
	s_nop 0
	global_load_lds_dwordx4 v144, s[58:59]
	s_setprio 1
	s_waitcnt vmcnt(8) lgkmcnt(0)
	s_barrier
	v_mfma_f32_16x16x32_bf16 v[68:71], v[132:135], v[192:195], v[68:71]
	v_mfma_f32_16x16x32_bf16 v[68:71], v[164:167], v[196:199], v[68:71]
	v_mfma_f32_16x16x32_bf16 v[64:67], v[168:171], v[192:195], v[64:67]
	v_mfma_f32_16x16x32_bf16 v[64:67], v[172:175], v[196:199], v[64:67]
	v_mfma_f32_16x16x32_bf16 v[60:63], v[176:179], v[192:195], v[60:63]
	v_mfma_f32_16x16x32_bf16 v[60:63], v[180:183], v[196:199], v[60:63]
	v_mfma_f32_16x16x32_bf16 v[56:59], v[184:187], v[192:195], v[56:59]
	v_mfma_f32_16x16x32_bf16 v[56:59], v[188:191], v[196:199], v[56:59]
	v_mfma_f32_16x16x32_bf16 v[40:43], v[184:187], v[200:203], v[40:43]
	v_mfma_f32_16x16x32_bf16 v[40:43], v[188:191], v[204:207], v[40:43]
	v_mfma_f32_16x16x32_bf16 v[44:47], v[176:179], v[200:203], v[44:47]
	v_mfma_f32_16x16x32_bf16 v[44:47], v[180:183], v[204:207], v[44:47]
	v_mfma_f32_16x16x32_bf16 v[48:51], v[168:171], v[200:203], v[48:51]
	v_mfma_f32_16x16x32_bf16 v[48:51], v[172:175], v[204:207], v[48:51]
	v_mfma_f32_16x16x32_bf16 v[52:55], v[132:135], v[200:203], v[52:55]
	v_mfma_f32_16x16x32_bf16 v[52:55], v[164:167], v[204:207], v[52:55]
	v_mfma_f32_16x16x32_bf16 v[36:39], v[132:135], v[208:211], v[36:39]
	v_mfma_f32_16x16x32_bf16 v[36:39], v[164:167], v[212:215], v[36:39]
	v_mfma_f32_16x16x32_bf16 v[32:35], v[168:171], v[208:211], v[32:35]
	v_mfma_f32_16x16x32_bf16 v[32:35], v[172:175], v[212:215], v[32:35]
	v_mfma_f32_16x16x32_bf16 v[28:31], v[176:179], v[208:211], v[28:31]
	v_mfma_f32_16x16x32_bf16 v[28:31], v[180:183], v[212:215], v[28:31]
	v_mfma_f32_16x16x32_bf16 v[24:27], v[184:187], v[208:211], v[24:27]
	v_mfma_f32_16x16x32_bf16 v[24:27], v[188:191], v[212:215], v[24:27]
	v_mfma_f32_16x16x32_bf16 v[8:11], v[184:187], v[216:219], v[8:11]
	v_mfma_f32_16x16x32_bf16 v[8:11], v[188:191], v[220:223], v[8:11]
	v_mfma_f32_16x16x32_bf16 v[12:15], v[176:179], v[216:219], v[12:15]
	v_mfma_f32_16x16x32_bf16 v[12:15], v[180:183], v[220:223], v[12:15]
	v_mfma_f32_16x16x32_bf16 v[16:19], v[168:171], v[216:219], v[16:19]
	v_mfma_f32_16x16x32_bf16 v[16:19], v[172:175], v[220:223], v[16:19]
	v_mfma_f32_16x16x32_bf16 v[20:23], v[132:135], v[216:219], v[20:23]
	v_mfma_f32_16x16x32_bf16 v[20:23], v[164:167], v[220:223], v[20:23]
	s_setprio 0
	s_barrier
	s_add_i32 s0, 0, 0x18000
	s_add_i32 s76, 0, 0x1c000
	v_add_u32_e32 v172, s0, v156
	v_add_u32_e32 v188, s76, v156
	ds_read_b128 v[132:135], v172
	ds_read_b128 v[164:167], v172 offset:1024
	ds_read_b128 v[168:171], v172 offset:2048
	ds_read_b128 v[172:175], v172 offset:3072
	ds_read_b128 v[176:179], v188
	ds_read_b128 v[180:183], v188 offset:1024
	ds_read_b128 v[184:187], v188 offset:2048
	ds_read_b128 v[188:191], v188 offset:3072
	s_add_u32 s98, s58, 0x100000
	s_addc_u32 s99, s59, 0
	s_mov_b32 m0, s51
	ds_read_b128 v[192:195], v161 offset:32768
	ds_read_b128 v[196:199], v161 offset:33792
	ds_read_b128 v[200:203], v161 offset:34816
	ds_read_b128 v[204:207], v161 offset:35840
	ds_read_b128 v[208:211], v161 offset:36864
	ds_read_b128 v[212:215], v161 offset:37888
	ds_read_b128 v[216:219], v161 offset:38912
	ds_read_b128 v[220:223], v161 offset:39936
	global_load_lds_dwordx4 v140, s[98:99]
	s_mov_b32 m0, s53
	s_nop 0
	global_load_lds_dwordx4 v144, s[98:99]
	s_setprio 1
	s_waitcnt vmcnt(8) lgkmcnt(0)
	s_barrier
	v_mfma_f32_16x16x32_bf16 v[136:139], v[132:135], v[192:195], v[136:139]
	v_mfma_f32_16x16x32_bf16 v[136:139], v[164:167], v[196:199], v[136:139]
	v_mfma_f32_16x16x32_bf16 v[128:131], v[168:171], v[192:195], v[128:131]
	v_mfma_f32_16x16x32_bf16 v[128:131], v[172:175], v[196:199], v[128:131]
	v_mfma_f32_16x16x32_bf16 v[124:127], v[176:179], v[192:195], v[124:127]
	v_mfma_f32_16x16x32_bf16 v[124:127], v[180:183], v[196:199], v[124:127]
	v_mfma_f32_16x16x32_bf16 v[120:123], v[184:187], v[192:195], v[120:123]
	v_mfma_f32_16x16x32_bf16 v[120:123], v[188:191], v[196:199], v[120:123]
	v_mfma_f32_16x16x32_bf16 v[104:107], v[184:187], v[200:203], v[104:107]
	v_mfma_f32_16x16x32_bf16 v[104:107], v[188:191], v[204:207], v[104:107]
	v_mfma_f32_16x16x32_bf16 v[108:111], v[176:179], v[200:203], v[108:111]
	v_mfma_f32_16x16x32_bf16 v[108:111], v[180:183], v[204:207], v[108:111]
	v_mfma_f32_16x16x32_bf16 v[112:115], v[168:171], v[200:203], v[112:115]
	v_mfma_f32_16x16x32_bf16 v[112:115], v[172:175], v[204:207], v[112:115]
	v_mfma_f32_16x16x32_bf16 v[116:119], v[132:135], v[200:203], v[116:119]
	v_mfma_f32_16x16x32_bf16 v[116:119], v[164:167], v[204:207], v[116:119]
	v_mfma_f32_16x16x32_bf16 v[100:103], v[132:135], v[208:211], v[100:103]
	v_mfma_f32_16x16x32_bf16 v[100:103], v[164:167], v[212:215], v[100:103]
	v_mfma_f32_16x16x32_bf16 v[96:99], v[168:171], v[208:211], v[96:99]
	v_mfma_f32_16x16x32_bf16 v[96:99], v[172:175], v[212:215], v[96:99]
	v_mfma_f32_16x16x32_bf16 v[92:95], v[176:179], v[208:211], v[92:95]
	v_mfma_f32_16x16x32_bf16 v[92:95], v[180:183], v[212:215], v[92:95]
	v_mfma_f32_16x16x32_bf16 v[88:91], v[184:187], v[208:211], v[88:91]
	v_mfma_f32_16x16x32_bf16 v[88:91], v[188:191], v[212:215], v[88:91]
	v_mfma_f32_16x16x32_bf16 v[72:75], v[184:187], v[216:219], v[72:75]
	v_mfma_f32_16x16x32_bf16 v[72:75], v[188:191], v[220:223], v[72:75]
	v_mfma_f32_16x16x32_bf16 v[76:79], v[176:179], v[216:219], v[76:79]
	v_mfma_f32_16x16x32_bf16 v[76:79], v[180:183], v[220:223], v[76:79]
	v_mfma_f32_16x16x32_bf16 v[80:83], v[168:171], v[216:219], v[80:83]
	v_mfma_f32_16x16x32_bf16 v[80:83], v[172:175], v[220:223], v[80:83]
	v_mfma_f32_16x16x32_bf16 v[84:87], v[132:135], v[216:219], v[84:87]
	v_mfma_f32_16x16x32_bf16 v[84:87], v[164:167], v[220:223], v[84:87]
	s_setprio 0
	s_barrier
	s_add_i32 s0, s0, s47
	s_add_i32 m0, s0, 0xffffff80
	ds_read_b128 v[192:195], v161 offset:49152
	ds_read_b128 v[196:199], v161 offset:50176
	ds_read_b128 v[200:203], v161 offset:51200
	ds_read_b128 v[204:207], v161 offset:52224
	ds_read_b128 v[208:211], v161 offset:53248
	ds_read_b128 v[212:215], v161 offset:54272
	ds_read_b128 v[216:219], v161 offset:55296
	ds_read_b128 v[220:223], v161 offset:56320
	global_load_lds_dwordx4 v142, s[56:57] offset:128
	s_add_i32 m0, s0, 0x1f80
	s_add_i32 s0, s76, s47
	global_load_lds_dwordx4 v146, s[56:57] offset:128
	s_add_u32 s56, s56, 0x100080
	s_addc_u32 s57, s57, 0
	s_mov_b32 m0, s0
	s_nop 0
	global_load_lds_dwordx4 v142, s[56:57]
	s_add_i32 m0, s0, 0x2000
	s_nop 0
	global_load_lds_dwordx4 v146, s[56:57]
	s_add_i32 m0, s62, 0xffffff80
	s_nop 0
	global_load_lds_dwordx4 v140, s[58:59] offset:128
	s_add_i32 m0, s63, 0xffffff80
	s_nop 0
	global_load_lds_dwordx4 v144, s[58:59] offset:128
	s_setprio 1
	s_waitcnt vmcnt(8) lgkmcnt(0)
	s_barrier
	v_mfma_f32_16x16x32_bf16 v[68:71], v[132:135], v[192:195], v[68:71]
	v_mfma_f32_16x16x32_bf16 v[68:71], v[164:167], v[196:199], v[68:71]
	v_mfma_f32_16x16x32_bf16 v[64:67], v[168:171], v[192:195], v[64:67]
	v_mfma_f32_16x16x32_bf16 v[64:67], v[172:175], v[196:199], v[64:67]
	v_mfma_f32_16x16x32_bf16 v[60:63], v[176:179], v[192:195], v[60:63]
	v_mfma_f32_16x16x32_bf16 v[60:63], v[180:183], v[196:199], v[60:63]
	v_mfma_f32_16x16x32_bf16 v[56:59], v[184:187], v[192:195], v[56:59]
	v_mfma_f32_16x16x32_bf16 v[56:59], v[188:191], v[196:199], v[56:59]
	v_mfma_f32_16x16x32_bf16 v[40:43], v[184:187], v[200:203], v[40:43]
	v_mfma_f32_16x16x32_bf16 v[40:43], v[188:191], v[204:207], v[40:43]
	v_mfma_f32_16x16x32_bf16 v[44:47], v[176:179], v[200:203], v[44:47]
	v_mfma_f32_16x16x32_bf16 v[44:47], v[180:183], v[204:207], v[44:47]
	v_mfma_f32_16x16x32_bf16 v[48:51], v[168:171], v[200:203], v[48:51]
	v_mfma_f32_16x16x32_bf16 v[48:51], v[172:175], v[204:207], v[48:51]
	v_mfma_f32_16x16x32_bf16 v[52:55], v[132:135], v[200:203], v[52:55]
	v_mfma_f32_16x16x32_bf16 v[52:55], v[164:167], v[204:207], v[52:55]
	v_mfma_f32_16x16x32_bf16 v[36:39], v[132:135], v[208:211], v[36:39]
	v_mfma_f32_16x16x32_bf16 v[36:39], v[164:167], v[212:215], v[36:39]
	v_mfma_f32_16x16x32_bf16 v[32:35], v[168:171], v[208:211], v[32:35]
	v_mfma_f32_16x16x32_bf16 v[32:35], v[172:175], v[212:215], v[32:35]
	v_mfma_f32_16x16x32_bf16 v[28:31], v[176:179], v[208:211], v[28:31]
	v_mfma_f32_16x16x32_bf16 v[28:31], v[180:183], v[212:215], v[28:31]
	v_mfma_f32_16x16x32_bf16 v[24:27], v[184:187], v[208:211], v[24:27]
	v_mfma_f32_16x16x32_bf16 v[24:27], v[188:191], v[212:215], v[24:27]
	v_mfma_f32_16x16x32_bf16 v[8:11], v[184:187], v[216:219], v[8:11]
	v_mfma_f32_16x16x32_bf16 v[8:11], v[188:191], v[220:223], v[8:11]
	v_mfma_f32_16x16x32_bf16 v[12:15], v[176:179], v[216:219], v[12:15]
	v_mfma_f32_16x16x32_bf16 v[12:15], v[180:183], v[220:223], v[12:15]
	v_mfma_f32_16x16x32_bf16 v[16:19], v[168:171], v[216:219], v[16:19]
	v_mfma_f32_16x16x32_bf16 v[16:19], v[172:175], v[220:223], v[16:19]
	v_mfma_f32_16x16x32_bf16 v[20:23], v[132:135], v[216:219], v[20:23]
	v_mfma_f32_16x16x32_bf16 v[20:23], v[164:167], v[220:223], v[20:23]
	s_setprio 0
	s_barrier
	s_add_i32 s75, s75, 2
	s_add_u32 s54, s54, 0x100
	s_addc_u32 s55, s55, 0
	s_add_u32 s73, s73, 0x100
	s_addc_u32 s74, s74, 0
	s_cmp_gt_u32 s75, 61
	s_cbranch_scc0 .LBB0_1503
	s_and_b64 vcc, exec, s[26:27]
	s_cbranch_vccz .LBB0_1506
	s_barrier

.LBB0_1672:
	ds_read_b128 v[132:135], v193
	ds_read_b128 v[136:139], v193 offset:1024
	ds_read_b128 v[140:143], v193 offset:2048
	ds_read_b128 v[144:147], v193 offset:3072
	ds_read_b128 v[148:151], v194
	ds_read_b128 v[152:155], v194 offset:1024
	ds_read_b128 v[172:175], v194 offset:2048
	ds_read_b128 v[176:179], v194 offset:3072
	s_add_u32 s0, s30, 0xffd50080
	s_addc_u32 s42, s31, -1
	s_cmpk_eq_i32 s66, 0xa8
	s_cselect_b32 s51, s7, s42
	s_cselect_b32 s50, s6, s0
	s_cselect_b32 s43, s29, s65
	s_cselect_b32 s42, s28, s64
	s_add_i32 m0, s46, 0xc000
	ds_read_b128 v[180:183], v195
	ds_read_b128 v[198:201], v195 offset:1024
	ds_read_b128 v[202:205], v195 offset:2048
	ds_read_b128 v[206:209], v195 offset:3072
	ds_read_b128 v[210:213], v195 offset:4096
	ds_read_b128 v[214:217], v195 offset:5120
	ds_read_b128 v[218:221], v195 offset:6144
	ds_read_b128 v[222:225], v195 offset:7168
	global_load_lds_dwordx4 v164, s[30:31]
	s_add_i32 m0, s46, 0xe000
	s_nop 0
	global_load_lds_dwordx4 v166, s[30:31]
	s_setprio 1
	s_waitcnt vmcnt(8) lgkmcnt(0)
	s_barrier
	v_mfma_f32_16x16x32_bf16 v[128:131], v[132:135], v[180:183], v[128:131]
	v_mfma_f32_16x16x32_bf16 v[128:131], v[136:139], v[198:201], v[128:131]
	v_mfma_f32_16x16x32_bf16 v[124:127], v[140:143], v[180:183], v[124:127]
	v_mfma_f32_16x16x32_bf16 v[124:127], v[144:147], v[198:201], v[124:127]
	v_mfma_f32_16x16x32_bf16 v[120:123], v[148:151], v[180:183], v[120:123]
	v_mfma_f32_16x16x32_bf16 v[120:123], v[152:155], v[198:201], v[120:123]
	v_mfma_f32_16x16x32_bf16 v[116:119], v[172:175], v[180:183], v[116:119]
	v_mfma_f32_16x16x32_bf16 v[116:119], v[176:179], v[198:201], v[116:119]
	v_mfma_f32_16x16x32_bf16 v[100:103], v[172:175], v[202:205], v[100:103]
	v_mfma_f32_16x16x32_bf16 v[100:103], v[176:179], v[206:209], v[100:103]
	v_mfma_f32_16x16x32_bf16 v[104:107], v[148:151], v[202:205], v[104:107]
	v_mfma_f32_16x16x32_bf16 v[104:107], v[152:155], v[206:209], v[104:107]
	v_mfma_f32_16x16x32_bf16 v[108:111], v[140:143], v[202:205], v[108:111]
	v_mfma_f32_16x16x32_bf16 v[108:111], v[144:147], v[206:209], v[108:111]
	v_mfma_f32_16x16x32_bf16 v[112:115], v[132:135], v[202:205], v[112:115]
	v_mfma_f32_16x16x32_bf16 v[112:115], v[136:139], v[206:209], v[112:115]
	v_mfma_f32_16x16x32_bf16 v[96:99], v[132:135], v[210:213], v[96:99]
	v_mfma_f32_16x16x32_bf16 v[96:99], v[136:139], v[214:217], v[96:99]
	v_mfma_f32_16x16x32_bf16 v[92:95], v[140:143], v[210:213], v[92:95]
	v_mfma_f32_16x16x32_bf16 v[92:95], v[144:147], v[214:217], v[92:95]
	v_mfma_f32_16x16x32_bf16 v[88:91], v[148:151], v[210:213], v[88:91]
	v_mfma_f32_16x16x32_bf16 v[88:91], v[152:155], v[214:217], v[88:91]
	v_mfma_f32_16x16x32_bf16 v[84:87], v[172:175], v[210:213], v[84:87]
	v_mfma_f32_16x16x32_bf16 v[84:87], v[176:179], v[214:217], v[84:87]
	v_mfma_f32_16x16x32_bf16 v[68:71], v[172:175], v[218:221], v[68:71]
	v_mfma_f32_16x16x32_bf16 v[68:71], v[176:179], v[222:225], v[68:71]
	v_mfma_f32_16x16x32_bf16 v[72:75], v[148:151], v[218:221], v[72:75]
	v_mfma_f32_16x16x32_bf16 v[72:75], v[152:155], v[222:225], v[72:75]
	v_mfma_f32_16x16x32_bf16 v[76:79], v[140:143], v[218:221], v[76:79]
	v_mfma_f32_16x16x32_bf16 v[76:79], v[144:147], v[222:225], v[76:79]
	v_mfma_f32_16x16x32_bf16 v[80:83], v[132:135], v[218:221], v[80:83]
	v_mfma_f32_16x16x32_bf16 v[80:83], v[136:139], v[222:225], v[80:83]
	s_setprio 0
	s_barrier
	s_add_i32 s0, s57, s45
	s_mov_b32 m0, s0
	ds_read_b128 v[180:183], v195 offset:16384
	ds_read_b128 v[198:201], v195 offset:17408
	ds_read_b128 v[202:205], v195 offset:18432
	ds_read_b128 v[206:209], v195 offset:19456
	ds_read_b128 v[210:213], v195 offset:20480
	ds_read_b128 v[214:217], v195 offset:21504
	ds_read_b128 v[218:221], v195 offset:22528
	ds_read_b128 v[222:225], v195 offset:23552
	global_load_lds_dwordx4 v158, s[42:43]
	s_add_i32 m0, s0, 0x2000
	s_add_u32 s70, s42, 0x2b0000
	s_addc_u32 s71, s43, 0
	s_add_i32 s0, s58, s45
	global_load_lds_dwordx4 v162, s[42:43]
	s_mov_b32 m0, s0
	s_nop 0
	global_load_lds_dwordx4 v158, s[70:71]
	s_add_i32 m0, s0, 0x2000
	s_nop 0
	global_load_lds_dwordx4 v162, s[70:71]
	s_mov_b32 m0, s46
	s_nop 0
	global_load_lds_dwordx4 v156, s[50:51]
	s_mov_b32 m0, s47
	s_nop 0
	global_load_lds_dwordx4 v160, s[50:51]
	s_setprio 1
	s_waitcnt vmcnt(8) lgkmcnt(0)
	s_barrier
	v_mfma_f32_16x16x32_bf16 v[64:67], v[132:135], v[180:183], v[64:67]
	v_mfma_f32_16x16x32_bf16 v[64:67], v[136:139], v[198:201], v[64:67]
	v_mfma_f32_16x16x32_bf16 v[60:63], v[140:143], v[180:183], v[60:63]
	v_mfma_f32_16x16x32_bf16 v[60:63], v[144:147], v[198:201], v[60:63]
	v_mfma_f32_16x16x32_bf16 v[56:59], v[148:151], v[180:183], v[56:59]
	v_mfma_f32_16x16x32_bf16 v[56:59], v[152:155], v[198:201], v[56:59]
	v_mfma_f32_16x16x32_bf16 v[52:55], v[172:175], v[180:183], v[52:55]
	v_mfma_f32_16x16x32_bf16 v[52:55], v[176:179], v[198:201], v[52:55]
	v_mfma_f32_16x16x32_bf16 v[36:39], v[172:175], v[202:205], v[36:39]
	v_mfma_f32_16x16x32_bf16 v[36:39], v[176:179], v[206:209], v[36:39]
	v_mfma_f32_16x16x32_bf16 v[40:43], v[148:151], v[202:205], v[40:43]
	v_mfma_f32_16x16x32_bf16 v[40:43], v[152:155], v[206:209], v[40:43]
	v_mfma_f32_16x16x32_bf16 v[44:47], v[140:143], v[202:205], v[44:47]
	v_mfma_f32_16x16x32_bf16 v[44:47], v[144:147], v[206:209], v[44:47]
	v_mfma_f32_16x16x32_bf16 v[48:51], v[132:135], v[202:205], v[48:51]
	v_mfma_f32_16x16x32_bf16 v[48:51], v[136:139], v[206:209], v[48:51]
	v_mfma_f32_16x16x32_bf16 v[32:35], v[132:135], v[210:213], v[32:35]
	v_mfma_f32_16x16x32_bf16 v[32:35], v[136:139], v[214:217], v[32:35]
	v_mfma_f32_16x16x32_bf16 v[28:31], v[140:143], v[210:213], v[28:31]
	v_mfma_f32_16x16x32_bf16 v[28:31], v[144:147], v[214:217], v[28:31]
	v_mfma_f32_16x16x32_bf16 v[24:27], v[148:151], v[210:213], v[24:27]
	v_mfma_f32_16x16x32_bf16 v[24:27], v[152:155], v[214:217], v[24:27]
	v_mfma_f32_16x16x32_bf16 v[20:23], v[172:175], v[210:213], v[20:23]
	v_mfma_f32_16x16x32_bf16 v[20:23], v[176:179], v[214:217], v[20:23]
	v_mfma_f32_16x16x32_bf16 v[4:7], v[172:175], v[218:221], v[4:7]
	v_mfma_f32_16x16x32_bf16 v[4:7], v[176:179], v[222:225], v[4:7]
	v_mfma_f32_16x16x32_bf16 v[8:11], v[148:151], v[218:221], v[8:11]
	v_mfma_f32_16x16x32_bf16 v[8:11], v[152:155], v[222:225], v[8:11]
	v_mfma_f32_16x16x32_bf16 v[12:15], v[140:143], v[218:221], v[12:15]
	v_mfma_f32_16x16x32_bf16 v[12:15], v[144:147], v[222:225], v[12:15]
	v_mfma_f32_16x16x32_bf16 v[16:19], v[132:135], v[218:221], v[16:19]
	v_mfma_f32_16x16x32_bf16 v[16:19], v[136:139], v[222:225], v[16:19]
	s_setprio 0
	s_barrier
	s_add_i32 s0, 0, 0x18000
	s_add_i32 s67, 0, 0x1c000
	v_add_u32_e32 v144, s0, v191
	v_add_u32_e32 v176, s67, v191
	ds_read_b128 v[132:135], v144
	ds_read_b128 v[136:139], v144 offset:1024
	ds_read_b128 v[140:143], v144 offset:2048
	ds_read_b128 v[144:147], v144 offset:3072
	ds_read_b128 v[148:151], v176
	ds_read_b128 v[152:155], v176 offset:1024
	ds_read_b128 v[172:175], v176 offset:2048
	ds_read_b128 v[176:179], v176 offset:3072
	s_add_u32 s98, s50, 0x2b0000
	s_addc_u32 s99, s51, 0
	s_mov_b32 m0, s48
	ds_read_b128 v[180:183], v195 offset:32768
	ds_read_b128 v[198:201], v195 offset:33792
	ds_read_b128 v[202:205], v195 offset:34816
	ds_read_b128 v[206:209], v195 offset:35840
	ds_read_b128 v[210:213], v195 offset:36864
	ds_read_b128 v[214:217], v195 offset:37888
	ds_read_b128 v[218:221], v195 offset:38912
	ds_read_b128 v[222:225], v195 offset:39936
	global_load_lds_dwordx4 v156, s[98:99]
	s_mov_b32 m0, s49
	s_nop 0
	global_load_lds_dwordx4 v160, s[98:99]
	s_setprio 1
	s_waitcnt vmcnt(8) lgkmcnt(0)
	s_barrier
	v_mfma_f32_16x16x32_bf16 v[128:131], v[132:135], v[180:183], v[128:131]
	v_mfma_f32_16x16x32_bf16 v[128:131], v[136:139], v[198:201], v[128:131]
	v_mfma_f32_16x16x32_bf16 v[124:127], v[140:143], v[180:183], v[124:127]
	v_mfma_f32_16x16x32_bf16 v[124:127], v[144:147], v[198:201], v[124:127]
	v_mfma_f32_16x16x32_bf16 v[120:123], v[148:151], v[180:183], v[120:123]
	v_mfma_f32_16x16x32_bf16 v[120:123], v[152:155], v[198:201], v[120:123]
	v_mfma_f32_16x16x32_bf16 v[116:119], v[172:175], v[180:183], v[116:119]
	v_mfma_f32_16x16x32_bf16 v[116:119], v[176:179], v[198:201], v[116:119]
	v_mfma_f32_16x16x32_bf16 v[100:103], v[172:175], v[202:205], v[100:103]
	v_mfma_f32_16x16x32_bf16 v[100:103], v[176:179], v[206:209], v[100:103]
	v_mfma_f32_16x16x32_bf16 v[104:107], v[148:151], v[202:205], v[104:107]
	v_mfma_f32_16x16x32_bf16 v[104:107], v[152:155], v[206:209], v[104:107]
	v_mfma_f32_16x16x32_bf16 v[108:111], v[140:143], v[202:205], v[108:111]
	v_mfma_f32_16x16x32_bf16 v[108:111], v[144:147], v[206:209], v[108:111]
	v_mfma_f32_16x16x32_bf16 v[112:115], v[132:135], v[202:205], v[112:115]
	v_mfma_f32_16x16x32_bf16 v[112:115], v[136:139], v[206:209], v[112:115]
	v_mfma_f32_16x16x32_bf16 v[96:99], v[132:135], v[210:213], v[96:99]
	v_mfma_f32_16x16x32_bf16 v[96:99], v[136:139], v[214:217], v[96:99]
	v_mfma_f32_16x16x32_bf16 v[92:95], v[140:143], v[210:213], v[92:95]
	v_mfma_f32_16x16x32_bf16 v[92:95], v[144:147], v[214:217], v[92:95]
	v_mfma_f32_16x16x32_bf16 v[88:91], v[148:151], v[210:213], v[88:91]
	v_mfma_f32_16x16x32_bf16 v[88:91], v[152:155], v[214:217], v[88:91]
	v_mfma_f32_16x16x32_bf16 v[84:87], v[172:175], v[210:213], v[84:87]
	v_mfma_f32_16x16x32_bf16 v[84:87], v[176:179], v[214:217], v[84:87]
	v_mfma_f32_16x16x32_bf16 v[68:71], v[172:175], v[218:221], v[68:71]
	v_mfma_f32_16x16x32_bf16 v[68:71], v[176:179], v[222:225], v[68:71]
	v_mfma_f32_16x16x32_bf16 v[72:75], v[148:151], v[218:221], v[72:75]
	v_mfma_f32_16x16x32_bf16 v[72:75], v[152:155], v[222:225], v[72:75]
	v_mfma_f32_16x16x32_bf16 v[76:79], v[140:143], v[218:221], v[76:79]
	v_mfma_f32_16x16x32_bf16 v[76:79], v[144:147], v[222:225], v[76:79]
	v_mfma_f32_16x16x32_bf16 v[80:83], v[132:135], v[218:221], v[80:83]
	v_mfma_f32_16x16x32_bf16 v[80:83], v[136:139], v[222:225], v[80:83]
	s_setprio 0
	s_barrier
	s_add_i32 s0, s0, s45
	s_add_i32 m0, s0, 0xffffff80
	ds_read_b128 v[180:183], v195 offset:49152
	ds_read_b128 v[198:201], v195 offset:50176
	ds_read_b128 v[202:205], v195 offset:51200
	ds_read_b128 v[206:209], v195 offset:52224
	ds_read_b128 v[210:213], v195 offset:53248
	ds_read_b128 v[214:217], v195 offset:54272
	ds_read_b128 v[218:221], v195 offset:55296
	ds_read_b128 v[222:225], v195 offset:56320
	global_load_lds_dwordx4 v158, s[42:43] offset:128
	s_add_i32 m0, s0, 0x1f80
	s_add_i32 s0, s67, s45
	global_load_lds_dwordx4 v162, s[42:43] offset:128
	s_add_u32 s42, s42, 0x2b0080
	s_addc_u32 s43, s43, 0
	s_mov_b32 m0, s0
	s_nop 0
	global_load_lds_dwordx4 v158, s[42:43]
	s_add_i32 m0, s0, 0x2000
	s_nop 0
	global_load_lds_dwordx4 v162, s[42:43]
	s_add_i32 m0, s55, 0xffffff80
	s_nop 0
	global_load_lds_dwordx4 v156, s[50:51] offset:128
	s_add_i32 m0, s56, 0xffffff80
	s_nop 0
	global_load_lds_dwordx4 v160, s[50:51] offset:128
	s_setprio 1
	s_waitcnt vmcnt(8) lgkmcnt(0)
	s_barrier
	v_mfma_f32_16x16x32_bf16 v[64:67], v[132:135], v[180:183], v[64:67]
	v_mfma_f32_16x16x32_bf16 v[64:67], v[136:139], v[198:201], v[64:67]
	v_mfma_f32_16x16x32_bf16 v[60:63], v[140:143], v[180:183], v[60:63]
	v_mfma_f32_16x16x32_bf16 v[60:63], v[144:147], v[198:201], v[60:63]
	v_mfma_f32_16x16x32_bf16 v[56:59], v[148:151], v[180:183], v[56:59]
	v_mfma_f32_16x16x32_bf16 v[56:59], v[152:155], v[198:201], v[56:59]
	v_mfma_f32_16x16x32_bf16 v[52:55], v[172:175], v[180:183], v[52:55]
	v_mfma_f32_16x16x32_bf16 v[52:55], v[176:179], v[198:201], v[52:55]
	v_mfma_f32_16x16x32_bf16 v[36:39], v[172:175], v[202:205], v[36:39]
	v_mfma_f32_16x16x32_bf16 v[36:39], v[176:179], v[206:209], v[36:39]
	v_mfma_f32_16x16x32_bf16 v[40:43], v[148:151], v[202:205], v[40:43]
	v_mfma_f32_16x16x32_bf16 v[40:43], v[152:155], v[206:209], v[40:43]
	v_mfma_f32_16x16x32_bf16 v[44:47], v[140:143], v[202:205], v[44:47]
	v_mfma_f32_16x16x32_bf16 v[44:47], v[144:147], v[206:209], v[44:47]
	v_mfma_f32_16x16x32_bf16 v[48:51], v[132:135], v[202:205], v[48:51]
	v_mfma_f32_16x16x32_bf16 v[48:51], v[136:139], v[206:209], v[48:51]
	v_mfma_f32_16x16x32_bf16 v[32:35], v[132:135], v[210:213], v[32:35]
	v_mfma_f32_16x16x32_bf16 v[32:35], v[136:139], v[214:217], v[32:35]
	v_mfma_f32_16x16x32_bf16 v[28:31], v[140:143], v[210:213], v[28:31]
	v_mfma_f32_16x16x32_bf16 v[28:31], v[144:147], v[214:217], v[28:31]
	v_mfma_f32_16x16x32_bf16 v[24:27], v[148:151], v[210:213], v[24:27]
	v_mfma_f32_16x16x32_bf16 v[24:27], v[152:155], v[214:217], v[24:27]
	v_mfma_f32_16x16x32_bf16 v[20:23], v[172:175], v[210:213], v[20:23]
	v_mfma_f32_16x16x32_bf16 v[20:23], v[176:179], v[214:217], v[20:23]
	v_mfma_f32_16x16x32_bf16 v[4:7], v[172:175], v[218:221], v[4:7]
	v_mfma_f32_16x16x32_bf16 v[4:7], v[176:179], v[222:225], v[4:7]
	v_mfma_f32_16x16x32_bf16 v[8:11], v[148:151], v[218:221], v[8:11]
	v_mfma_f32_16x16x32_bf16 v[8:11], v[152:155], v[222:225], v[8:11]
	v_mfma_f32_16x16x32_bf16 v[12:15], v[140:143], v[218:221], v[12:15]
	v_mfma_f32_16x16x32_bf16 v[12:15], v[144:147], v[222:225], v[12:15]
	v_mfma_f32_16x16x32_bf16 v[16:19], v[132:135], v[218:221], v[16:19]
	v_mfma_f32_16x16x32_bf16 v[16:19], v[136:139], v[222:225], v[16:19]
	s_setprio 0
	s_barrier
	s_add_i32 s66, s66, 2
	s_add_u32 s30, s30, 0x100
	s_addc_u32 s31, s31, 0
	s_add_u32 s64, s64, 0x100
	s_addc_u32 s65, s65, 0
	s_cmpk_gt_u32 s66, 0xa9
	s_cbranch_scc0 .LBB0_1672
	s_and_b64 vcc, exec, s[24:25]
	s_cbranch_vccz .LBB0_1675
	s_barrier

.LBB0_1703:
	ds_read_b128 v[136:139], v196
	ds_read_b128 v[140:143], v196 offset:1024
	ds_read_b128 v[144:147], v196 offset:2048
	ds_read_b128 v[148:151], v196 offset:3072
	ds_read_b128 v[152:155], v197
	ds_read_b128 v[176:179], v197 offset:1024
	ds_read_b128 v[180:183], v197 offset:2048
	ds_read_b128 v[184:187], v197 offset:3072
	s_add_u32 s8, s6, 0x100
	s_addc_u32 s9, s7, 0
	s_add_u32 s0, s65, s6
	s_addc_u32 s40, s66, s7
	s_cmpk_eq_i32 s67, 0xa8
	s_cselect_b32 s43, s50, s40
	s_cselect_b32 s40, 0, s8
	s_cselect_b32 s42, s51, s0
	s_cselect_b32 s0, 0, s9
	s_add_u32 s40, s16, s40
	s_addc_u32 s41, s17, s0
	s_mov_b32 m0, s58
	v_lshl_add_u64 v[226:227], v[132:133], 0, s[6:7]
	ds_read_b128 v[188:191], v198
	ds_read_b128 v[192:195], v198 offset:1024
	ds_read_b128 v[202:205], v198 offset:2048
	ds_read_b128 v[206:209], v198 offset:3072
	ds_read_b128 v[210:213], v198 offset:4096
	ds_read_b128 v[214:217], v198 offset:5120
	ds_read_b128 v[218:221], v198 offset:6144
	ds_read_b128 v[222:225], v198 offset:7168
	global_load_lds_dwordx4 v[226:227], off
	v_lshl_add_u64 v[226:227], v[134:135], 0, s[6:7]
	s_mov_b32 m0, s59
	s_nop 0
	global_load_lds_dwordx4 v[226:227], off
	s_setprio 1
	s_waitcnt vmcnt(8) lgkmcnt(0)
	s_barrier
	v_mfma_f32_16x16x32_bf16 v[128:131], v[136:139], v[188:191], v[128:131]
	v_mfma_f32_16x16x32_bf16 v[128:131], v[140:143], v[192:195], v[128:131]
	v_mfma_f32_16x16x32_bf16 v[124:127], v[144:147], v[188:191], v[124:127]
	v_mfma_f32_16x16x32_bf16 v[124:127], v[148:151], v[192:195], v[124:127]
	v_mfma_f32_16x16x32_bf16 v[120:123], v[152:155], v[188:191], v[120:123]
	v_mfma_f32_16x16x32_bf16 v[120:123], v[176:179], v[192:195], v[120:123]
	v_mfma_f32_16x16x32_bf16 v[116:119], v[180:183], v[188:191], v[116:119]
	v_mfma_f32_16x16x32_bf16 v[116:119], v[184:187], v[192:195], v[116:119]
	v_mfma_f32_16x16x32_bf16 v[100:103], v[180:183], v[202:205], v[100:103]
	v_mfma_f32_16x16x32_bf16 v[100:103], v[184:187], v[206:209], v[100:103]
	v_mfma_f32_16x16x32_bf16 v[104:107], v[152:155], v[202:205], v[104:107]
	v_mfma_f32_16x16x32_bf16 v[104:107], v[176:179], v[206:209], v[104:107]
	v_mfma_f32_16x16x32_bf16 v[108:111], v[144:147], v[202:205], v[108:111]
	v_mfma_f32_16x16x32_bf16 v[108:111], v[148:151], v[206:209], v[108:111]
	v_mfma_f32_16x16x32_bf16 v[112:115], v[136:139], v[202:205], v[112:115]
	v_mfma_f32_16x16x32_bf16 v[112:115], v[140:143], v[206:209], v[112:115]
	v_mfma_f32_16x16x32_bf16 v[96:99], v[136:139], v[210:213], v[96:99]
	v_mfma_f32_16x16x32_bf16 v[96:99], v[140:143], v[214:217], v[96:99]
	v_mfma_f32_16x16x32_bf16 v[92:95], v[144:147], v[210:213], v[92:95]
	v_mfma_f32_16x16x32_bf16 v[92:95], v[148:151], v[214:217], v[92:95]
	v_mfma_f32_16x16x32_bf16 v[88:91], v[152:155], v[210:213], v[88:91]
	v_mfma_f32_16x16x32_bf16 v[88:91], v[176:179], v[214:217], v[88:91]
	v_mfma_f32_16x16x32_bf16 v[84:87], v[180:183], v[210:213], v[84:87]
	v_mfma_f32_16x16x32_bf16 v[84:87], v[184:187], v[214:217], v[84:87]
	v_mfma_f32_16x16x32_bf16 v[68:71], v[180:183], v[218:221], v[68:71]
	v_mfma_f32_16x16x32_bf16 v[68:71], v[184:187], v[222:225], v[68:71]
	v_mfma_f32_16x16x32_bf16 v[72:75], v[152:155], v[218:221], v[72:75]
	v_mfma_f32_16x16x32_bf16 v[72:75], v[176:179], v[222:225], v[72:75]
	v_mfma_f32_16x16x32_bf16 v[76:79], v[144:147], v[218:221], v[76:79]
	v_mfma_f32_16x16x32_bf16 v[76:79], v[148:151], v[222:225], v[76:79]
	v_mfma_f32_16x16x32_bf16 v[80:83], v[136:139], v[218:221], v[80:83]
	v_mfma_f32_16x16x32_bf16 v[80:83], v[140:143], v[222:225], v[80:83]
	s_setprio 0
	s_barrier
	s_mov_b32 m0, s60
	v_lshl_add_u64 v[226:227], s[40:41], 0, v[158:159]
	s_add_u32 s6, s40, 0x2b0000
	ds_read_b128 v[188:191], v198 offset:16384
	ds_read_b128 v[192:195], v198 offset:17408
	ds_read_b128 v[202:205], v198 offset:18432
	ds_read_b128 v[206:209], v198 offset:19456
	ds_read_b128 v[210:213], v198 offset:20480
	ds_read_b128 v[214:217], v198 offset:21504
	ds_read_b128 v[218:221], v198 offset:22528
	ds_read_b128 v[222:225], v198 offset:23552
	global_load_lds_dwordx4 v[226:227], off
	v_lshl_add_u64 v[228:229], s[40:41], 0, v[162:163]
	s_mov_b32 m0, s61
	s_addc_u32 s7, s41, 0
	global_load_lds_dwordx4 v[228:229], off
	v_lshl_add_u64 v[230:231], s[6:7], 0, v[158:159]
	s_mov_b32 m0, s62
	v_lshl_add_u64 v[232:233], s[42:43], 0, v[160:161]
	global_load_lds_dwordx4 v[230:231], off
	v_lshl_add_u64 v[230:231], s[6:7], 0, v[162:163]
	s_mov_b32 m0, s63
	s_nop 0
	global_load_lds_dwordx4 v[230:231], off
	v_lshl_add_u64 v[230:231], s[42:43], 0, v[156:157]
	s_mov_b32 m0, s46
	s_nop 0
	global_load_lds_dwordx4 v[230:231], off
	s_mov_b32 m0, s47
	s_nop 0
	global_load_lds_dwordx4 v[232:233], off
	s_setprio 1
	s_waitcnt vmcnt(8) lgkmcnt(0)
	s_barrier
	v_mfma_f32_16x16x32_bf16 v[64:67], v[136:139], v[188:191], v[64:67]
	v_mfma_f32_16x16x32_bf16 v[64:67], v[140:143], v[192:195], v[64:67]
	v_mfma_f32_16x16x32_bf16 v[60:63], v[144:147], v[188:191], v[60:63]
	v_mfma_f32_16x16x32_bf16 v[60:63], v[148:151], v[192:195], v[60:63]
	v_mfma_f32_16x16x32_bf16 v[56:59], v[152:155], v[188:191], v[56:59]
	v_mfma_f32_16x16x32_bf16 v[56:59], v[176:179], v[192:195], v[56:59]
	v_mfma_f32_16x16x32_bf16 v[52:55], v[180:183], v[188:191], v[52:55]
	v_mfma_f32_16x16x32_bf16 v[52:55], v[184:187], v[192:195], v[52:55]
	v_mfma_f32_16x16x32_bf16 v[36:39], v[180:183], v[202:205], v[36:39]
	v_mfma_f32_16x16x32_bf16 v[36:39], v[184:187], v[206:209], v[36:39]
	v_mfma_f32_16x16x32_bf16 v[40:43], v[152:155], v[202:205], v[40:43]
	v_mfma_f32_16x16x32_bf16 v[40:43], v[176:179], v[206:209], v[40:43]
	v_mfma_f32_16x16x32_bf16 v[44:47], v[144:147], v[202:205], v[44:47]
	v_mfma_f32_16x16x32_bf16 v[44:47], v[148:151], v[206:209], v[44:47]
	v_mfma_f32_16x16x32_bf16 v[48:51], v[136:139], v[202:205], v[48:51]
	v_mfma_f32_16x16x32_bf16 v[48:51], v[140:143], v[206:209], v[48:51]
	v_mfma_f32_16x16x32_bf16 v[32:35], v[136:139], v[210:213], v[32:35]
	v_mfma_f32_16x16x32_bf16 v[32:35], v[140:143], v[214:217], v[32:35]
	v_mfma_f32_16x16x32_bf16 v[28:31], v[144:147], v[210:213], v[28:31]
	v_mfma_f32_16x16x32_bf16 v[28:31], v[148:151], v[214:217], v[28:31]
	v_mfma_f32_16x16x32_bf16 v[24:27], v[152:155], v[210:213], v[24:27]
	v_mfma_f32_16x16x32_bf16 v[24:27], v[176:179], v[214:217], v[24:27]
	v_mfma_f32_16x16x32_bf16 v[20:23], v[180:183], v[210:213], v[20:23]
	v_mfma_f32_16x16x32_bf16 v[20:23], v[184:187], v[214:217], v[20:23]
	v_mfma_f32_16x16x32_bf16 v[4:7], v[180:183], v[218:221], v[4:7]
	v_mfma_f32_16x16x32_bf16 v[4:7], v[184:187], v[222:225], v[4:7]
	v_mfma_f32_16x16x32_bf16 v[8:11], v[152:155], v[218:221], v[8:11]
	v_mfma_f32_16x16x32_bf16 v[8:11], v[176:179], v[222:225], v[8:11]
	v_mfma_f32_16x16x32_bf16 v[12:15], v[144:147], v[218:221], v[12:15]
	v_mfma_f32_16x16x32_bf16 v[12:15], v[148:151], v[222:225], v[12:15]
	v_mfma_f32_16x16x32_bf16 v[16:19], v[136:139], v[218:221], v[16:19]
	v_mfma_f32_16x16x32_bf16 v[16:19], v[140:143], v[222:225], v[16:19]
	s_setprio 0
	s_barrier
	s_add_i32 s0, 0, 0x18000
	s_add_i32 s68, 0, 0x1c000
	v_add_u32_e32 v148, s0, v3
	v_add_u32_e32 v170, s68, v3
	ds_read_b128 v[136:139], v148
	ds_read_b128 v[140:143], v148 offset:1024
	ds_read_b128 v[144:147], v148 offset:2048
	ds_read_b128 v[148:151], v148 offset:3072
	ds_read_b128 v[152:155], v170
	ds_read_b128 v[176:179], v170 offset:1024
	ds_read_b128 v[180:183], v170 offset:2048
	ds_read_b128 v[184:187], v170 offset:3072
	s_add_u32 s6, s42, 0x2b0000
	s_addc_u32 s7, s43, 0
	s_mov_b32 m0, s48
	v_lshl_add_u64 v[234:235], s[6:7], 0, v[156:157]
	ds_read_b128 v[188:191], v198 offset:32768
	ds_read_b128 v[192:195], v198 offset:33792
	ds_read_b128 v[202:205], v198 offset:34816
	ds_read_b128 v[206:209], v198 offset:35840
	ds_read_b128 v[210:213], v198 offset:36864
	ds_read_b128 v[214:217], v198 offset:37888
	ds_read_b128 v[218:221], v198 offset:38912
	ds_read_b128 v[222:225], v198 offset:39936
	global_load_lds_dwordx4 v[234:235], off
	v_lshl_add_u64 v[234:235], s[6:7], 0, v[160:161]
	s_mov_b32 m0, s49
	s_nop 0
	global_load_lds_dwordx4 v[234:235], off
	s_setprio 1
	s_waitcnt vmcnt(8) lgkmcnt(0)
	s_barrier
	v_mfma_f32_16x16x32_bf16 v[128:131], v[136:139], v[188:191], v[128:131]
	v_mfma_f32_16x16x32_bf16 v[128:131], v[140:143], v[192:195], v[128:131]
	v_mfma_f32_16x16x32_bf16 v[124:127], v[144:147], v[188:191], v[124:127]
	v_mfma_f32_16x16x32_bf16 v[124:127], v[148:151], v[192:195], v[124:127]
	v_mfma_f32_16x16x32_bf16 v[120:123], v[152:155], v[188:191], v[120:123]
	v_mfma_f32_16x16x32_bf16 v[120:123], v[176:179], v[192:195], v[120:123]
	v_mfma_f32_16x16x32_bf16 v[116:119], v[180:183], v[188:191], v[116:119]
	v_mfma_f32_16x16x32_bf16 v[116:119], v[184:187], v[192:195], v[116:119]
	v_mfma_f32_16x16x32_bf16 v[100:103], v[180:183], v[202:205], v[100:103]
	v_mfma_f32_16x16x32_bf16 v[100:103], v[184:187], v[206:209], v[100:103]
	v_mfma_f32_16x16x32_bf16 v[104:107], v[152:155], v[202:205], v[104:107]
	v_mfma_f32_16x16x32_bf16 v[104:107], v[176:179], v[206:209], v[104:107]
	v_mfma_f32_16x16x32_bf16 v[108:111], v[144:147], v[202:205], v[108:111]
	v_mfma_f32_16x16x32_bf16 v[108:111], v[148:151], v[206:209], v[108:111]
	v_mfma_f32_16x16x32_bf16 v[112:115], v[136:139], v[202:205], v[112:115]
	v_mfma_f32_16x16x32_bf16 v[112:115], v[140:143], v[206:209], v[112:115]
	v_mfma_f32_16x16x32_bf16 v[96:99], v[136:139], v[210:213], v[96:99]
	v_mfma_f32_16x16x32_bf16 v[96:99], v[140:143], v[214:217], v[96:99]
	v_mfma_f32_16x16x32_bf16 v[92:95], v[144:147], v[210:213], v[92:95]
	v_mfma_f32_16x16x32_bf16 v[92:95], v[148:151], v[214:217], v[92:95]
	v_mfma_f32_16x16x32_bf16 v[88:91], v[152:155], v[210:213], v[88:91]
	v_mfma_f32_16x16x32_bf16 v[88:91], v[176:179], v[214:217], v[88:91]
	v_mfma_f32_16x16x32_bf16 v[84:87], v[180:183], v[210:213], v[84:87]
	v_mfma_f32_16x16x32_bf16 v[84:87], v[184:187], v[214:217], v[84:87]
	v_mfma_f32_16x16x32_bf16 v[68:71], v[180:183], v[218:221], v[68:71]
	v_mfma_f32_16x16x32_bf16 v[68:71], v[184:187], v[222:225], v[68:71]
	v_mfma_f32_16x16x32_bf16 v[72:75], v[152:155], v[218:221], v[72:75]
	v_mfma_f32_16x16x32_bf16 v[72:75], v[176:179], v[222:225], v[72:75]
	v_mfma_f32_16x16x32_bf16 v[76:79], v[144:147], v[218:221], v[76:79]
	v_mfma_f32_16x16x32_bf16 v[76:79], v[148:151], v[222:225], v[76:79]
	v_mfma_f32_16x16x32_bf16 v[80:83], v[136:139], v[218:221], v[80:83]
	v_mfma_f32_16x16x32_bf16 v[80:83], v[140:143], v[222:225], v[80:83]
	s_setprio 0
	s_barrier
	s_add_i32 s0, s0, s45
	v_lshl_add_u64 v[226:227], v[226:227], 0, s[28:29]
	s_mov_b32 m0, s0
	ds_read_b128 v[188:191], v198 offset:49152
	ds_read_b128 v[192:195], v198 offset:50176
	ds_read_b128 v[202:205], v198 offset:51200
	ds_read_b128 v[206:209], v198 offset:52224
	ds_read_b128 v[210:213], v198 offset:53248
	ds_read_b128 v[214:217], v198 offset:54272
	ds_read_b128 v[218:221], v198 offset:55296
	ds_read_b128 v[222:225], v198 offset:56320
	global_load_lds_dwordx4 v[226:227], off
	s_add_i32 m0, s0, 0x2000
	s_add_u32 s6, s40, 0x2b0080
	v_lshl_add_u64 v[226:227], v[228:229], 0, s[28:29]
	s_addc_u32 s7, s41, 0
	s_add_i32 s0, s68, s45
	global_load_lds_dwordx4 v[226:227], off
	v_lshl_add_u64 v[226:227], s[6:7], 0, v[158:159]
	s_mov_b32 m0, s0
	s_nop 0
	global_load_lds_dwordx4 v[226:227], off
	v_lshl_add_u64 v[226:227], s[6:7], 0, v[162:163]
	s_add_i32 m0, s0, 0x2000
	s_nop 0
	global_load_lds_dwordx4 v[226:227], off
	v_lshl_add_u64 v[226:227], v[230:231], 0, s[28:29]
	s_mov_b32 m0, s54
	s_nop 0
	global_load_lds_dwordx4 v[226:227], off
	v_lshl_add_u64 v[226:227], v[232:233], 0, s[28:29]
	s_mov_b32 m0, s55
	s_nop 0
	global_load_lds_dwordx4 v[226:227], off
	s_setprio 1
	s_waitcnt vmcnt(8) lgkmcnt(0)
	s_barrier
	v_mfma_f32_16x16x32_bf16 v[64:67], v[136:139], v[188:191], v[64:67]
	v_mfma_f32_16x16x32_bf16 v[64:67], v[140:143], v[192:195], v[64:67]
	v_mfma_f32_16x16x32_bf16 v[60:63], v[144:147], v[188:191], v[60:63]
	v_mfma_f32_16x16x32_bf16 v[60:63], v[148:151], v[192:195], v[60:63]
	v_mfma_f32_16x16x32_bf16 v[56:59], v[152:155], v[188:191], v[56:59]
	v_mfma_f32_16x16x32_bf16 v[56:59], v[176:179], v[192:195], v[56:59]
	v_mfma_f32_16x16x32_bf16 v[52:55], v[180:183], v[188:191], v[52:55]
	v_mfma_f32_16x16x32_bf16 v[52:55], v[184:187], v[192:195], v[52:55]
	v_mfma_f32_16x16x32_bf16 v[36:39], v[180:183], v[202:205], v[36:39]
	v_mfma_f32_16x16x32_bf16 v[36:39], v[184:187], v[206:209], v[36:39]
	v_mfma_f32_16x16x32_bf16 v[40:43], v[152:155], v[202:205], v[40:43]
	v_mfma_f32_16x16x32_bf16 v[40:43], v[176:179], v[206:209], v[40:43]
	v_mfma_f32_16x16x32_bf16 v[44:47], v[144:147], v[202:205], v[44:47]
	v_mfma_f32_16x16x32_bf16 v[44:47], v[148:151], v[206:209], v[44:47]
	v_mfma_f32_16x16x32_bf16 v[48:51], v[136:139], v[202:205], v[48:51]
	v_mfma_f32_16x16x32_bf16 v[48:51], v[140:143], v[206:209], v[48:51]
	v_mfma_f32_16x16x32_bf16 v[32:35], v[136:139], v[210:213], v[32:35]
	v_mfma_f32_16x16x32_bf16 v[32:35], v[140:143], v[214:217], v[32:35]
	v_mfma_f32_16x16x32_bf16 v[28:31], v[144:147], v[210:213], v[28:31]
	v_mfma_f32_16x16x32_bf16 v[28:31], v[148:151], v[214:217], v[28:31]
	v_mfma_f32_16x16x32_bf16 v[24:27], v[152:155], v[210:213], v[24:27]
	v_mfma_f32_16x16x32_bf16 v[24:27], v[176:179], v[214:217], v[24:27]
	v_mfma_f32_16x16x32_bf16 v[20:23], v[180:183], v[210:213], v[20:23]
	v_mfma_f32_16x16x32_bf16 v[20:23], v[184:187], v[214:217], v[20:23]
	v_mfma_f32_16x16x32_bf16 v[4:7], v[180:183], v[218:221], v[4:7]
	v_mfma_f32_16x16x32_bf16 v[4:7], v[184:187], v[222:225], v[4:7]
	v_mfma_f32_16x16x32_bf16 v[8:11], v[152:155], v[218:221], v[8:11]
	v_mfma_f32_16x16x32_bf16 v[8:11], v[176:179], v[222:225], v[8:11]
	v_mfma_f32_16x16x32_bf16 v[12:15], v[144:147], v[218:221], v[12:15]
	v_mfma_f32_16x16x32_bf16 v[12:15], v[148:151], v[222:225], v[12:15]
	v_mfma_f32_16x16x32_bf16 v[16:19], v[136:139], v[218:221], v[16:19]
	v_mfma_f32_16x16x32_bf16 v[16:19], v[140:143], v[222:225], v[16:19]
	s_setprio 0
	s_barrier
	s_add_i32 s67, s67, 2
	s_cmpk_gt_u32 s67, 0xa9
	s_mov_b64 s[6:7], s[8:9]
	s_cbranch_scc0 .LBB0_1703
	s_and_b64 vcc, exec, s[30:31]
	s_cbranch_vccz .LBB0_1706
	s_barrier
